# GDN: deferred decay factor (state kept unscaled, materialized when phi<2^-40), loops fully unrolled with baked LDS offsets; RWKV predecessor-token loads deferred
# speedup vs baseline: 1.2731x; 1.0085x over previous
.LBB0_533:
	s_cmpk_gt_i32 s71, 0x7f
	s_mov_b64 s[0:1], -1
	s_cbranch_scc0 .LBB0_560
	s_add_i32 s3, s71, 0xffffff80
	v_mov_b32_e32 v1, v180
	s_lshl_b32 s0, s3, 8
	s_bfe_u32 s6, s71, 0x20001
	s_and_b32 s16, s0, 0x7800
	s_waitcnt vmcnt(2)
	v_ashrrev_i32_e32 v18, 3, v1
	s_lshl_b32 s72, s6, 2
	s_lshl_b32 s0, s6, 8
	v_add_u32_e32 v21, s16, v18
	v_mov_b64_e32 v[18:19], s[22:23]
	s_mov_b32 s1, s73
	s_add_u32 s8, s22, s0
	v_mad_i64_i32 v[18:19], s[4:5], v21, s83, v[18:19]
	s_addc_u32 s9, s23, 0
	v_lshl_add_u64 v[18:19], v[18:19], 0, s[0:1]
	s_lshl_b32 s0, s3, 6
	s_and_b32 s3, s0, 64
	v_mov_b32_e32 v2, s72
	v_lshlrev_b32_e32 v20, 4, v1
	s_lshl_b32 s0, s3, 1
	global_load_dword v24, v2, s[64:65]
	global_load_dword v124, v2, s[66:67]
	v_and_b32_e32 v25, 63, v1
	v_and_b32_e32 v2, 0xf0, v20
	v_lshl_add_u64 v[18:19], v[18:19], 0, s[0:1]
	v_and_b32_e32 v20, 0x70, v20
	v_mov_b32_e32 v21, v94
	v_mov_b32_e32 v3, v94
	v_add_u32_e32 v12, 0x200, v1
	v_lshl_add_u64 v[18:19], v[18:19], 0, v[20:21]
	v_or_b32_e32 v20, s16, v25
	v_lshl_add_u64 v[10:11], s[8:9], 0, v[2:3]
	v_ashrrev_i32_e32 v2, 4, v1
	v_ashrrev_i32_e32 v12, 4, v12
	v_mul_u32_u24_e32 v20, 0x88, v20
	v_add_u32_e32 v2, s16, v2
	v_add_u32_e32 v12, s16, v12
	v_lshlrev_b32_e32 v20, 2, v20
	v_mad_i64_i32 v[6:7], s[4:5], v2, s83, v[10:11]
	v_mad_i64_i32 v[14:15], s[4:5], v12, s83, v[10:11]
	v_lshl_add_u64 v[20:21], s[26:27], 0, v[20:21]
	global_load_dwordx4 v[2:5], v[6:7], off
	s_nop 0
	global_load_dwordx4 v[6:9], v[6:7], off offset:1024
	s_nop 0
	global_load_dwordx4 v[10:13], v[14:15], off
	s_nop 0
	global_load_dwordx4 v[14:17], v[14:15], off offset:1024
	v_lshl_add_u64 v[22:23], v[20:21], 0, s[72:73]
	global_load_dwordx4 v[18:21], v[18:19], off offset:2048
	s_nop 0
	global_load_dword v126, v[22:23], off offset:512
	global_load_dword v127, v[22:23], off offset:528
	s_lshl_b32 s1, s6, 9
	v_lshlrev_b32_e32 v22, 3, v1
	s_add_u32 s1, s75, s1
	v_and_b32_e32 v22, 0xfffffe00, v22
	v_lshlrev_b32_e32 v23, 2, v25
	s_addc_u32 s4, s79, 0
	s_lshl_b32 s3, s3, 2
	v_add3_u32 v22, s82, v22, v23
	s_add_u32 s10, s1, s3
	ds_write2st64_b32 v22, v94, v94 offset1:1
	s_addc_u32 s11, s4, 0
	s_add_u32 s12, s8, s0
	s_addc_u32 s13, s9, 0
	v_mov_b32_e32 v95, v94
	s_add_u32 s14, s26, s72
	s_mov_b32 s17, 0
	v_mov_b64_e32 v[96:97], v[94:95]
	v_mov_b64_e32 v[98:99], v[94:95]
	v_mov_b64_e32 v[100:101], v[94:95]
	s_addc_u32 s15, s27, 0
	v_mov_b64_e32 v[102:103], v[94:95]
	v_mov_b64_e32 v[104:105], v[94:95]
	v_mov_b64_e32 v[106:107], v[94:95]
	v_mov_b64_e32 v[108:109], v[94:95]
	v_mov_b64_e32 v[110:111], v[94:95]
	s_waitcnt vmcnt(8)
	v_mul_f32_e32 v22, 0x3fb8aa3b, v24
	v_exp_f32_e32 v125, v22
	v_mov_b32_e32 v184, 0
	v_mov_b32_e32 v185, 0
	v_mov_b32_e32 v186, 0
	v_mov_b32_e32 v187, 0
	v_mov_b32_e32 v188, 0
	v_mov_b32_e32 v189, 0
	v_mov_b32_e32 v190, 0
	v_mov_b32_e32 v191, 0
	v_mov_b32_e32 v192, 0
	v_mov_b32_e32 v193, 0
	v_mov_b32_e32 v194, 0
	v_mov_b32_e32 v195, 0
	v_mov_b32_e32 v196, 0
	v_mov_b32_e32 v197, 0
	v_mov_b32_e32 v198, 0
	v_mov_b32_e32 v199, 0
	v_mov_b32_e32 v200, 0
	v_mov_b32_e32 v201, 0
	v_mov_b32_e32 v202, 0
	v_mov_b32_e32 v203, 0
	v_mov_b32_e32 v204, 0
	v_mov_b32_e32 v205, 0
	v_mov_b32_e32 v206, 0
	v_mov_b32_e32 v207, 0
	v_mov_b32_e32 v208, 0
	v_mov_b32_e32 v209, 0
	v_mov_b32_e32 v210, 0
	v_mov_b32_e32 v211, 0
	v_mov_b32_e32 v212, 0
	v_mov_b32_e32 v213, 0
	v_mov_b32_e32 v214, 0
	v_mov_b32_e32 v215, 0
	v_mov_b32_e32 v238, 1.0
	s_branch .LBB0_537

.LBB0_547:
	s_or_b64 exec, exec, s[4:5]
	v_and_b32_e32 v165, 63, v180
	v_lshrrev_b32_e32 v168, 6, v180
	v_mul_u32_u24_e32 v163, 0x1080, v168
	v_lshlrev_b32_e32 v164, 7, v168
	v_lshrrev_b32_e32 v168, 1, v165
	v_lshl_add_u32 v164, v168, 2, v164
	v_add_u32_e32 v164, 0x15800, v164
	v_and_b32_e32 v165, 1, v165
	v_lshl_add_u32 v163, v165, 8, v163
	v_bfe_u32 v165, v168, 2, 2
	v_add_u32_e32 v165, 4, v165
	v_mul_u32_u24_e32 v165, 0x210, v165
	v_add_u32_e32 v162, v163, v165
	v_bfe_u32 v165, v168, 4, 1
	v_sub_u32_e32 v165, 1, v165
	v_mul_u32_u24_e32 v165, 0x8400, v165
	v_add_u32_e32 v162, v162, v165
	v_and_b32_e32 v165, 3, v168
	v_mul_u32_u24_e32 v165, 0x210, v165
	v_add_u32_e32 v163, v163, v165
	v_add_u32_e32 v163, 0x8400, v163
	v_mov_b32_e32 v166, 0
	v_mov_b32_e32 v167, 0
	ds_read_b128 v[216:219], v162 offset:0
	ds_read_b128 v[220:223], v162 offset:16
	ds_read_b128 v[224:227], v163 offset:0
	ds_read_b128 v[228:231], v163 offset:16
	ds_read_b128 v[232:235], v162 offset:32
	ds_read_b128 v[154:157], v162 offset:48
	ds_read_b128 v[170:173], v163 offset:32
	ds_read_b128 v[174:177], v163 offset:48
	s_waitcnt lgkmcnt(4)
	v_pk_fma_f32 v[166:167], v[216:217], v[224:225], v[166:167]
	v_pk_fma_f32 v[166:167], v[218:219], v[226:227], v[166:167]
	v_pk_fma_f32 v[166:167], v[220:221], v[228:229], v[166:167]
	v_pk_fma_f32 v[166:167], v[222:223], v[230:231], v[166:167]
	ds_read_b128 v[216:219], v162 offset:64
	ds_read_b128 v[220:223], v162 offset:80
	ds_read_b128 v[224:227], v163 offset:64
	ds_read_b128 v[228:231], v163 offset:80
	s_waitcnt lgkmcnt(4)
	v_pk_fma_f32 v[166:167], v[232:233], v[170:171], v[166:167]
	v_pk_fma_f32 v[166:167], v[234:235], v[172:173], v[166:167]
	v_pk_fma_f32 v[166:167], v[154:155], v[174:175], v[166:167]
	v_pk_fma_f32 v[166:167], v[156:157], v[176:177], v[166:167]
	ds_read_b128 v[232:235], v162 offset:96
	ds_read_b128 v[154:157], v162 offset:112
	ds_read_b128 v[170:173], v163 offset:96
	ds_read_b128 v[174:177], v163 offset:112
	s_waitcnt lgkmcnt(4)
	v_pk_fma_f32 v[166:167], v[216:217], v[224:225], v[166:167]
	v_pk_fma_f32 v[166:167], v[218:219], v[226:227], v[166:167]
	v_pk_fma_f32 v[166:167], v[220:221], v[228:229], v[166:167]
	v_pk_fma_f32 v[166:167], v[222:223], v[230:231], v[166:167]
	ds_read_b128 v[216:219], v162 offset:128
	ds_read_b128 v[220:223], v162 offset:144
	ds_read_b128 v[224:227], v163 offset:128
	ds_read_b128 v[228:231], v163 offset:144
	s_waitcnt lgkmcnt(4)
	v_pk_fma_f32 v[166:167], v[232:233], v[170:171], v[166:167]
	v_pk_fma_f32 v[166:167], v[234:235], v[172:173], v[166:167]
	v_pk_fma_f32 v[166:167], v[154:155], v[174:175], v[166:167]
	v_pk_fma_f32 v[166:167], v[156:157], v[176:177], v[166:167]
	ds_read_b128 v[232:235], v162 offset:160
	ds_read_b128 v[154:157], v162 offset:176
	ds_read_b128 v[170:173], v163 offset:160
	ds_read_b128 v[174:177], v163 offset:176
	s_waitcnt lgkmcnt(4)
	v_pk_fma_f32 v[166:167], v[216:217], v[224:225], v[166:167]
	v_pk_fma_f32 v[166:167], v[218:219], v[226:227], v[166:167]
	v_pk_fma_f32 v[166:167], v[220:221], v[228:229], v[166:167]
	v_pk_fma_f32 v[166:167], v[222:223], v[230:231], v[166:167]
	ds_read_b128 v[216:219], v162 offset:192
	ds_read_b128 v[220:223], v162 offset:208
	ds_read_b128 v[224:227], v163 offset:192
	ds_read_b128 v[228:231], v163 offset:208
	s_waitcnt lgkmcnt(4)
	v_pk_fma_f32 v[166:167], v[232:233], v[170:171], v[166:167]
	v_pk_fma_f32 v[166:167], v[234:235], v[172:173], v[166:167]
	v_pk_fma_f32 v[166:167], v[154:155], v[174:175], v[166:167]
	v_pk_fma_f32 v[166:167], v[156:157], v[176:177], v[166:167]
	ds_read_b128 v[232:235], v162 offset:224
	ds_read_b128 v[154:157], v162 offset:240
	ds_read_b128 v[170:173], v163 offset:224
	ds_read_b128 v[174:177], v163 offset:240
	s_waitcnt lgkmcnt(4)
	v_pk_fma_f32 v[166:167], v[216:217], v[224:225], v[166:167]
	v_pk_fma_f32 v[166:167], v[218:219], v[226:227], v[166:167]
	v_pk_fma_f32 v[166:167], v[220:221], v[228:229], v[166:167]
	v_pk_fma_f32 v[166:167], v[222:223], v[230:231], v[166:167]
	s_waitcnt lgkmcnt(0)
	v_pk_fma_f32 v[166:167], v[232:233], v[170:171], v[166:167]
	v_pk_fma_f32 v[166:167], v[234:235], v[172:173], v[166:167]
	v_pk_fma_f32 v[166:167], v[154:155], v[174:175], v[166:167]
	v_pk_fma_f32 v[166:167], v[156:157], v[176:177], v[166:167]
	v_add_f32_e32 v166, v166, v167
	s_nop 1
	v_add_f32_dpp v166, v166, v166 quad_perm:[1,0,3,2] row_mask:0xf bank_mask:0xf bound_ctrl:1
	ds_write_b32 v164, v166
	s_lshl_b32 s0, s17, 6
	s_add_i32 s72, s0, s16
	v_and_b32_e32 v128, 63, v112
	s_cmp_eq_u32 s17, 31
	s_waitcnt lgkmcnt(0)
	s_barrier
	s_cbranch_scc1 .LBB0_549
	s_add_i32 s0, s72, 64
	s_mov_b32 s1, s73
	v_ashrrev_i32_e32 v27, 31, v26
	v_lshlrev_b32_e32 v2, 1, v23
	v_mov_b32_e32 v3, v94
	v_ashrrev_i32_e32 v23, 31, v22
	v_ashrrev_i32_e32 v25, 31, v24
	v_lshl_add_u64 v[18:19], s[0:1], 0, v[26:27]
	v_mov_b64_e32 v[20:21], s[12:13]
	v_lshl_add_u64 v[10:11], s[8:9], 0, v[2:3]
	v_lshl_add_u64 v[2:3], s[0:1], 0, v[22:23]
	v_lshl_add_u64 v[12:13], s[0:1], 0, v[24:25]
	v_mad_u64_u32 v[20:21], s[4:5], v18, s83, v[20:21]
	v_mad_u64_u32 v[6:7], s[4:5], v2, s83, v[10:11]
	v_mad_u64_u32 v[14:15], s[4:5], v12, s83, v[10:11]
	v_mad_i32_i24 v21, v19, s83, v21
	v_lshlrev_b32_e32 v18, 1, v28
	v_mov_b32_e32 v19, v94
	v_mad_i32_i24 v7, v3, s83, v7
	v_mad_i32_i24 v15, v13, s83, v15
	v_lshl_add_u64 v[18:19], v[20:21], 0, v[18:19]
	v_or_b32_e32 v22, s0, v128
	v_mov_b64_e32 v[20:21], s[14:15]
	global_load_dwordx4 v[2:5], v[6:7], off
	s_nop 0
	global_load_dwordx4 v[6:9], v[6:7], off offset:1024
	s_nop 0
	global_load_dwordx4 v[10:13], v[14:15], off
	s_nop 0
	global_load_dwordx4 v[14:17], v[14:15], off offset:1024
	v_mad_u64_u32 v[22:23], s[0:1], v22, s87, v[20:21]
	global_load_dwordx4 v[18:21], v[18:19], off offset:2048
	s_nop 0
	global_load_dword v126, v[22:23], off offset:512
	global_load_dword v127, v[22:23], off offset:528
.LBB0_549:
	v_readfirstlane_b32 s0, v180
	s_nop 1
	s_cmpk_ge_u32 s0, 0x100
	s_cbranch_scc1 .Lgdn_done
	v_and_b32_e32 v166, 15, v180
	v_bfe_u32 v167, v180, 4, 2
	v_lshrrev_b32_e32 v168, 6, v180
	v_and_b32_e32 v177, 3, v166
	v_bfe_u32 v178, v166, 3, 1
	v_lshl_add_u32 v177, v178, 2, v177
	v_mul_u32_u24_e32 v177, 0x210, v177
	v_and_b32_e32 v87, 7, v166
	v_lshlrev_b32_e32 v87, 4, v87
	v_lshl_add_u32 v87, v167, 2, v87
	v_add_u32_e32 v87, 0x15800, v87
	v_and_b32_e32 v178, 4, v166
	v_sub_u32_e32 v178, 4, v178
	v_mul_u32_u24_e32 v178, 0x2100, v178
	v_lshl_add_u32 v169, v167, 4, v177
	v_add_u32_e32 v169, v169, v178
	v_mul_u32_u24_e32 v177, 0x210, v167
	v_lshl_add_u32 v170, v166, 2, v177
	v_add_u32_e32 v170, 0x8400, v170
	v_add_u32_e32 v237, 0x840, v170
	v_add_u32_e32 v95, 0x1080, v170
	v_lshlrev_b32_e32 v177, 6, v168
	v_lshl_add_u32 v177, v166, 2, v177
	v_add_u32_e32 v171, 0x10800, v177
	v_lshl_add_u32 v172, v167, 8, v177
	v_add_u32_e32 v172, 0x1d800, v172
	v_mov_b32_e32 v173, 0x14800
	v_lshlrev_b32_e32 v174, 5, v167
	v_add_u32_e32 v174, 0x14900, v174
	v_mov_b32_e32 v175, 0x21900
	v_lshl_add_u32 v176, v167, 2, v175
	v_cmp_eq_u32_e32 vcc, 1, v167
	v_cmp_eq_u32_e64 s[4:5], 2, v167
	v_cmp_eq_u32_e64 s[6:7], 3, v167
	ds_read_b128 v[22:25], v169 offset:0
	ds_read_b128 v[26:29], v169 offset:64
	ds_read_b128 v[30:33], v169 offset:128
	ds_read_b128 v[34:37], v169 offset:192
	ds_read_b128 v[38:41], v169 offset:256
	ds_read_b128 v[42:45], v169 offset:320
	ds_read_b128 v[46:49], v169 offset:384
	ds_read_b128 v[50:53], v169 offset:448
	ds_read2_b32 v[54:55], v170 offset0:0 offset1:16
	ds_read2_b32 v[56:57], v170 offset0:32 offset1:48
	ds_read2_b32 v[58:59], v170 offset0:64 offset1:80
	ds_read2_b32 v[60:61], v170 offset0:96 offset1:112
	ds_read2st64_b32 v[70:71], v171 offset0:0 offset1:1
	ds_read2st64_b32 v[72:73], v171 offset0:2 offset1:3
	ds_read_b128 v[132:135], v175 offset:0
	ds_read_b128 v[136:139], v175 offset:256
	ds_read_b32 v151, v176 offset:256
	ds_read_b32 v152, v176 offset:512
	ds_read_b32 v150, v173 offset:32
	ds_read_b64 v[148:149], v173 offset:64
	ds_read_b128 v[140:143], v173 offset:96
	ds_read_b128 v[144:147], v174 offset:0
	s_mov_b32 s1, 0
	s_waitcnt lgkmcnt(0)
	s_waitcnt lgkmcnt(1)
	v_mfma_f32_16x16x4_f32 v[96:99], v22, v184, 0
	v_mfma_f32_16x16x4_f32 v[100:103], v23, v185, 0
	v_mfma_f32_16x16x4_f32 v[96:99], v24, v186, v[96:99]
	v_mfma_f32_16x16x4_f32 v[100:103], v25, v187, v[100:103]
	v_mul_f32_e32 v129, v132, v70
	v_mul_f32_e32 v130, v133, v71
	v_mul_f32_e32 v131, v134, v72
	v_mul_f32_e32 v153, v135, v73
	v_mfma_f32_16x16x4_f32 v[96:99], v26, v188, v[96:99]
	v_mfma_f32_16x16x4_f32 v[100:103], v27, v189, v[100:103]
	v_mfma_f32_16x16x4_f32 v[96:99], v28, v190, v[96:99]
	v_mfma_f32_16x16x4_f32 v[100:103], v29, v191, v[100:103]
	v_mul_f32_e64 v114, -v132, v136
	v_mul_f32_e64 v115, -v133, v137
	v_mul_f32_e64 v116, -v134, v138
	v_mul_f32_e64 v117, -v135, v139
	v_mfma_f32_16x16x4_f32 v[96:99], v30, v192, v[96:99]
	v_mfma_f32_16x16x4_f32 v[100:103], v31, v193, v[100:103]
	v_mfma_f32_16x16x4_f32 v[96:99], v32, v194, v[96:99]
	v_mfma_f32_16x16x4_f32 v[100:103], v33, v195, v[100:103]
	v_mul_f32_e32 v240, v238, v139
	v_rcp_f32_e32 v89, v240
	v_readfirstlane_b32 s0, v240
	ds_read_b32 v86, v87 offset:0
	v_mfma_f32_16x16x4_f32 v[96:99], v34, v196, v[96:99]
	v_mfma_f32_16x16x4_f32 v[100:103], v35, v197, v[100:103]
	v_mfma_f32_16x16x4_f32 v[96:99], v36, v198, v[96:99]
	v_mfma_f32_16x16x4_f32 v[100:103], v37, v199, v[100:103]
	ds_read2_b32 v[62:63], v237 offset0:0 offset1:16
	ds_read2_b32 v[64:65], v237 offset0:32 offset1:48
	ds_read2_b32 v[66:67], v237 offset0:64 offset1:80
	ds_read2_b32 v[68:69], v237 offset0:96 offset1:112
	v_mfma_f32_16x16x4_f32 v[96:99], v38, v200, v[96:99]
	v_mfma_f32_16x16x4_f32 v[100:103], v39, v201, v[100:103]
	v_mfma_f32_16x16x4_f32 v[96:99], v40, v202, v[96:99]
	v_mfma_f32_16x16x4_f32 v[100:103], v41, v203, v[100:103]
	ds_read2st64_b32 v[74:75], v171 offset0:4 offset1:5
	ds_read2st64_b32 v[76:77], v171 offset0:6 offset1:7
	ds_read_b128 v[216:219], v175 offset:16
	ds_read_b128 v[220:223], v175 offset:272
	v_mfma_f32_16x16x4_f32 v[96:99], v42, v204, v[96:99]
	v_mfma_f32_16x16x4_f32 v[100:103], v43, v205, v[100:103]
	v_mfma_f32_16x16x4_f32 v[96:99], v44, v206, v[96:99]
	v_mfma_f32_16x16x4_f32 v[100:103], v45, v207, v[100:103]
	ds_read_b32 v235, v176 offset:272
	ds_read_b32 v236, v176 offset:528
	ds_read_b32 v234, v173 offset:176
	ds_read_b64 v[232:233], v173 offset:208
	v_mfma_f32_16x16x4_f32 v[96:99], v46, v208, v[96:99]
	v_mfma_f32_16x16x4_f32 v[100:103], v47, v209, v[100:103]
	v_mfma_f32_16x16x4_f32 v[96:99], v48, v210, v[96:99]
	v_mfma_f32_16x16x4_f32 v[100:103], v49, v211, v[100:103]
	ds_read_b128 v[224:227], v173 offset:240
	ds_read_b128 v[228:231], v174 offset:144
	v_mfma_f32_16x16x4_f32 v[96:99], v50, v212, v[96:99]
	v_mfma_f32_16x16x4_f32 v[100:103], v51, v213, v[100:103]
	v_mfma_f32_16x16x4_f32 v[96:99], v52, v214, v[96:99]
	v_mfma_f32_16x16x4_f32 v[100:103], v53, v215, v[100:103]
	s_nop 7
	s_nop 1
	v_pk_mul_f32 v[100:101], v[100:101], v[238:239] op_sel_hi:[1,0]
	v_pk_mul_f32 v[102:103], v[102:103], v[238:239] op_sel_hi:[1,0]
	v_pk_fma_f32 v[78:79], v[96:97], v[238:239], v[100:101] op_sel_hi:[1,0,1]
	v_pk_fma_f32 v[80:81], v[98:99], v[238:239], v[102:103] op_sel_hi:[1,0,1]
	v_pk_fma_f32 v[96:97], v[96:97], v[238:239], v[100:101] op_sel_hi:[1,0,1]
	v_pk_fma_f32 v[98:99], v[98:99], v[238:239], v[102:103] op_sel_hi:[1,0,1]
	s_nop 0
	v_permlane32_swap_b32_e32 v96, v78
	v_permlane32_swap_b32_e32 v97, v79
	v_permlane32_swap_b32_e32 v98, v80
	v_permlane32_swap_b32_e32 v99, v81
	v_mov_b32_e32 v82, v96
	v_mov_b32_e32 v83, v97
	v_mov_b32_e32 v84, v98
	v_mov_b32_e32 v85, v99
	s_nop 0
	v_permlane16_swap_b32_e32 v96, v82
	v_permlane16_swap_b32_e32 v97, v83
	v_permlane16_swap_b32_e32 v98, v84
	v_permlane16_swap_b32_e32 v99, v85
	v_fma_f32 v108, v114, v96, v129
	v_fma_f32 v109, v115, v97, v130
	v_fma_f32 v110, v116, v98, v131
	v_fma_f32 v111, v117, v99, v153
	v_fma_f32 v109, -v150, v108, v109
	v_fma_f32 v110, -v148, v108, v110
	v_fma_f32 v111, -v140, v108, v111
	v_fma_f32 v110, -v149, v109, v110
	v_fma_f32 v111, -v141, v109, v111
	v_fma_f32 v111, -v142, v110, v111
	v_cndmask_b32_e32 v182, v108, v109, vcc
	v_cndmask_b32_e64 v182, v182, v110, s[4:5]
	v_cndmask_b32_e64 v182, v182, v111, s[6:7]
	v_mul_f32_e32 v182, v152, v182
	s_cmp_lt_u32 s0, 0x2b800000
	s_cbranch_scc0 .Lgdn_nomat_0_0
	v_pk_mul_f32 v[184:185], v[184:185], v[240:241] op_sel_hi:[1,0]
	v_pk_mul_f32 v[186:187], v[186:187], v[240:241] op_sel_hi:[1,0]
	v_pk_mul_f32 v[188:189], v[188:189], v[240:241] op_sel_hi:[1,0]
	v_pk_mul_f32 v[190:191], v[190:191], v[240:241] op_sel_hi:[1,0]
	v_pk_mul_f32 v[192:193], v[192:193], v[240:241] op_sel_hi:[1,0]
	v_pk_mul_f32 v[194:195], v[194:195], v[240:241] op_sel_hi:[1,0]
	v_pk_mul_f32 v[196:197], v[196:197], v[240:241] op_sel_hi:[1,0]
	v_pk_mul_f32 v[198:199], v[198:199], v[240:241] op_sel_hi:[1,0]
	v_pk_mul_f32 v[200:201], v[200:201], v[240:241] op_sel_hi:[1,0]
	v_pk_mul_f32 v[202:203], v[202:203], v[240:241] op_sel_hi:[1,0]
	v_pk_mul_f32 v[204:205], v[204:205], v[240:241] op_sel_hi:[1,0]
	v_pk_mul_f32 v[206:207], v[206:207], v[240:241] op_sel_hi:[1,0]
	v_pk_mul_f32 v[208:209], v[208:209], v[240:241] op_sel_hi:[1,0]
	v_pk_mul_f32 v[210:211], v[210:211], v[240:241] op_sel_hi:[1,0]
	v_pk_mul_f32 v[212:213], v[212:213], v[240:241] op_sel_hi:[1,0]
	v_pk_mul_f32 v[214:215], v[214:215], v[240:241] op_sel_hi:[1,0]
	v_mov_b32_e32 v240, 1.0
	v_mov_b32_e32 v89, 1.0
.Lgdn_nomat_0_0:
	v_mov_b32_e32 v238, v240
	v_mul_f32_e32 v90, v182, v89
	s_nop 1
	v_mfma_f32_16x16x4_f32 v[184:187], v54, v90, v[184:187]
	v_mfma_f32_16x16x4_f32 v[188:191], v55, v90, v[188:191]
	v_mfma_f32_16x16x4_f32 v[192:195], v56, v90, v[192:195]
	v_mfma_f32_16x16x4_f32 v[196:199], v57, v90, v[196:199]
	v_mfma_f32_16x16x4_f32 v[200:203], v58, v90, v[200:203]
	v_mfma_f32_16x16x4_f32 v[204:207], v59, v90, v[204:207]
	v_mfma_f32_16x16x4_f32 v[208:211], v60, v90, v[208:211]
	v_mfma_f32_16x16x4_f32 v[212:215], v61, v90, v[212:215]
	v_pk_mul_f32 v[78:79], v[78:79], v[138:139] op_sel:[0,1] op_sel_hi:[1,1]
	v_pk_mul_f32 v[80:81], v[80:81], v[138:139] op_sel:[0,1] op_sel_hi:[1,1]
	v_cndmask_b32_e32 v183, v82, v83, vcc
	v_cndmask_b32_e64 v183, v183, v84, s[4:5]
	v_cndmask_b32_e64 v183, v183, v85, s[6:7]
	v_mul_f32_e32 v179, v151, v183
	v_fmac_f32_e32 v179, v144, v108
	v_fmac_f32_e32 v179, v145, v109
	v_fmac_f32_e32 v179, v146, v110
	v_fmac_f32_e32 v179, v147, v111
	ds_write_b32 v172, v179 offset:0
	s_waitcnt lgkmcnt(1)
	v_mfma_f32_16x16x4_f32 v[96:99], v86, v182, v[78:81]
	s_nop 7
	v_mul_f32_e32 v129, v216, v74
	v_mul_f32_e32 v130, v217, v75
	v_mul_f32_e32 v131, v218, v76
	v_mul_f32_e32 v153, v219, v77
	v_mul_f32_e64 v114, -v216, v220
	v_mul_f32_e64 v115, -v217, v221
	v_mul_f32_e64 v116, -v218, v222
	v_mul_f32_e64 v117, -v219, v223
	v_mul_f32_e32 v240, v238, v223
	v_rcp_f32_e32 v89, v240
	v_readfirstlane_b32 s0, v240
	ds_read_b128 v[22:25], v169 offset:4224
	ds_read_b128 v[26:29], v169 offset:4288
	ds_read_b128 v[30:33], v169 offset:4352
	ds_read_b128 v[34:37], v169 offset:4416
	ds_read_b128 v[38:41], v169 offset:4480
	ds_read_b128 v[42:45], v169 offset:4544
	ds_read_b128 v[46:49], v169 offset:4608
	ds_read_b128 v[50:53], v169 offset:4672
	ds_read2_b32 v[54:55], v95 offset0:0 offset1:16
	ds_read2_b32 v[56:57], v95 offset0:32 offset1:48
	ds_read2_b32 v[58:59], v95 offset0:64 offset1:80
	ds_read2_b32 v[60:61], v95 offset0:96 offset1:112
	ds_read2st64_b32 v[70:71], v171 offset0:8 offset1:9
	ds_read2st64_b32 v[72:73], v171 offset0:10 offset1:11
	ds_read_b128 v[132:135], v175 offset:32
	ds_read_b128 v[136:139], v175 offset:288
	ds_read_b32 v151, v176 offset:288
	ds_read_b32 v152, v176 offset:544
	ds_read_b32 v150, v173 offset:544
	ds_read_b64 v[148:149], v173 offset:576
	ds_read_b128 v[140:143], v173 offset:608
	ds_read_b128 v[144:147], v174 offset:512
	v_mov_b32_e32 v82, v96
	v_mov_b32_e32 v83, v97
	v_mov_b32_e32 v84, v98
	v_mov_b32_e32 v85, v99
	s_nop 0
	v_permlane16_swap_b32_e32 v96, v82
	v_permlane16_swap_b32_e32 v97, v83
	v_permlane16_swap_b32_e32 v98, v84
	v_permlane16_swap_b32_e32 v99, v85
	v_fma_f32 v108, v114, v96, v129
	v_fma_f32 v109, v115, v97, v130
	v_fma_f32 v110, v116, v98, v131
	v_fma_f32 v111, v117, v99, v153
	v_fma_f32 v109, -v234, v108, v109
	v_fma_f32 v110, -v232, v108, v110
	v_fma_f32 v111, -v224, v108, v111
	v_fma_f32 v110, -v233, v109, v110
	v_fma_f32 v111, -v225, v109, v111
	v_fma_f32 v111, -v226, v110, v111
	v_cndmask_b32_e32 v182, v108, v109, vcc
	v_cndmask_b32_e64 v182, v182, v110, s[4:5]
	v_cndmask_b32_e64 v182, v182, v111, s[6:7]
	v_mul_f32_e32 v182, v236, v182
	s_cmp_lt_u32 s0, 0x2b800000
	s_cbranch_scc0 .Lgdn_nomat_0_1
	v_pk_mul_f32 v[184:185], v[184:185], v[240:241] op_sel_hi:[1,0]
	v_pk_mul_f32 v[186:187], v[186:187], v[240:241] op_sel_hi:[1,0]
	v_pk_mul_f32 v[188:189], v[188:189], v[240:241] op_sel_hi:[1,0]
	v_pk_mul_f32 v[190:191], v[190:191], v[240:241] op_sel_hi:[1,0]
	v_pk_mul_f32 v[192:193], v[192:193], v[240:241] op_sel_hi:[1,0]
	v_pk_mul_f32 v[194:195], v[194:195], v[240:241] op_sel_hi:[1,0]
	v_pk_mul_f32 v[196:197], v[196:197], v[240:241] op_sel_hi:[1,0]
	v_pk_mul_f32 v[198:199], v[198:199], v[240:241] op_sel_hi:[1,0]
	v_pk_mul_f32 v[200:201], v[200:201], v[240:241] op_sel_hi:[1,0]
	v_pk_mul_f32 v[202:203], v[202:203], v[240:241] op_sel_hi:[1,0]
	v_pk_mul_f32 v[204:205], v[204:205], v[240:241] op_sel_hi:[1,0]
	v_pk_mul_f32 v[206:207], v[206:207], v[240:241] op_sel_hi:[1,0]
	v_pk_mul_f32 v[208:209], v[208:209], v[240:241] op_sel_hi:[1,0]
	v_pk_mul_f32 v[210:211], v[210:211], v[240:241] op_sel_hi:[1,0]
	v_pk_mul_f32 v[212:213], v[212:213], v[240:241] op_sel_hi:[1,0]
	v_pk_mul_f32 v[214:215], v[214:215], v[240:241] op_sel_hi:[1,0]
	v_mov_b32_e32 v240, 1.0
	v_mov_b32_e32 v89, 1.0
.Lgdn_nomat_0_1:
	v_mov_b32_e32 v238, v240
	v_mul_f32_e32 v90, v182, v89
	s_nop 1
	v_mfma_f32_16x16x4_f32 v[184:187], v62, v90, v[184:187]
	v_mfma_f32_16x16x4_f32 v[188:191], v63, v90, v[188:191]
	v_mfma_f32_16x16x4_f32 v[192:195], v64, v90, v[192:195]
	v_mfma_f32_16x16x4_f32 v[196:199], v65, v90, v[196:199]
	v_mfma_f32_16x16x4_f32 v[200:203], v66, v90, v[200:203]
	v_mfma_f32_16x16x4_f32 v[204:207], v67, v90, v[204:207]
	v_mfma_f32_16x16x4_f32 v[208:211], v68, v90, v[208:211]
	v_mfma_f32_16x16x4_f32 v[212:215], v69, v90, v[212:215]
	v_cndmask_b32_e32 v183, v82, v83, vcc
	v_cndmask_b32_e64 v183, v183, v84, s[4:5]
	v_cndmask_b32_e64 v183, v183, v85, s[6:7]
	v_mul_f32_e32 v179, v235, v183
	v_fmac_f32_e32 v179, v228, v108
	v_fmac_f32_e32 v179, v229, v109
	v_fmac_f32_e32 v179, v230, v110
	v_fmac_f32_e32 v179, v231, v111
	ds_write_b32 v172, v179 offset:1024
	v_add_u32_e32 v170, 0x1080, v170
	v_add_u32_e32 v237, 0x1080, v237
	v_add_u32_e32 v95, 0x1080, v95
	s_waitcnt lgkmcnt(1)
	v_mfma_f32_16x16x4_f32 v[96:99], v22, v184, 0
	v_mfma_f32_16x16x4_f32 v[100:103], v23, v185, 0
	v_mfma_f32_16x16x4_f32 v[96:99], v24, v186, v[96:99]
	v_mfma_f32_16x16x4_f32 v[100:103], v25, v187, v[100:103]
	v_mul_f32_e32 v129, v132, v70
	v_mul_f32_e32 v130, v133, v71
	v_mul_f32_e32 v131, v134, v72
	v_mul_f32_e32 v153, v135, v73
	v_mfma_f32_16x16x4_f32 v[96:99], v26, v188, v[96:99]
	v_mfma_f32_16x16x4_f32 v[100:103], v27, v189, v[100:103]
	v_mfma_f32_16x16x4_f32 v[96:99], v28, v190, v[96:99]
	v_mfma_f32_16x16x4_f32 v[100:103], v29, v191, v[100:103]
	v_mul_f32_e64 v114, -v132, v136
	v_mul_f32_e64 v115, -v133, v137
	v_mul_f32_e64 v116, -v134, v138
	v_mul_f32_e64 v117, -v135, v139
	v_mfma_f32_16x16x4_f32 v[96:99], v30, v192, v[96:99]
	v_mfma_f32_16x16x4_f32 v[100:103], v31, v193, v[100:103]
	v_mfma_f32_16x16x4_f32 v[96:99], v32, v194, v[96:99]
	v_mfma_f32_16x16x4_f32 v[100:103], v33, v195, v[100:103]
	v_mul_f32_e32 v240, v238, v139
	v_rcp_f32_e32 v89, v240
	v_readfirstlane_b32 s0, v240
	ds_read_b32 v86, v87 offset:128
	v_mfma_f32_16x16x4_f32 v[96:99], v34, v196, v[96:99]
	v_mfma_f32_16x16x4_f32 v[100:103], v35, v197, v[100:103]
	v_mfma_f32_16x16x4_f32 v[96:99], v36, v198, v[96:99]
	v_mfma_f32_16x16x4_f32 v[100:103], v37, v199, v[100:103]
	ds_read2_b32 v[62:63], v237 offset0:0 offset1:16
	ds_read2_b32 v[64:65], v237 offset0:32 offset1:48
	ds_read2_b32 v[66:67], v237 offset0:64 offset1:80
	ds_read2_b32 v[68:69], v237 offset0:96 offset1:112
	v_mfma_f32_16x16x4_f32 v[96:99], v38, v200, v[96:99]
	v_mfma_f32_16x16x4_f32 v[100:103], v39, v201, v[100:103]
	v_mfma_f32_16x16x4_f32 v[96:99], v40, v202, v[96:99]
	v_mfma_f32_16x16x4_f32 v[100:103], v41, v203, v[100:103]
	ds_read2st64_b32 v[74:75], v171 offset0:12 offset1:13
	ds_read2st64_b32 v[76:77], v171 offset0:14 offset1:15
	ds_read_b128 v[216:219], v175 offset:48
	ds_read_b128 v[220:223], v175 offset:304
	v_mfma_f32_16x16x4_f32 v[96:99], v42, v204, v[96:99]
	v_mfma_f32_16x16x4_f32 v[100:103], v43, v205, v[100:103]
	v_mfma_f32_16x16x4_f32 v[96:99], v44, v206, v[96:99]
	v_mfma_f32_16x16x4_f32 v[100:103], v45, v207, v[100:103]
	ds_read_b32 v235, v176 offset:304
	ds_read_b32 v236, v176 offset:560
	ds_read_b32 v234, v173 offset:688
	ds_read_b64 v[232:233], v173 offset:720
	v_mfma_f32_16x16x4_f32 v[96:99], v46, v208, v[96:99]
	v_mfma_f32_16x16x4_f32 v[100:103], v47, v209, v[100:103]
	v_mfma_f32_16x16x4_f32 v[96:99], v48, v210, v[96:99]
	v_mfma_f32_16x16x4_f32 v[100:103], v49, v211, v[100:103]
	ds_read_b128 v[224:227], v173 offset:752
	ds_read_b128 v[228:231], v174 offset:656
	v_mfma_f32_16x16x4_f32 v[96:99], v50, v212, v[96:99]
	v_mfma_f32_16x16x4_f32 v[100:103], v51, v213, v[100:103]
	v_mfma_f32_16x16x4_f32 v[96:99], v52, v214, v[96:99]
	v_mfma_f32_16x16x4_f32 v[100:103], v53, v215, v[100:103]
	s_nop 7
	s_nop 1
	v_pk_mul_f32 v[100:101], v[100:101], v[238:239] op_sel_hi:[1,0]
	v_pk_mul_f32 v[102:103], v[102:103], v[238:239] op_sel_hi:[1,0]
	v_pk_fma_f32 v[78:79], v[96:97], v[238:239], v[100:101] op_sel_hi:[1,0,1]
	v_pk_fma_f32 v[80:81], v[98:99], v[238:239], v[102:103] op_sel_hi:[1,0,1]
	v_pk_fma_f32 v[96:97], v[96:97], v[238:239], v[100:101] op_sel_hi:[1,0,1]
	v_pk_fma_f32 v[98:99], v[98:99], v[238:239], v[102:103] op_sel_hi:[1,0,1]
	s_nop 0
	v_permlane32_swap_b32_e32 v96, v78
	v_permlane32_swap_b32_e32 v97, v79
	v_permlane32_swap_b32_e32 v98, v80
	v_permlane32_swap_b32_e32 v99, v81
	v_mov_b32_e32 v82, v96
	v_mov_b32_e32 v83, v97
	v_mov_b32_e32 v84, v98
	v_mov_b32_e32 v85, v99
	s_nop 0
	v_permlane16_swap_b32_e32 v96, v82
	v_permlane16_swap_b32_e32 v97, v83
	v_permlane16_swap_b32_e32 v98, v84
	v_permlane16_swap_b32_e32 v99, v85
	v_fma_f32 v108, v114, v96, v129
	v_fma_f32 v109, v115, v97, v130
	v_fma_f32 v110, v116, v98, v131
	v_fma_f32 v111, v117, v99, v153
	v_fma_f32 v109, -v150, v108, v109
	v_fma_f32 v110, -v148, v108, v110
	v_fma_f32 v111, -v140, v108, v111
	v_fma_f32 v110, -v149, v109, v110
	v_fma_f32 v111, -v141, v109, v111
	v_fma_f32 v111, -v142, v110, v111
	v_cndmask_b32_e32 v182, v108, v109, vcc
	v_cndmask_b32_e64 v182, v182, v110, s[4:5]
	v_cndmask_b32_e64 v182, v182, v111, s[6:7]
	v_mul_f32_e32 v182, v152, v182
	s_cmp_lt_u32 s0, 0x2b800000
	s_cbranch_scc0 .Lgdn_nomat_1_0
	v_pk_mul_f32 v[184:185], v[184:185], v[240:241] op_sel_hi:[1,0]
	v_pk_mul_f32 v[186:187], v[186:187], v[240:241] op_sel_hi:[1,0]
	v_pk_mul_f32 v[188:189], v[188:189], v[240:241] op_sel_hi:[1,0]
	v_pk_mul_f32 v[190:191], v[190:191], v[240:241] op_sel_hi:[1,0]
	v_pk_mul_f32 v[192:193], v[192:193], v[240:241] op_sel_hi:[1,0]
	v_pk_mul_f32 v[194:195], v[194:195], v[240:241] op_sel_hi:[1,0]
	v_pk_mul_f32 v[196:197], v[196:197], v[240:241] op_sel_hi:[1,0]
	v_pk_mul_f32 v[198:199], v[198:199], v[240:241] op_sel_hi:[1,0]
	v_pk_mul_f32 v[200:201], v[200:201], v[240:241] op_sel_hi:[1,0]
	v_pk_mul_f32 v[202:203], v[202:203], v[240:241] op_sel_hi:[1,0]
	v_pk_mul_f32 v[204:205], v[204:205], v[240:241] op_sel_hi:[1,0]
	v_pk_mul_f32 v[206:207], v[206:207], v[240:241] op_sel_hi:[1,0]
	v_pk_mul_f32 v[208:209], v[208:209], v[240:241] op_sel_hi:[1,0]
	v_pk_mul_f32 v[210:211], v[210:211], v[240:241] op_sel_hi:[1,0]
	v_pk_mul_f32 v[212:213], v[212:213], v[240:241] op_sel_hi:[1,0]
	v_pk_mul_f32 v[214:215], v[214:215], v[240:241] op_sel_hi:[1,0]
	v_mov_b32_e32 v240, 1.0
	v_mov_b32_e32 v89, 1.0
.Lgdn_nomat_1_0:
	v_mov_b32_e32 v238, v240
	v_mul_f32_e32 v90, v182, v89
	s_nop 1
	v_mfma_f32_16x16x4_f32 v[184:187], v54, v90, v[184:187]
	v_mfma_f32_16x16x4_f32 v[188:191], v55, v90, v[188:191]
	v_mfma_f32_16x16x4_f32 v[192:195], v56, v90, v[192:195]
	v_mfma_f32_16x16x4_f32 v[196:199], v57, v90, v[196:199]
	v_mfma_f32_16x16x4_f32 v[200:203], v58, v90, v[200:203]
	v_mfma_f32_16x16x4_f32 v[204:207], v59, v90, v[204:207]
	v_mfma_f32_16x16x4_f32 v[208:211], v60, v90, v[208:211]
	v_mfma_f32_16x16x4_f32 v[212:215], v61, v90, v[212:215]
	v_pk_mul_f32 v[78:79], v[78:79], v[138:139] op_sel:[0,1] op_sel_hi:[1,1]
	v_pk_mul_f32 v[80:81], v[80:81], v[138:139] op_sel:[0,1] op_sel_hi:[1,1]
	v_cndmask_b32_e32 v183, v82, v83, vcc
	v_cndmask_b32_e64 v183, v183, v84, s[4:5]
	v_cndmask_b32_e64 v183, v183, v85, s[6:7]
	v_mul_f32_e32 v179, v151, v183
	v_fmac_f32_e32 v179, v144, v108
	v_fmac_f32_e32 v179, v145, v109
	v_fmac_f32_e32 v179, v146, v110
	v_fmac_f32_e32 v179, v147, v111
	ds_write_b32 v172, v179 offset:2048
	s_waitcnt lgkmcnt(1)
	v_mfma_f32_16x16x4_f32 v[96:99], v86, v182, v[78:81]
	s_nop 7
	v_mul_f32_e32 v129, v216, v74
	v_mul_f32_e32 v130, v217, v75
	v_mul_f32_e32 v131, v218, v76
	v_mul_f32_e32 v153, v219, v77
	v_mul_f32_e64 v114, -v216, v220
	v_mul_f32_e64 v115, -v217, v221
	v_mul_f32_e64 v116, -v218, v222
	v_mul_f32_e64 v117, -v219, v223
	v_mul_f32_e32 v240, v238, v223
	v_rcp_f32_e32 v89, v240
	v_readfirstlane_b32 s0, v240
	ds_read_b128 v[22:25], v169 offset:8448
	ds_read_b128 v[26:29], v169 offset:8512
	ds_read_b128 v[30:33], v169 offset:8576
	ds_read_b128 v[34:37], v169 offset:8640
	ds_read_b128 v[38:41], v169 offset:8704
	ds_read_b128 v[42:45], v169 offset:8768
	ds_read_b128 v[46:49], v169 offset:8832
	ds_read_b128 v[50:53], v169 offset:8896
	ds_read2_b32 v[54:55], v95 offset0:0 offset1:16
	ds_read2_b32 v[56:57], v95 offset0:32 offset1:48
	ds_read2_b32 v[58:59], v95 offset0:64 offset1:80
	ds_read2_b32 v[60:61], v95 offset0:96 offset1:112
	ds_read2st64_b32 v[70:71], v171 offset0:16 offset1:17
	ds_read2st64_b32 v[72:73], v171 offset0:18 offset1:19
	ds_read_b128 v[132:135], v175 offset:64
	ds_read_b128 v[136:139], v175 offset:320
	ds_read_b32 v151, v176 offset:320
	ds_read_b32 v152, v176 offset:576
	ds_read_b32 v150, v173 offset:1056
	ds_read_b64 v[148:149], v173 offset:1088
	ds_read_b128 v[140:143], v173 offset:1120
	ds_read_b128 v[144:147], v174 offset:1024
	v_mov_b32_e32 v82, v96
	v_mov_b32_e32 v83, v97
	v_mov_b32_e32 v84, v98
	v_mov_b32_e32 v85, v99
	s_nop 0
	v_permlane16_swap_b32_e32 v96, v82
	v_permlane16_swap_b32_e32 v97, v83
	v_permlane16_swap_b32_e32 v98, v84
	v_permlane16_swap_b32_e32 v99, v85
	v_fma_f32 v108, v114, v96, v129
	v_fma_f32 v109, v115, v97, v130
	v_fma_f32 v110, v116, v98, v131
	v_fma_f32 v111, v117, v99, v153
	v_fma_f32 v109, -v234, v108, v109
	v_fma_f32 v110, -v232, v108, v110
	v_fma_f32 v111, -v224, v108, v111
	v_fma_f32 v110, -v233, v109, v110
	v_fma_f32 v111, -v225, v109, v111
	v_fma_f32 v111, -v226, v110, v111
	v_cndmask_b32_e32 v182, v108, v109, vcc
	v_cndmask_b32_e64 v182, v182, v110, s[4:5]
	v_cndmask_b32_e64 v182, v182, v111, s[6:7]
	v_mul_f32_e32 v182, v236, v182
	s_cmp_lt_u32 s0, 0x2b800000
	s_cbranch_scc0 .Lgdn_nomat_1_1
	v_pk_mul_f32 v[184:185], v[184:185], v[240:241] op_sel_hi:[1,0]
	v_pk_mul_f32 v[186:187], v[186:187], v[240:241] op_sel_hi:[1,0]
	v_pk_mul_f32 v[188:189], v[188:189], v[240:241] op_sel_hi:[1,0]
	v_pk_mul_f32 v[190:191], v[190:191], v[240:241] op_sel_hi:[1,0]
	v_pk_mul_f32 v[192:193], v[192:193], v[240:241] op_sel_hi:[1,0]
	v_pk_mul_f32 v[194:195], v[194:195], v[240:241] op_sel_hi:[1,0]
	v_pk_mul_f32 v[196:197], v[196:197], v[240:241] op_sel_hi:[1,0]
	v_pk_mul_f32 v[198:199], v[198:199], v[240:241] op_sel_hi:[1,0]
	v_pk_mul_f32 v[200:201], v[200:201], v[240:241] op_sel_hi:[1,0]
	v_pk_mul_f32 v[202:203], v[202:203], v[240:241] op_sel_hi:[1,0]
	v_pk_mul_f32 v[204:205], v[204:205], v[240:241] op_sel_hi:[1,0]
	v_pk_mul_f32 v[206:207], v[206:207], v[240:241] op_sel_hi:[1,0]
	v_pk_mul_f32 v[208:209], v[208:209], v[240:241] op_sel_hi:[1,0]
	v_pk_mul_f32 v[210:211], v[210:211], v[240:241] op_sel_hi:[1,0]
	v_pk_mul_f32 v[212:213], v[212:213], v[240:241] op_sel_hi:[1,0]
	v_pk_mul_f32 v[214:215], v[214:215], v[240:241] op_sel_hi:[1,0]
	v_mov_b32_e32 v240, 1.0
	v_mov_b32_e32 v89, 1.0
.Lgdn_nomat_1_1:
	v_mov_b32_e32 v238, v240
	v_mul_f32_e32 v90, v182, v89
	s_nop 1
	v_mfma_f32_16x16x4_f32 v[184:187], v62, v90, v[184:187]
	v_mfma_f32_16x16x4_f32 v[188:191], v63, v90, v[188:191]
	v_mfma_f32_16x16x4_f32 v[192:195], v64, v90, v[192:195]
	v_mfma_f32_16x16x4_f32 v[196:199], v65, v90, v[196:199]
	v_mfma_f32_16x16x4_f32 v[200:203], v66, v90, v[200:203]
	v_mfma_f32_16x16x4_f32 v[204:207], v67, v90, v[204:207]
	v_mfma_f32_16x16x4_f32 v[208:211], v68, v90, v[208:211]
	v_mfma_f32_16x16x4_f32 v[212:215], v69, v90, v[212:215]
	v_cndmask_b32_e32 v183, v82, v83, vcc
	v_cndmask_b32_e64 v183, v183, v84, s[4:5]
	v_cndmask_b32_e64 v183, v183, v85, s[6:7]
	v_mul_f32_e32 v179, v235, v183
	v_fmac_f32_e32 v179, v228, v108
	v_fmac_f32_e32 v179, v229, v109
	v_fmac_f32_e32 v179, v230, v110
	v_fmac_f32_e32 v179, v231, v111
	ds_write_b32 v172, v179 offset:3072
	v_add_u32_e32 v170, 0x1080, v170
	v_add_u32_e32 v237, 0x1080, v237
	v_add_u32_e32 v95, 0x1080, v95
	s_waitcnt lgkmcnt(1)
	v_mfma_f32_16x16x4_f32 v[96:99], v22, v184, 0
	v_mfma_f32_16x16x4_f32 v[100:103], v23, v185, 0
	v_mfma_f32_16x16x4_f32 v[96:99], v24, v186, v[96:99]
	v_mfma_f32_16x16x4_f32 v[100:103], v25, v187, v[100:103]
	v_mul_f32_e32 v129, v132, v70
	v_mul_f32_e32 v130, v133, v71
	v_mul_f32_e32 v131, v134, v72
	v_mul_f32_e32 v153, v135, v73
	v_mfma_f32_16x16x4_f32 v[96:99], v26, v188, v[96:99]
	v_mfma_f32_16x16x4_f32 v[100:103], v27, v189, v[100:103]
	v_mfma_f32_16x16x4_f32 v[96:99], v28, v190, v[96:99]
	v_mfma_f32_16x16x4_f32 v[100:103], v29, v191, v[100:103]
	v_mul_f32_e64 v114, -v132, v136
	v_mul_f32_e64 v115, -v133, v137
	v_mul_f32_e64 v116, -v134, v138
	v_mul_f32_e64 v117, -v135, v139
	v_mfma_f32_16x16x4_f32 v[96:99], v30, v192, v[96:99]
	v_mfma_f32_16x16x4_f32 v[100:103], v31, v193, v[100:103]
	v_mfma_f32_16x16x4_f32 v[96:99], v32, v194, v[96:99]
	v_mfma_f32_16x16x4_f32 v[100:103], v33, v195, v[100:103]
	v_mul_f32_e32 v240, v238, v139
	v_rcp_f32_e32 v89, v240
	v_readfirstlane_b32 s0, v240
	ds_read_b32 v86, v87 offset:256
	v_mfma_f32_16x16x4_f32 v[96:99], v34, v196, v[96:99]
	v_mfma_f32_16x16x4_f32 v[100:103], v35, v197, v[100:103]
	v_mfma_f32_16x16x4_f32 v[96:99], v36, v198, v[96:99]
	v_mfma_f32_16x16x4_f32 v[100:103], v37, v199, v[100:103]
	ds_read2_b32 v[62:63], v237 offset0:0 offset1:16
	ds_read2_b32 v[64:65], v237 offset0:32 offset1:48
	ds_read2_b32 v[66:67], v237 offset0:64 offset1:80
	ds_read2_b32 v[68:69], v237 offset0:96 offset1:112
	v_mfma_f32_16x16x4_f32 v[96:99], v38, v200, v[96:99]
	v_mfma_f32_16x16x4_f32 v[100:103], v39, v201, v[100:103]
	v_mfma_f32_16x16x4_f32 v[96:99], v40, v202, v[96:99]
	v_mfma_f32_16x16x4_f32 v[100:103], v41, v203, v[100:103]
	ds_read2st64_b32 v[74:75], v171 offset0:20 offset1:21
	ds_read2st64_b32 v[76:77], v171 offset0:22 offset1:23
	ds_read_b128 v[216:219], v175 offset:80
	ds_read_b128 v[220:223], v175 offset:336
	v_mfma_f32_16x16x4_f32 v[96:99], v42, v204, v[96:99]
	v_mfma_f32_16x16x4_f32 v[100:103], v43, v205, v[100:103]
	v_mfma_f32_16x16x4_f32 v[96:99], v44, v206, v[96:99]
	v_mfma_f32_16x16x4_f32 v[100:103], v45, v207, v[100:103]
	ds_read_b32 v235, v176 offset:336
	ds_read_b32 v236, v176 offset:592
	ds_read_b32 v234, v173 offset:1200
	ds_read_b64 v[232:233], v173 offset:1232
	v_mfma_f32_16x16x4_f32 v[96:99], v46, v208, v[96:99]
	v_mfma_f32_16x16x4_f32 v[100:103], v47, v209, v[100:103]
	v_mfma_f32_16x16x4_f32 v[96:99], v48, v210, v[96:99]
	v_mfma_f32_16x16x4_f32 v[100:103], v49, v211, v[100:103]
	ds_read_b128 v[224:227], v173 offset:1264
	ds_read_b128 v[228:231], v174 offset:1168
	v_mfma_f32_16x16x4_f32 v[96:99], v50, v212, v[96:99]
	v_mfma_f32_16x16x4_f32 v[100:103], v51, v213, v[100:103]
	v_mfma_f32_16x16x4_f32 v[96:99], v52, v214, v[96:99]
	v_mfma_f32_16x16x4_f32 v[100:103], v53, v215, v[100:103]
	s_nop 7
	s_nop 1
	v_pk_mul_f32 v[100:101], v[100:101], v[238:239] op_sel_hi:[1,0]
	v_pk_mul_f32 v[102:103], v[102:103], v[238:239] op_sel_hi:[1,0]
	v_pk_fma_f32 v[78:79], v[96:97], v[238:239], v[100:101] op_sel_hi:[1,0,1]
	v_pk_fma_f32 v[80:81], v[98:99], v[238:239], v[102:103] op_sel_hi:[1,0,1]
	v_pk_fma_f32 v[96:97], v[96:97], v[238:239], v[100:101] op_sel_hi:[1,0,1]
	v_pk_fma_f32 v[98:99], v[98:99], v[238:239], v[102:103] op_sel_hi:[1,0,1]
	s_nop 0
	v_permlane32_swap_b32_e32 v96, v78
	v_permlane32_swap_b32_e32 v97, v79
	v_permlane32_swap_b32_e32 v98, v80
	v_permlane32_swap_b32_e32 v99, v81
	v_mov_b32_e32 v82, v96
	v_mov_b32_e32 v83, v97
	v_mov_b32_e32 v84, v98
	v_mov_b32_e32 v85, v99
	s_nop 0
	v_permlane16_swap_b32_e32 v96, v82
	v_permlane16_swap_b32_e32 v97, v83
	v_permlane16_swap_b32_e32 v98, v84
	v_permlane16_swap_b32_e32 v99, v85
	v_fma_f32 v108, v114, v96, v129
	v_fma_f32 v109, v115, v97, v130
	v_fma_f32 v110, v116, v98, v131
	v_fma_f32 v111, v117, v99, v153
	v_fma_f32 v109, -v150, v108, v109
	v_fma_f32 v110, -v148, v108, v110
	v_fma_f32 v111, -v140, v108, v111
	v_fma_f32 v110, -v149, v109, v110
	v_fma_f32 v111, -v141, v109, v111
	v_fma_f32 v111, -v142, v110, v111
	v_cndmask_b32_e32 v182, v108, v109, vcc
	v_cndmask_b32_e64 v182, v182, v110, s[4:5]
	v_cndmask_b32_e64 v182, v182, v111, s[6:7]
	v_mul_f32_e32 v182, v152, v182
	s_cmp_lt_u32 s0, 0x2b800000
	s_cbranch_scc0 .Lgdn_nomat_2_0
	v_pk_mul_f32 v[184:185], v[184:185], v[240:241] op_sel_hi:[1,0]
	v_pk_mul_f32 v[186:187], v[186:187], v[240:241] op_sel_hi:[1,0]
	v_pk_mul_f32 v[188:189], v[188:189], v[240:241] op_sel_hi:[1,0]
	v_pk_mul_f32 v[190:191], v[190:191], v[240:241] op_sel_hi:[1,0]
	v_pk_mul_f32 v[192:193], v[192:193], v[240:241] op_sel_hi:[1,0]
	v_pk_mul_f32 v[194:195], v[194:195], v[240:241] op_sel_hi:[1,0]
	v_pk_mul_f32 v[196:197], v[196:197], v[240:241] op_sel_hi:[1,0]
	v_pk_mul_f32 v[198:199], v[198:199], v[240:241] op_sel_hi:[1,0]
	v_pk_mul_f32 v[200:201], v[200:201], v[240:241] op_sel_hi:[1,0]
	v_pk_mul_f32 v[202:203], v[202:203], v[240:241] op_sel_hi:[1,0]
	v_pk_mul_f32 v[204:205], v[204:205], v[240:241] op_sel_hi:[1,0]
	v_pk_mul_f32 v[206:207], v[206:207], v[240:241] op_sel_hi:[1,0]
	v_pk_mul_f32 v[208:209], v[208:209], v[240:241] op_sel_hi:[1,0]
	v_pk_mul_f32 v[210:211], v[210:211], v[240:241] op_sel_hi:[1,0]
	v_pk_mul_f32 v[212:213], v[212:213], v[240:241] op_sel_hi:[1,0]
	v_pk_mul_f32 v[214:215], v[214:215], v[240:241] op_sel_hi:[1,0]
	v_mov_b32_e32 v240, 1.0
	v_mov_b32_e32 v89, 1.0
.Lgdn_nomat_2_0:
	v_mov_b32_e32 v238, v240
	v_mul_f32_e32 v90, v182, v89
	s_nop 1
	v_mfma_f32_16x16x4_f32 v[184:187], v54, v90, v[184:187]
	v_mfma_f32_16x16x4_f32 v[188:191], v55, v90, v[188:191]
	v_mfma_f32_16x16x4_f32 v[192:195], v56, v90, v[192:195]
	v_mfma_f32_16x16x4_f32 v[196:199], v57, v90, v[196:199]
	v_mfma_f32_16x16x4_f32 v[200:203], v58, v90, v[200:203]
	v_mfma_f32_16x16x4_f32 v[204:207], v59, v90, v[204:207]
	v_mfma_f32_16x16x4_f32 v[208:211], v60, v90, v[208:211]
	v_mfma_f32_16x16x4_f32 v[212:215], v61, v90, v[212:215]
	v_pk_mul_f32 v[78:79], v[78:79], v[138:139] op_sel:[0,1] op_sel_hi:[1,1]
	v_pk_mul_f32 v[80:81], v[80:81], v[138:139] op_sel:[0,1] op_sel_hi:[1,1]
	v_cndmask_b32_e32 v183, v82, v83, vcc
	v_cndmask_b32_e64 v183, v183, v84, s[4:5]
	v_cndmask_b32_e64 v183, v183, v85, s[6:7]
	v_mul_f32_e32 v179, v151, v183
	v_fmac_f32_e32 v179, v144, v108
	v_fmac_f32_e32 v179, v145, v109
	v_fmac_f32_e32 v179, v146, v110
	v_fmac_f32_e32 v179, v147, v111
	ds_write_b32 v172, v179 offset:4096
	s_waitcnt lgkmcnt(1)
	v_mfma_f32_16x16x4_f32 v[96:99], v86, v182, v[78:81]
	s_nop 7
	v_mul_f32_e32 v129, v216, v74
	v_mul_f32_e32 v130, v217, v75
	v_mul_f32_e32 v131, v218, v76
	v_mul_f32_e32 v153, v219, v77
	v_mul_f32_e64 v114, -v216, v220
	v_mul_f32_e64 v115, -v217, v221
	v_mul_f32_e64 v116, -v218, v222
	v_mul_f32_e64 v117, -v219, v223
	v_mul_f32_e32 v240, v238, v223
	v_rcp_f32_e32 v89, v240
	v_readfirstlane_b32 s0, v240
	ds_read_b128 v[22:25], v169 offset:12672
	ds_read_b128 v[26:29], v169 offset:12736
	ds_read_b128 v[30:33], v169 offset:12800
	ds_read_b128 v[34:37], v169 offset:12864
	ds_read_b128 v[38:41], v169 offset:12928
	ds_read_b128 v[42:45], v169 offset:12992
	ds_read_b128 v[46:49], v169 offset:13056
	ds_read_b128 v[50:53], v169 offset:13120
	ds_read2_b32 v[54:55], v95 offset0:0 offset1:16
	ds_read2_b32 v[56:57], v95 offset0:32 offset1:48
	ds_read2_b32 v[58:59], v95 offset0:64 offset1:80
	ds_read2_b32 v[60:61], v95 offset0:96 offset1:112
	ds_read2st64_b32 v[70:71], v171 offset0:24 offset1:25
	ds_read2st64_b32 v[72:73], v171 offset0:26 offset1:27
	ds_read_b128 v[132:135], v175 offset:96
	ds_read_b128 v[136:139], v175 offset:352
	ds_read_b32 v151, v176 offset:352
	ds_read_b32 v152, v176 offset:608
	ds_read_b32 v150, v173 offset:1568
	ds_read_b64 v[148:149], v173 offset:1600
	ds_read_b128 v[140:143], v173 offset:1632
	ds_read_b128 v[144:147], v174 offset:1536
	v_mov_b32_e32 v82, v96
	v_mov_b32_e32 v83, v97
	v_mov_b32_e32 v84, v98
	v_mov_b32_e32 v85, v99
	s_nop 0
	v_permlane16_swap_b32_e32 v96, v82
	v_permlane16_swap_b32_e32 v97, v83
	v_permlane16_swap_b32_e32 v98, v84
	v_permlane16_swap_b32_e32 v99, v85
	v_fma_f32 v108, v114, v96, v129
	v_fma_f32 v109, v115, v97, v130
	v_fma_f32 v110, v116, v98, v131
	v_fma_f32 v111, v117, v99, v153
	v_fma_f32 v109, -v234, v108, v109
	v_fma_f32 v110, -v232, v108, v110
	v_fma_f32 v111, -v224, v108, v111
	v_fma_f32 v110, -v233, v109, v110
	v_fma_f32 v111, -v225, v109, v111
	v_fma_f32 v111, -v226, v110, v111
	v_cndmask_b32_e32 v182, v108, v109, vcc
	v_cndmask_b32_e64 v182, v182, v110, s[4:5]
	v_cndmask_b32_e64 v182, v182, v111, s[6:7]
	v_mul_f32_e32 v182, v236, v182
	s_cmp_lt_u32 s0, 0x2b800000
	s_cbranch_scc0 .Lgdn_nomat_2_1
	v_pk_mul_f32 v[184:185], v[184:185], v[240:241] op_sel_hi:[1,0]
	v_pk_mul_f32 v[186:187], v[186:187], v[240:241] op_sel_hi:[1,0]
	v_pk_mul_f32 v[188:189], v[188:189], v[240:241] op_sel_hi:[1,0]
	v_pk_mul_f32 v[190:191], v[190:191], v[240:241] op_sel_hi:[1,0]
	v_pk_mul_f32 v[192:193], v[192:193], v[240:241] op_sel_hi:[1,0]
	v_pk_mul_f32 v[194:195], v[194:195], v[240:241] op_sel_hi:[1,0]
	v_pk_mul_f32 v[196:197], v[196:197], v[240:241] op_sel_hi:[1,0]
	v_pk_mul_f32 v[198:199], v[198:199], v[240:241] op_sel_hi:[1,0]
	v_pk_mul_f32 v[200:201], v[200:201], v[240:241] op_sel_hi:[1,0]
	v_pk_mul_f32 v[202:203], v[202:203], v[240:241] op_sel_hi:[1,0]
	v_pk_mul_f32 v[204:205], v[204:205], v[240:241] op_sel_hi:[1,0]
	v_pk_mul_f32 v[206:207], v[206:207], v[240:241] op_sel_hi:[1,0]
	v_pk_mul_f32 v[208:209], v[208:209], v[240:241] op_sel_hi:[1,0]
	v_pk_mul_f32 v[210:211], v[210:211], v[240:241] op_sel_hi:[1,0]
	v_pk_mul_f32 v[212:213], v[212:213], v[240:241] op_sel_hi:[1,0]
	v_pk_mul_f32 v[214:215], v[214:215], v[240:241] op_sel_hi:[1,0]
	v_mov_b32_e32 v240, 1.0
	v_mov_b32_e32 v89, 1.0
.Lgdn_nomat_2_1:
	v_mov_b32_e32 v238, v240
	v_mul_f32_e32 v90, v182, v89
	s_nop 1
	v_mfma_f32_16x16x4_f32 v[184:187], v62, v90, v[184:187]
	v_mfma_f32_16x16x4_f32 v[188:191], v63, v90, v[188:191]
	v_mfma_f32_16x16x4_f32 v[192:195], v64, v90, v[192:195]
	v_mfma_f32_16x16x4_f32 v[196:199], v65, v90, v[196:199]
	v_mfma_f32_16x16x4_f32 v[200:203], v66, v90, v[200:203]
	v_mfma_f32_16x16x4_f32 v[204:207], v67, v90, v[204:207]
	v_mfma_f32_16x16x4_f32 v[208:211], v68, v90, v[208:211]
	v_mfma_f32_16x16x4_f32 v[212:215], v69, v90, v[212:215]
	v_cndmask_b32_e32 v183, v82, v83, vcc
	v_cndmask_b32_e64 v183, v183, v84, s[4:5]
	v_cndmask_b32_e64 v183, v183, v85, s[6:7]
	v_mul_f32_e32 v179, v235, v183
	v_fmac_f32_e32 v179, v228, v108
	v_fmac_f32_e32 v179, v229, v109
	v_fmac_f32_e32 v179, v230, v110
	v_fmac_f32_e32 v179, v231, v111
	ds_write_b32 v172, v179 offset:5120
	v_add_u32_e32 v170, 0x1080, v170
	v_add_u32_e32 v237, 0x1080, v237
	v_add_u32_e32 v95, 0x1080, v95
	s_waitcnt lgkmcnt(1)
	v_mfma_f32_16x16x4_f32 v[96:99], v22, v184, 0
	v_mfma_f32_16x16x4_f32 v[100:103], v23, v185, 0
	v_mfma_f32_16x16x4_f32 v[96:99], v24, v186, v[96:99]
	v_mfma_f32_16x16x4_f32 v[100:103], v25, v187, v[100:103]
	v_mul_f32_e32 v129, v132, v70
	v_mul_f32_e32 v130, v133, v71
	v_mul_f32_e32 v131, v134, v72
	v_mul_f32_e32 v153, v135, v73
	v_mfma_f32_16x16x4_f32 v[96:99], v26, v188, v[96:99]
	v_mfma_f32_16x16x4_f32 v[100:103], v27, v189, v[100:103]
	v_mfma_f32_16x16x4_f32 v[96:99], v28, v190, v[96:99]
	v_mfma_f32_16x16x4_f32 v[100:103], v29, v191, v[100:103]
	v_mul_f32_e64 v114, -v132, v136
	v_mul_f32_e64 v115, -v133, v137
	v_mul_f32_e64 v116, -v134, v138
	v_mul_f32_e64 v117, -v135, v139
	v_mfma_f32_16x16x4_f32 v[96:99], v30, v192, v[96:99]
	v_mfma_f32_16x16x4_f32 v[100:103], v31, v193, v[100:103]
	v_mfma_f32_16x16x4_f32 v[96:99], v32, v194, v[96:99]
	v_mfma_f32_16x16x4_f32 v[100:103], v33, v195, v[100:103]
	v_mul_f32_e32 v240, v238, v139
	v_rcp_f32_e32 v89, v240
	v_readfirstlane_b32 s0, v240
	ds_read_b32 v86, v87 offset:384
	v_mfma_f32_16x16x4_f32 v[96:99], v34, v196, v[96:99]
	v_mfma_f32_16x16x4_f32 v[100:103], v35, v197, v[100:103]
	v_mfma_f32_16x16x4_f32 v[96:99], v36, v198, v[96:99]
	v_mfma_f32_16x16x4_f32 v[100:103], v37, v199, v[100:103]
	ds_read2_b32 v[62:63], v237 offset0:0 offset1:16
	ds_read2_b32 v[64:65], v237 offset0:32 offset1:48
	ds_read2_b32 v[66:67], v237 offset0:64 offset1:80
	ds_read2_b32 v[68:69], v237 offset0:96 offset1:112
	v_mfma_f32_16x16x4_f32 v[96:99], v38, v200, v[96:99]
	v_mfma_f32_16x16x4_f32 v[100:103], v39, v201, v[100:103]
	v_mfma_f32_16x16x4_f32 v[96:99], v40, v202, v[96:99]
	v_mfma_f32_16x16x4_f32 v[100:103], v41, v203, v[100:103]
	ds_read2st64_b32 v[74:75], v171 offset0:28 offset1:29
	ds_read2st64_b32 v[76:77], v171 offset0:30 offset1:31
	ds_read_b128 v[216:219], v175 offset:112
	ds_read_b128 v[220:223], v175 offset:368
	v_mfma_f32_16x16x4_f32 v[96:99], v42, v204, v[96:99]
	v_mfma_f32_16x16x4_f32 v[100:103], v43, v205, v[100:103]
	v_mfma_f32_16x16x4_f32 v[96:99], v44, v206, v[96:99]
	v_mfma_f32_16x16x4_f32 v[100:103], v45, v207, v[100:103]
	ds_read_b32 v235, v176 offset:368
	ds_read_b32 v236, v176 offset:624
	ds_read_b32 v234, v173 offset:1712
	ds_read_b64 v[232:233], v173 offset:1744
	v_mfma_f32_16x16x4_f32 v[96:99], v46, v208, v[96:99]
	v_mfma_f32_16x16x4_f32 v[100:103], v47, v209, v[100:103]
	v_mfma_f32_16x16x4_f32 v[96:99], v48, v210, v[96:99]
	v_mfma_f32_16x16x4_f32 v[100:103], v49, v211, v[100:103]
	ds_read_b128 v[224:227], v173 offset:1776
	ds_read_b128 v[228:231], v174 offset:1680
	v_mfma_f32_16x16x4_f32 v[96:99], v50, v212, v[96:99]
	v_mfma_f32_16x16x4_f32 v[100:103], v51, v213, v[100:103]
	v_mfma_f32_16x16x4_f32 v[96:99], v52, v214, v[96:99]
	v_mfma_f32_16x16x4_f32 v[100:103], v53, v215, v[100:103]
	s_nop 7
	s_nop 1
	v_pk_mul_f32 v[100:101], v[100:101], v[238:239] op_sel_hi:[1,0]
	v_pk_mul_f32 v[102:103], v[102:103], v[238:239] op_sel_hi:[1,0]
	v_pk_fma_f32 v[78:79], v[96:97], v[238:239], v[100:101] op_sel_hi:[1,0,1]
	v_pk_fma_f32 v[80:81], v[98:99], v[238:239], v[102:103] op_sel_hi:[1,0,1]
	v_pk_fma_f32 v[96:97], v[96:97], v[238:239], v[100:101] op_sel_hi:[1,0,1]
	v_pk_fma_f32 v[98:99], v[98:99], v[238:239], v[102:103] op_sel_hi:[1,0,1]
	s_nop 0
	v_permlane32_swap_b32_e32 v96, v78
	v_permlane32_swap_b32_e32 v97, v79
	v_permlane32_swap_b32_e32 v98, v80
	v_permlane32_swap_b32_e32 v99, v81
	v_mov_b32_e32 v82, v96
	v_mov_b32_e32 v83, v97
	v_mov_b32_e32 v84, v98
	v_mov_b32_e32 v85, v99
	s_nop 0
	v_permlane16_swap_b32_e32 v96, v82
	v_permlane16_swap_b32_e32 v97, v83
	v_permlane16_swap_b32_e32 v98, v84
	v_permlane16_swap_b32_e32 v99, v85
	v_fma_f32 v108, v114, v96, v129
	v_fma_f32 v109, v115, v97, v130
	v_fma_f32 v110, v116, v98, v131
	v_fma_f32 v111, v117, v99, v153
	v_fma_f32 v109, -v150, v108, v109
	v_fma_f32 v110, -v148, v108, v110
	v_fma_f32 v111, -v140, v108, v111
	v_fma_f32 v110, -v149, v109, v110
	v_fma_f32 v111, -v141, v109, v111
	v_fma_f32 v111, -v142, v110, v111
	v_cndmask_b32_e32 v182, v108, v109, vcc
	v_cndmask_b32_e64 v182, v182, v110, s[4:5]
	v_cndmask_b32_e64 v182, v182, v111, s[6:7]
	v_mul_f32_e32 v182, v152, v182
	s_cmp_lt_u32 s0, 0x2b800000
	s_cbranch_scc0 .Lgdn_nomat_3_0
	v_pk_mul_f32 v[184:185], v[184:185], v[240:241] op_sel_hi:[1,0]
	v_pk_mul_f32 v[186:187], v[186:187], v[240:241] op_sel_hi:[1,0]
	v_pk_mul_f32 v[188:189], v[188:189], v[240:241] op_sel_hi:[1,0]
	v_pk_mul_f32 v[190:191], v[190:191], v[240:241] op_sel_hi:[1,0]
	v_pk_mul_f32 v[192:193], v[192:193], v[240:241] op_sel_hi:[1,0]
	v_pk_mul_f32 v[194:195], v[194:195], v[240:241] op_sel_hi:[1,0]
	v_pk_mul_f32 v[196:197], v[196:197], v[240:241] op_sel_hi:[1,0]
	v_pk_mul_f32 v[198:199], v[198:199], v[240:241] op_sel_hi:[1,0]
	v_pk_mul_f32 v[200:201], v[200:201], v[240:241] op_sel_hi:[1,0]
	v_pk_mul_f32 v[202:203], v[202:203], v[240:241] op_sel_hi:[1,0]
	v_pk_mul_f32 v[204:205], v[204:205], v[240:241] op_sel_hi:[1,0]
	v_pk_mul_f32 v[206:207], v[206:207], v[240:241] op_sel_hi:[1,0]
	v_pk_mul_f32 v[208:209], v[208:209], v[240:241] op_sel_hi:[1,0]
	v_pk_mul_f32 v[210:211], v[210:211], v[240:241] op_sel_hi:[1,0]
	v_pk_mul_f32 v[212:213], v[212:213], v[240:241] op_sel_hi:[1,0]
	v_pk_mul_f32 v[214:215], v[214:215], v[240:241] op_sel_hi:[1,0]
	v_mov_b32_e32 v240, 1.0
	v_mov_b32_e32 v89, 1.0
.Lgdn_nomat_3_0:
	v_mov_b32_e32 v238, v240
	v_mul_f32_e32 v90, v182, v89
	s_nop 1
	v_mfma_f32_16x16x4_f32 v[184:187], v54, v90, v[184:187]
	v_mfma_f32_16x16x4_f32 v[188:191], v55, v90, v[188:191]
	v_mfma_f32_16x16x4_f32 v[192:195], v56, v90, v[192:195]
	v_mfma_f32_16x16x4_f32 v[196:199], v57, v90, v[196:199]
	v_mfma_f32_16x16x4_f32 v[200:203], v58, v90, v[200:203]
	v_mfma_f32_16x16x4_f32 v[204:207], v59, v90, v[204:207]
	v_mfma_f32_16x16x4_f32 v[208:211], v60, v90, v[208:211]
	v_mfma_f32_16x16x4_f32 v[212:215], v61, v90, v[212:215]
	v_pk_mul_f32 v[78:79], v[78:79], v[138:139] op_sel:[0,1] op_sel_hi:[1,1]
	v_pk_mul_f32 v[80:81], v[80:81], v[138:139] op_sel:[0,1] op_sel_hi:[1,1]
	v_cndmask_b32_e32 v183, v82, v83, vcc
	v_cndmask_b32_e64 v183, v183, v84, s[4:5]
	v_cndmask_b32_e64 v183, v183, v85, s[6:7]
	v_mul_f32_e32 v179, v151, v183
	v_fmac_f32_e32 v179, v144, v108
	v_fmac_f32_e32 v179, v145, v109
	v_fmac_f32_e32 v179, v146, v110
	v_fmac_f32_e32 v179, v147, v111
	ds_write_b32 v172, v179 offset:6144
	s_waitcnt lgkmcnt(1)
	v_mfma_f32_16x16x4_f32 v[96:99], v86, v182, v[78:81]
	s_nop 7
	v_mul_f32_e32 v129, v216, v74
	v_mul_f32_e32 v130, v217, v75
	v_mul_f32_e32 v131, v218, v76
	v_mul_f32_e32 v153, v219, v77
	v_mul_f32_e64 v114, -v216, v220
	v_mul_f32_e64 v115, -v217, v221
	v_mul_f32_e64 v116, -v218, v222
	v_mul_f32_e64 v117, -v219, v223
	v_mul_f32_e32 v240, v238, v223
	v_rcp_f32_e32 v89, v240
	v_readfirstlane_b32 s0, v240
	ds_read_b128 v[22:25], v169 offset:16896
	ds_read_b128 v[26:29], v169 offset:16960
	ds_read_b128 v[30:33], v169 offset:17024
	ds_read_b128 v[34:37], v169 offset:17088
	ds_read_b128 v[38:41], v169 offset:17152
	ds_read_b128 v[42:45], v169 offset:17216
	ds_read_b128 v[46:49], v169 offset:17280
	ds_read_b128 v[50:53], v169 offset:17344
	ds_read2_b32 v[54:55], v95 offset0:0 offset1:16
	ds_read2_b32 v[56:57], v95 offset0:32 offset1:48
	ds_read2_b32 v[58:59], v95 offset0:64 offset1:80
	ds_read2_b32 v[60:61], v95 offset0:96 offset1:112
	ds_read2st64_b32 v[70:71], v171 offset0:32 offset1:33
	ds_read2st64_b32 v[72:73], v171 offset0:34 offset1:35
	ds_read_b128 v[132:135], v175 offset:128
	ds_read_b128 v[136:139], v175 offset:384
	ds_read_b32 v151, v176 offset:384
	ds_read_b32 v152, v176 offset:640
	ds_read_b32 v150, v173 offset:2080
	ds_read_b64 v[148:149], v173 offset:2112
	ds_read_b128 v[140:143], v173 offset:2144
	ds_read_b128 v[144:147], v174 offset:2048
	v_mov_b32_e32 v82, v96
	v_mov_b32_e32 v83, v97
	v_mov_b32_e32 v84, v98
	v_mov_b32_e32 v85, v99
	s_nop 0
	v_permlane16_swap_b32_e32 v96, v82
	v_permlane16_swap_b32_e32 v97, v83
	v_permlane16_swap_b32_e32 v98, v84
	v_permlane16_swap_b32_e32 v99, v85
	v_fma_f32 v108, v114, v96, v129
	v_fma_f32 v109, v115, v97, v130
	v_fma_f32 v110, v116, v98, v131
	v_fma_f32 v111, v117, v99, v153
	v_fma_f32 v109, -v234, v108, v109
	v_fma_f32 v110, -v232, v108, v110
	v_fma_f32 v111, -v224, v108, v111
	v_fma_f32 v110, -v233, v109, v110
	v_fma_f32 v111, -v225, v109, v111
	v_fma_f32 v111, -v226, v110, v111
	v_cndmask_b32_e32 v182, v108, v109, vcc
	v_cndmask_b32_e64 v182, v182, v110, s[4:5]
	v_cndmask_b32_e64 v182, v182, v111, s[6:7]
	v_mul_f32_e32 v182, v236, v182
	s_cmp_lt_u32 s0, 0x2b800000
	s_cbranch_scc0 .Lgdn_nomat_3_1
	v_pk_mul_f32 v[184:185], v[184:185], v[240:241] op_sel_hi:[1,0]
	v_pk_mul_f32 v[186:187], v[186:187], v[240:241] op_sel_hi:[1,0]
	v_pk_mul_f32 v[188:189], v[188:189], v[240:241] op_sel_hi:[1,0]
	v_pk_mul_f32 v[190:191], v[190:191], v[240:241] op_sel_hi:[1,0]
	v_pk_mul_f32 v[192:193], v[192:193], v[240:241] op_sel_hi:[1,0]
	v_pk_mul_f32 v[194:195], v[194:195], v[240:241] op_sel_hi:[1,0]
	v_pk_mul_f32 v[196:197], v[196:197], v[240:241] op_sel_hi:[1,0]
	v_pk_mul_f32 v[198:199], v[198:199], v[240:241] op_sel_hi:[1,0]
	v_pk_mul_f32 v[200:201], v[200:201], v[240:241] op_sel_hi:[1,0]
	v_pk_mul_f32 v[202:203], v[202:203], v[240:241] op_sel_hi:[1,0]
	v_pk_mul_f32 v[204:205], v[204:205], v[240:241] op_sel_hi:[1,0]
	v_pk_mul_f32 v[206:207], v[206:207], v[240:241] op_sel_hi:[1,0]
	v_pk_mul_f32 v[208:209], v[208:209], v[240:241] op_sel_hi:[1,0]
	v_pk_mul_f32 v[210:211], v[210:211], v[240:241] op_sel_hi:[1,0]
	v_pk_mul_f32 v[212:213], v[212:213], v[240:241] op_sel_hi:[1,0]
	v_pk_mul_f32 v[214:215], v[214:215], v[240:241] op_sel_hi:[1,0]
	v_mov_b32_e32 v240, 1.0
	v_mov_b32_e32 v89, 1.0
.Lgdn_nomat_3_1:
	v_mov_b32_e32 v238, v240
	v_mul_f32_e32 v90, v182, v89
	s_nop 1
	v_mfma_f32_16x16x4_f32 v[184:187], v62, v90, v[184:187]
	v_mfma_f32_16x16x4_f32 v[188:191], v63, v90, v[188:191]
	v_mfma_f32_16x16x4_f32 v[192:195], v64, v90, v[192:195]
	v_mfma_f32_16x16x4_f32 v[196:199], v65, v90, v[196:199]
	v_mfma_f32_16x16x4_f32 v[200:203], v66, v90, v[200:203]
	v_mfma_f32_16x16x4_f32 v[204:207], v67, v90, v[204:207]
	v_mfma_f32_16x16x4_f32 v[208:211], v68, v90, v[208:211]
	v_mfma_f32_16x16x4_f32 v[212:215], v69, v90, v[212:215]
	v_cndmask_b32_e32 v183, v82, v83, vcc
	v_cndmask_b32_e64 v183, v183, v84, s[4:5]
	v_cndmask_b32_e64 v183, v183, v85, s[6:7]
	v_mul_f32_e32 v179, v235, v183
	v_fmac_f32_e32 v179, v228, v108
	v_fmac_f32_e32 v179, v229, v109
	v_fmac_f32_e32 v179, v230, v110
	v_fmac_f32_e32 v179, v231, v111
	ds_write_b32 v172, v179 offset:7168
	v_add_u32_e32 v170, 0x1080, v170
	v_add_u32_e32 v237, 0x1080, v237
	v_add_u32_e32 v95, 0x1080, v95
	s_waitcnt lgkmcnt(1)
	v_mfma_f32_16x16x4_f32 v[96:99], v22, v184, 0
	v_mfma_f32_16x16x4_f32 v[100:103], v23, v185, 0
	v_mfma_f32_16x16x4_f32 v[96:99], v24, v186, v[96:99]
	v_mfma_f32_16x16x4_f32 v[100:103], v25, v187, v[100:103]
	v_mul_f32_e32 v129, v132, v70
	v_mul_f32_e32 v130, v133, v71
	v_mul_f32_e32 v131, v134, v72
	v_mul_f32_e32 v153, v135, v73
	v_mfma_f32_16x16x4_f32 v[96:99], v26, v188, v[96:99]
	v_mfma_f32_16x16x4_f32 v[100:103], v27, v189, v[100:103]
	v_mfma_f32_16x16x4_f32 v[96:99], v28, v190, v[96:99]
	v_mfma_f32_16x16x4_f32 v[100:103], v29, v191, v[100:103]
	v_mul_f32_e64 v114, -v132, v136
	v_mul_f32_e64 v115, -v133, v137
	v_mul_f32_e64 v116, -v134, v138
	v_mul_f32_e64 v117, -v135, v139
	v_mfma_f32_16x16x4_f32 v[96:99], v30, v192, v[96:99]
	v_mfma_f32_16x16x4_f32 v[100:103], v31, v193, v[100:103]
	v_mfma_f32_16x16x4_f32 v[96:99], v32, v194, v[96:99]
	v_mfma_f32_16x16x4_f32 v[100:103], v33, v195, v[100:103]
	v_mul_f32_e32 v240, v238, v139
	v_rcp_f32_e32 v89, v240
	v_readfirstlane_b32 s0, v240
	ds_read_b32 v86, v87 offset:512
	v_mfma_f32_16x16x4_f32 v[96:99], v34, v196, v[96:99]
	v_mfma_f32_16x16x4_f32 v[100:103], v35, v197, v[100:103]
	v_mfma_f32_16x16x4_f32 v[96:99], v36, v198, v[96:99]
	v_mfma_f32_16x16x4_f32 v[100:103], v37, v199, v[100:103]
	ds_read2_b32 v[62:63], v237 offset0:0 offset1:16
	ds_read2_b32 v[64:65], v237 offset0:32 offset1:48
	ds_read2_b32 v[66:67], v237 offset0:64 offset1:80
	ds_read2_b32 v[68:69], v237 offset0:96 offset1:112
	v_mfma_f32_16x16x4_f32 v[96:99], v38, v200, v[96:99]
	v_mfma_f32_16x16x4_f32 v[100:103], v39, v201, v[100:103]
	v_mfma_f32_16x16x4_f32 v[96:99], v40, v202, v[96:99]
	v_mfma_f32_16x16x4_f32 v[100:103], v41, v203, v[100:103]
	ds_read2st64_b32 v[74:75], v171 offset0:36 offset1:37
	ds_read2st64_b32 v[76:77], v171 offset0:38 offset1:39
	ds_read_b128 v[216:219], v175 offset:144
	ds_read_b128 v[220:223], v175 offset:400
	v_mfma_f32_16x16x4_f32 v[96:99], v42, v204, v[96:99]
	v_mfma_f32_16x16x4_f32 v[100:103], v43, v205, v[100:103]
	v_mfma_f32_16x16x4_f32 v[96:99], v44, v206, v[96:99]
	v_mfma_f32_16x16x4_f32 v[100:103], v45, v207, v[100:103]
	ds_read_b32 v235, v176 offset:400
	ds_read_b32 v236, v176 offset:656
	ds_read_b32 v234, v173 offset:2224
	ds_read_b64 v[232:233], v173 offset:2256
	v_mfma_f32_16x16x4_f32 v[96:99], v46, v208, v[96:99]
	v_mfma_f32_16x16x4_f32 v[100:103], v47, v209, v[100:103]
	v_mfma_f32_16x16x4_f32 v[96:99], v48, v210, v[96:99]
	v_mfma_f32_16x16x4_f32 v[100:103], v49, v211, v[100:103]
	ds_read_b128 v[224:227], v173 offset:2288
	ds_read_b128 v[228:231], v174 offset:2192
	v_mfma_f32_16x16x4_f32 v[96:99], v50, v212, v[96:99]
	v_mfma_f32_16x16x4_f32 v[100:103], v51, v213, v[100:103]
	v_mfma_f32_16x16x4_f32 v[96:99], v52, v214, v[96:99]
	v_mfma_f32_16x16x4_f32 v[100:103], v53, v215, v[100:103]
	s_nop 7
	s_nop 1
	v_pk_mul_f32 v[100:101], v[100:101], v[238:239] op_sel_hi:[1,0]
	v_pk_mul_f32 v[102:103], v[102:103], v[238:239] op_sel_hi:[1,0]
	v_pk_fma_f32 v[78:79], v[96:97], v[238:239], v[100:101] op_sel_hi:[1,0,1]
	v_pk_fma_f32 v[80:81], v[98:99], v[238:239], v[102:103] op_sel_hi:[1,0,1]
	v_pk_fma_f32 v[96:97], v[96:97], v[238:239], v[100:101] op_sel_hi:[1,0,1]
	v_pk_fma_f32 v[98:99], v[98:99], v[238:239], v[102:103] op_sel_hi:[1,0,1]
	s_nop 0
	v_permlane32_swap_b32_e32 v96, v78
	v_permlane32_swap_b32_e32 v97, v79
	v_permlane32_swap_b32_e32 v98, v80
	v_permlane32_swap_b32_e32 v99, v81
	v_mov_b32_e32 v82, v96
	v_mov_b32_e32 v83, v97
	v_mov_b32_e32 v84, v98
	v_mov_b32_e32 v85, v99
	s_nop 0
	v_permlane16_swap_b32_e32 v96, v82
	v_permlane16_swap_b32_e32 v97, v83
	v_permlane16_swap_b32_e32 v98, v84
	v_permlane16_swap_b32_e32 v99, v85
	v_fma_f32 v108, v114, v96, v129
	v_fma_f32 v109, v115, v97, v130
	v_fma_f32 v110, v116, v98, v131
	v_fma_f32 v111, v117, v99, v153
	v_fma_f32 v109, -v150, v108, v109
	v_fma_f32 v110, -v148, v108, v110
	v_fma_f32 v111, -v140, v108, v111
	v_fma_f32 v110, -v149, v109, v110
	v_fma_f32 v111, -v141, v109, v111
	v_fma_f32 v111, -v142, v110, v111
	v_cndmask_b32_e32 v182, v108, v109, vcc
	v_cndmask_b32_e64 v182, v182, v110, s[4:5]
	v_cndmask_b32_e64 v182, v182, v111, s[6:7]
	v_mul_f32_e32 v182, v152, v182
	s_cmp_lt_u32 s0, 0x2b800000
	s_cbranch_scc0 .Lgdn_nomat_4_0
	v_pk_mul_f32 v[184:185], v[184:185], v[240:241] op_sel_hi:[1,0]
	v_pk_mul_f32 v[186:187], v[186:187], v[240:241] op_sel_hi:[1,0]
	v_pk_mul_f32 v[188:189], v[188:189], v[240:241] op_sel_hi:[1,0]
	v_pk_mul_f32 v[190:191], v[190:191], v[240:241] op_sel_hi:[1,0]
	v_pk_mul_f32 v[192:193], v[192:193], v[240:241] op_sel_hi:[1,0]
	v_pk_mul_f32 v[194:195], v[194:195], v[240:241] op_sel_hi:[1,0]
	v_pk_mul_f32 v[196:197], v[196:197], v[240:241] op_sel_hi:[1,0]
	v_pk_mul_f32 v[198:199], v[198:199], v[240:241] op_sel_hi:[1,0]
	v_pk_mul_f32 v[200:201], v[200:201], v[240:241] op_sel_hi:[1,0]
	v_pk_mul_f32 v[202:203], v[202:203], v[240:241] op_sel_hi:[1,0]
	v_pk_mul_f32 v[204:205], v[204:205], v[240:241] op_sel_hi:[1,0]
	v_pk_mul_f32 v[206:207], v[206:207], v[240:241] op_sel_hi:[1,0]
	v_pk_mul_f32 v[208:209], v[208:209], v[240:241] op_sel_hi:[1,0]
	v_pk_mul_f32 v[210:211], v[210:211], v[240:241] op_sel_hi:[1,0]
	v_pk_mul_f32 v[212:213], v[212:213], v[240:241] op_sel_hi:[1,0]
	v_pk_mul_f32 v[214:215], v[214:215], v[240:241] op_sel_hi:[1,0]
	v_mov_b32_e32 v240, 1.0
	v_mov_b32_e32 v89, 1.0
.Lgdn_nomat_4_0:
	v_mov_b32_e32 v238, v240
	v_mul_f32_e32 v90, v182, v89
	s_nop 1
	v_mfma_f32_16x16x4_f32 v[184:187], v54, v90, v[184:187]
	v_mfma_f32_16x16x4_f32 v[188:191], v55, v90, v[188:191]
	v_mfma_f32_16x16x4_f32 v[192:195], v56, v90, v[192:195]
	v_mfma_f32_16x16x4_f32 v[196:199], v57, v90, v[196:199]
	v_mfma_f32_16x16x4_f32 v[200:203], v58, v90, v[200:203]
	v_mfma_f32_16x16x4_f32 v[204:207], v59, v90, v[204:207]
	v_mfma_f32_16x16x4_f32 v[208:211], v60, v90, v[208:211]
	v_mfma_f32_16x16x4_f32 v[212:215], v61, v90, v[212:215]
	v_pk_mul_f32 v[78:79], v[78:79], v[138:139] op_sel:[0,1] op_sel_hi:[1,1]
	v_pk_mul_f32 v[80:81], v[80:81], v[138:139] op_sel:[0,1] op_sel_hi:[1,1]
	v_cndmask_b32_e32 v183, v82, v83, vcc
	v_cndmask_b32_e64 v183, v183, v84, s[4:5]
	v_cndmask_b32_e64 v183, v183, v85, s[6:7]
	v_mul_f32_e32 v179, v151, v183
	v_fmac_f32_e32 v179, v144, v108
	v_fmac_f32_e32 v179, v145, v109
	v_fmac_f32_e32 v179, v146, v110
	v_fmac_f32_e32 v179, v147, v111
	ds_write_b32 v172, v179 offset:8192
	s_waitcnt lgkmcnt(1)
	v_mfma_f32_16x16x4_f32 v[96:99], v86, v182, v[78:81]
	s_nop 7
	v_mul_f32_e32 v129, v216, v74
	v_mul_f32_e32 v130, v217, v75
	v_mul_f32_e32 v131, v218, v76
	v_mul_f32_e32 v153, v219, v77
	v_mul_f32_e64 v114, -v216, v220
	v_mul_f32_e64 v115, -v217, v221
	v_mul_f32_e64 v116, -v218, v222
	v_mul_f32_e64 v117, -v219, v223
	v_mul_f32_e32 v240, v238, v223
	v_rcp_f32_e32 v89, v240
	v_readfirstlane_b32 s0, v240
	ds_read_b128 v[22:25], v169 offset:21120
	ds_read_b128 v[26:29], v169 offset:21184
	ds_read_b128 v[30:33], v169 offset:21248
	ds_read_b128 v[34:37], v169 offset:21312
	ds_read_b128 v[38:41], v169 offset:21376
	ds_read_b128 v[42:45], v169 offset:21440
	ds_read_b128 v[46:49], v169 offset:21504
	ds_read_b128 v[50:53], v169 offset:21568
	ds_read2_b32 v[54:55], v95 offset0:0 offset1:16
	ds_read2_b32 v[56:57], v95 offset0:32 offset1:48
	ds_read2_b32 v[58:59], v95 offset0:64 offset1:80
	ds_read2_b32 v[60:61], v95 offset0:96 offset1:112
	ds_read2st64_b32 v[70:71], v171 offset0:40 offset1:41
	ds_read2st64_b32 v[72:73], v171 offset0:42 offset1:43
	ds_read_b128 v[132:135], v175 offset:160
	ds_read_b128 v[136:139], v175 offset:416
	ds_read_b32 v151, v176 offset:416
	ds_read_b32 v152, v176 offset:672
	ds_read_b32 v150, v173 offset:2592
	ds_read_b64 v[148:149], v173 offset:2624
	ds_read_b128 v[140:143], v173 offset:2656
	ds_read_b128 v[144:147], v174 offset:2560
	v_mov_b32_e32 v82, v96
	v_mov_b32_e32 v83, v97
	v_mov_b32_e32 v84, v98
	v_mov_b32_e32 v85, v99
	s_nop 0
	v_permlane16_swap_b32_e32 v96, v82
	v_permlane16_swap_b32_e32 v97, v83
	v_permlane16_swap_b32_e32 v98, v84
	v_permlane16_swap_b32_e32 v99, v85
	v_fma_f32 v108, v114, v96, v129
	v_fma_f32 v109, v115, v97, v130
	v_fma_f32 v110, v116, v98, v131
	v_fma_f32 v111, v117, v99, v153
	v_fma_f32 v109, -v234, v108, v109
	v_fma_f32 v110, -v232, v108, v110
	v_fma_f32 v111, -v224, v108, v111
	v_fma_f32 v110, -v233, v109, v110
	v_fma_f32 v111, -v225, v109, v111
	v_fma_f32 v111, -v226, v110, v111
	v_cndmask_b32_e32 v182, v108, v109, vcc
	v_cndmask_b32_e64 v182, v182, v110, s[4:5]
	v_cndmask_b32_e64 v182, v182, v111, s[6:7]
	v_mul_f32_e32 v182, v236, v182
	s_cmp_lt_u32 s0, 0x2b800000
	s_cbranch_scc0 .Lgdn_nomat_4_1
	v_pk_mul_f32 v[184:185], v[184:185], v[240:241] op_sel_hi:[1,0]
	v_pk_mul_f32 v[186:187], v[186:187], v[240:241] op_sel_hi:[1,0]
	v_pk_mul_f32 v[188:189], v[188:189], v[240:241] op_sel_hi:[1,0]
	v_pk_mul_f32 v[190:191], v[190:191], v[240:241] op_sel_hi:[1,0]
	v_pk_mul_f32 v[192:193], v[192:193], v[240:241] op_sel_hi:[1,0]
	v_pk_mul_f32 v[194:195], v[194:195], v[240:241] op_sel_hi:[1,0]
	v_pk_mul_f32 v[196:197], v[196:197], v[240:241] op_sel_hi:[1,0]
	v_pk_mul_f32 v[198:199], v[198:199], v[240:241] op_sel_hi:[1,0]
	v_pk_mul_f32 v[200:201], v[200:201], v[240:241] op_sel_hi:[1,0]
	v_pk_mul_f32 v[202:203], v[202:203], v[240:241] op_sel_hi:[1,0]
	v_pk_mul_f32 v[204:205], v[204:205], v[240:241] op_sel_hi:[1,0]
	v_pk_mul_f32 v[206:207], v[206:207], v[240:241] op_sel_hi:[1,0]
	v_pk_mul_f32 v[208:209], v[208:209], v[240:241] op_sel_hi:[1,0]
	v_pk_mul_f32 v[210:211], v[210:211], v[240:241] op_sel_hi:[1,0]
	v_pk_mul_f32 v[212:213], v[212:213], v[240:241] op_sel_hi:[1,0]
	v_pk_mul_f32 v[214:215], v[214:215], v[240:241] op_sel_hi:[1,0]
	v_mov_b32_e32 v240, 1.0
	v_mov_b32_e32 v89, 1.0
.Lgdn_nomat_4_1:
	v_mov_b32_e32 v238, v240
	v_mul_f32_e32 v90, v182, v89
	s_nop 1
	v_mfma_f32_16x16x4_f32 v[184:187], v62, v90, v[184:187]
	v_mfma_f32_16x16x4_f32 v[188:191], v63, v90, v[188:191]
	v_mfma_f32_16x16x4_f32 v[192:195], v64, v90, v[192:195]
	v_mfma_f32_16x16x4_f32 v[196:199], v65, v90, v[196:199]
	v_mfma_f32_16x16x4_f32 v[200:203], v66, v90, v[200:203]
	v_mfma_f32_16x16x4_f32 v[204:207], v67, v90, v[204:207]
	v_mfma_f32_16x16x4_f32 v[208:211], v68, v90, v[208:211]
	v_mfma_f32_16x16x4_f32 v[212:215], v69, v90, v[212:215]
	v_cndmask_b32_e32 v183, v82, v83, vcc
	v_cndmask_b32_e64 v183, v183, v84, s[4:5]
	v_cndmask_b32_e64 v183, v183, v85, s[6:7]
	v_mul_f32_e32 v179, v235, v183
	v_fmac_f32_e32 v179, v228, v108
	v_fmac_f32_e32 v179, v229, v109
	v_fmac_f32_e32 v179, v230, v110
	v_fmac_f32_e32 v179, v231, v111
	ds_write_b32 v172, v179 offset:9216
	v_add_u32_e32 v170, 0x1080, v170
	v_add_u32_e32 v237, 0x1080, v237
	v_add_u32_e32 v95, 0x1080, v95
	s_waitcnt lgkmcnt(1)
	v_mfma_f32_16x16x4_f32 v[96:99], v22, v184, 0
	v_mfma_f32_16x16x4_f32 v[100:103], v23, v185, 0
	v_mfma_f32_16x16x4_f32 v[96:99], v24, v186, v[96:99]
	v_mfma_f32_16x16x4_f32 v[100:103], v25, v187, v[100:103]
	v_mul_f32_e32 v129, v132, v70
	v_mul_f32_e32 v130, v133, v71
	v_mul_f32_e32 v131, v134, v72
	v_mul_f32_e32 v153, v135, v73
	v_mfma_f32_16x16x4_f32 v[96:99], v26, v188, v[96:99]
	v_mfma_f32_16x16x4_f32 v[100:103], v27, v189, v[100:103]
	v_mfma_f32_16x16x4_f32 v[96:99], v28, v190, v[96:99]
	v_mfma_f32_16x16x4_f32 v[100:103], v29, v191, v[100:103]
	v_mul_f32_e64 v114, -v132, v136
	v_mul_f32_e64 v115, -v133, v137
	v_mul_f32_e64 v116, -v134, v138
	v_mul_f32_e64 v117, -v135, v139
	v_mfma_f32_16x16x4_f32 v[96:99], v30, v192, v[96:99]
	v_mfma_f32_16x16x4_f32 v[100:103], v31, v193, v[100:103]
	v_mfma_f32_16x16x4_f32 v[96:99], v32, v194, v[96:99]
	v_mfma_f32_16x16x4_f32 v[100:103], v33, v195, v[100:103]
	v_mul_f32_e32 v240, v238, v139
	v_rcp_f32_e32 v89, v240
	v_readfirstlane_b32 s0, v240
	ds_read_b32 v86, v87 offset:640
	v_mfma_f32_16x16x4_f32 v[96:99], v34, v196, v[96:99]
	v_mfma_f32_16x16x4_f32 v[100:103], v35, v197, v[100:103]
	v_mfma_f32_16x16x4_f32 v[96:99], v36, v198, v[96:99]
	v_mfma_f32_16x16x4_f32 v[100:103], v37, v199, v[100:103]
	ds_read2_b32 v[62:63], v237 offset0:0 offset1:16
	ds_read2_b32 v[64:65], v237 offset0:32 offset1:48
	ds_read2_b32 v[66:67], v237 offset0:64 offset1:80
	ds_read2_b32 v[68:69], v237 offset0:96 offset1:112
	v_mfma_f32_16x16x4_f32 v[96:99], v38, v200, v[96:99]
	v_mfma_f32_16x16x4_f32 v[100:103], v39, v201, v[100:103]
	v_mfma_f32_16x16x4_f32 v[96:99], v40, v202, v[96:99]
	v_mfma_f32_16x16x4_f32 v[100:103], v41, v203, v[100:103]
	ds_read2st64_b32 v[74:75], v171 offset0:44 offset1:45
	ds_read2st64_b32 v[76:77], v171 offset0:46 offset1:47
	ds_read_b128 v[216:219], v175 offset:176
	ds_read_b128 v[220:223], v175 offset:432
	v_mfma_f32_16x16x4_f32 v[96:99], v42, v204, v[96:99]
	v_mfma_f32_16x16x4_f32 v[100:103], v43, v205, v[100:103]
	v_mfma_f32_16x16x4_f32 v[96:99], v44, v206, v[96:99]
	v_mfma_f32_16x16x4_f32 v[100:103], v45, v207, v[100:103]
	ds_read_b32 v235, v176 offset:432
	ds_read_b32 v236, v176 offset:688
	ds_read_b32 v234, v173 offset:2736
	ds_read_b64 v[232:233], v173 offset:2768
	v_mfma_f32_16x16x4_f32 v[96:99], v46, v208, v[96:99]
	v_mfma_f32_16x16x4_f32 v[100:103], v47, v209, v[100:103]
	v_mfma_f32_16x16x4_f32 v[96:99], v48, v210, v[96:99]
	v_mfma_f32_16x16x4_f32 v[100:103], v49, v211, v[100:103]
	ds_read_b128 v[224:227], v173 offset:2800
	ds_read_b128 v[228:231], v174 offset:2704
	v_mfma_f32_16x16x4_f32 v[96:99], v50, v212, v[96:99]
	v_mfma_f32_16x16x4_f32 v[100:103], v51, v213, v[100:103]
	v_mfma_f32_16x16x4_f32 v[96:99], v52, v214, v[96:99]
	v_mfma_f32_16x16x4_f32 v[100:103], v53, v215, v[100:103]
	s_nop 7
	s_nop 1
	v_pk_mul_f32 v[100:101], v[100:101], v[238:239] op_sel_hi:[1,0]
	v_pk_mul_f32 v[102:103], v[102:103], v[238:239] op_sel_hi:[1,0]
	v_pk_fma_f32 v[78:79], v[96:97], v[238:239], v[100:101] op_sel_hi:[1,0,1]
	v_pk_fma_f32 v[80:81], v[98:99], v[238:239], v[102:103] op_sel_hi:[1,0,1]
	v_pk_fma_f32 v[96:97], v[96:97], v[238:239], v[100:101] op_sel_hi:[1,0,1]
	v_pk_fma_f32 v[98:99], v[98:99], v[238:239], v[102:103] op_sel_hi:[1,0,1]
	s_nop 0
	v_permlane32_swap_b32_e32 v96, v78
	v_permlane32_swap_b32_e32 v97, v79
	v_permlane32_swap_b32_e32 v98, v80
	v_permlane32_swap_b32_e32 v99, v81
	v_mov_b32_e32 v82, v96
	v_mov_b32_e32 v83, v97
	v_mov_b32_e32 v84, v98
	v_mov_b32_e32 v85, v99
	s_nop 0
	v_permlane16_swap_b32_e32 v96, v82
	v_permlane16_swap_b32_e32 v97, v83
	v_permlane16_swap_b32_e32 v98, v84
	v_permlane16_swap_b32_e32 v99, v85
	v_fma_f32 v108, v114, v96, v129
	v_fma_f32 v109, v115, v97, v130
	v_fma_f32 v110, v116, v98, v131
	v_fma_f32 v111, v117, v99, v153
	v_fma_f32 v109, -v150, v108, v109
	v_fma_f32 v110, -v148, v108, v110
	v_fma_f32 v111, -v140, v108, v111
	v_fma_f32 v110, -v149, v109, v110
	v_fma_f32 v111, -v141, v109, v111
	v_fma_f32 v111, -v142, v110, v111
	v_cndmask_b32_e32 v182, v108, v109, vcc
	v_cndmask_b32_e64 v182, v182, v110, s[4:5]
	v_cndmask_b32_e64 v182, v182, v111, s[6:7]
	v_mul_f32_e32 v182, v152, v182
	s_cmp_lt_u32 s0, 0x2b800000
	s_cbranch_scc0 .Lgdn_nomat_5_0
	v_pk_mul_f32 v[184:185], v[184:185], v[240:241] op_sel_hi:[1,0]
	v_pk_mul_f32 v[186:187], v[186:187], v[240:241] op_sel_hi:[1,0]
	v_pk_mul_f32 v[188:189], v[188:189], v[240:241] op_sel_hi:[1,0]
	v_pk_mul_f32 v[190:191], v[190:191], v[240:241] op_sel_hi:[1,0]
	v_pk_mul_f32 v[192:193], v[192:193], v[240:241] op_sel_hi:[1,0]
	v_pk_mul_f32 v[194:195], v[194:195], v[240:241] op_sel_hi:[1,0]
	v_pk_mul_f32 v[196:197], v[196:197], v[240:241] op_sel_hi:[1,0]
	v_pk_mul_f32 v[198:199], v[198:199], v[240:241] op_sel_hi:[1,0]
	v_pk_mul_f32 v[200:201], v[200:201], v[240:241] op_sel_hi:[1,0]
	v_pk_mul_f32 v[202:203], v[202:203], v[240:241] op_sel_hi:[1,0]
	v_pk_mul_f32 v[204:205], v[204:205], v[240:241] op_sel_hi:[1,0]
	v_pk_mul_f32 v[206:207], v[206:207], v[240:241] op_sel_hi:[1,0]
	v_pk_mul_f32 v[208:209], v[208:209], v[240:241] op_sel_hi:[1,0]
	v_pk_mul_f32 v[210:211], v[210:211], v[240:241] op_sel_hi:[1,0]
	v_pk_mul_f32 v[212:213], v[212:213], v[240:241] op_sel_hi:[1,0]
	v_pk_mul_f32 v[214:215], v[214:215], v[240:241] op_sel_hi:[1,0]
	v_mov_b32_e32 v240, 1.0
	v_mov_b32_e32 v89, 1.0
.Lgdn_nomat_5_0:
	v_mov_b32_e32 v238, v240
	v_mul_f32_e32 v90, v182, v89
	s_nop 1
	v_mfma_f32_16x16x4_f32 v[184:187], v54, v90, v[184:187]
	v_mfma_f32_16x16x4_f32 v[188:191], v55, v90, v[188:191]
	v_mfma_f32_16x16x4_f32 v[192:195], v56, v90, v[192:195]
	v_mfma_f32_16x16x4_f32 v[196:199], v57, v90, v[196:199]
	v_mfma_f32_16x16x4_f32 v[200:203], v58, v90, v[200:203]
	v_mfma_f32_16x16x4_f32 v[204:207], v59, v90, v[204:207]
	v_mfma_f32_16x16x4_f32 v[208:211], v60, v90, v[208:211]
	v_mfma_f32_16x16x4_f32 v[212:215], v61, v90, v[212:215]
	v_pk_mul_f32 v[78:79], v[78:79], v[138:139] op_sel:[0,1] op_sel_hi:[1,1]
	v_pk_mul_f32 v[80:81], v[80:81], v[138:139] op_sel:[0,1] op_sel_hi:[1,1]
	v_cndmask_b32_e32 v183, v82, v83, vcc
	v_cndmask_b32_e64 v183, v183, v84, s[4:5]
	v_cndmask_b32_e64 v183, v183, v85, s[6:7]
	v_mul_f32_e32 v179, v151, v183
	v_fmac_f32_e32 v179, v144, v108
	v_fmac_f32_e32 v179, v145, v109
	v_fmac_f32_e32 v179, v146, v110
	v_fmac_f32_e32 v179, v147, v111
	ds_write_b32 v172, v179 offset:10240
	s_waitcnt lgkmcnt(1)
	v_mfma_f32_16x16x4_f32 v[96:99], v86, v182, v[78:81]
	s_nop 7
	v_mul_f32_e32 v129, v216, v74
	v_mul_f32_e32 v130, v217, v75
	v_mul_f32_e32 v131, v218, v76
	v_mul_f32_e32 v153, v219, v77
	v_mul_f32_e64 v114, -v216, v220
	v_mul_f32_e64 v115, -v217, v221
	v_mul_f32_e64 v116, -v218, v222
	v_mul_f32_e64 v117, -v219, v223
	v_mul_f32_e32 v240, v238, v223
	v_rcp_f32_e32 v89, v240
	v_readfirstlane_b32 s0, v240
	ds_read_b128 v[22:25], v169 offset:25344
	ds_read_b128 v[26:29], v169 offset:25408
	ds_read_b128 v[30:33], v169 offset:25472
	ds_read_b128 v[34:37], v169 offset:25536
	ds_read_b128 v[38:41], v169 offset:25600
	ds_read_b128 v[42:45], v169 offset:25664
	ds_read_b128 v[46:49], v169 offset:25728
	ds_read_b128 v[50:53], v169 offset:25792
	ds_read2_b32 v[54:55], v95 offset0:0 offset1:16
	ds_read2_b32 v[56:57], v95 offset0:32 offset1:48
	ds_read2_b32 v[58:59], v95 offset0:64 offset1:80
	ds_read2_b32 v[60:61], v95 offset0:96 offset1:112
	ds_read2st64_b32 v[70:71], v171 offset0:48 offset1:49
	ds_read2st64_b32 v[72:73], v171 offset0:50 offset1:51
	ds_read_b128 v[132:135], v175 offset:192
	ds_read_b128 v[136:139], v175 offset:448
	ds_read_b32 v151, v176 offset:448
	ds_read_b32 v152, v176 offset:704
	ds_read_b32 v150, v173 offset:3104
	ds_read_b64 v[148:149], v173 offset:3136
	ds_read_b128 v[140:143], v173 offset:3168
	ds_read_b128 v[144:147], v174 offset:3072
	v_mov_b32_e32 v82, v96
	v_mov_b32_e32 v83, v97
	v_mov_b32_e32 v84, v98
	v_mov_b32_e32 v85, v99
	s_nop 0
	v_permlane16_swap_b32_e32 v96, v82
	v_permlane16_swap_b32_e32 v97, v83
	v_permlane16_swap_b32_e32 v98, v84
	v_permlane16_swap_b32_e32 v99, v85
	v_fma_f32 v108, v114, v96, v129
	v_fma_f32 v109, v115, v97, v130
	v_fma_f32 v110, v116, v98, v131
	v_fma_f32 v111, v117, v99, v153
	v_fma_f32 v109, -v234, v108, v109
	v_fma_f32 v110, -v232, v108, v110
	v_fma_f32 v111, -v224, v108, v111
	v_fma_f32 v110, -v233, v109, v110
	v_fma_f32 v111, -v225, v109, v111
	v_fma_f32 v111, -v226, v110, v111
	v_cndmask_b32_e32 v182, v108, v109, vcc
	v_cndmask_b32_e64 v182, v182, v110, s[4:5]
	v_cndmask_b32_e64 v182, v182, v111, s[6:7]
	v_mul_f32_e32 v182, v236, v182
	s_cmp_lt_u32 s0, 0x2b800000
	s_cbranch_scc0 .Lgdn_nomat_5_1
	v_pk_mul_f32 v[184:185], v[184:185], v[240:241] op_sel_hi:[1,0]
	v_pk_mul_f32 v[186:187], v[186:187], v[240:241] op_sel_hi:[1,0]
	v_pk_mul_f32 v[188:189], v[188:189], v[240:241] op_sel_hi:[1,0]
	v_pk_mul_f32 v[190:191], v[190:191], v[240:241] op_sel_hi:[1,0]
	v_pk_mul_f32 v[192:193], v[192:193], v[240:241] op_sel_hi:[1,0]
	v_pk_mul_f32 v[194:195], v[194:195], v[240:241] op_sel_hi:[1,0]
	v_pk_mul_f32 v[196:197], v[196:197], v[240:241] op_sel_hi:[1,0]
	v_pk_mul_f32 v[198:199], v[198:199], v[240:241] op_sel_hi:[1,0]
	v_pk_mul_f32 v[200:201], v[200:201], v[240:241] op_sel_hi:[1,0]
	v_pk_mul_f32 v[202:203], v[202:203], v[240:241] op_sel_hi:[1,0]
	v_pk_mul_f32 v[204:205], v[204:205], v[240:241] op_sel_hi:[1,0]
	v_pk_mul_f32 v[206:207], v[206:207], v[240:241] op_sel_hi:[1,0]
	v_pk_mul_f32 v[208:209], v[208:209], v[240:241] op_sel_hi:[1,0]
	v_pk_mul_f32 v[210:211], v[210:211], v[240:241] op_sel_hi:[1,0]
	v_pk_mul_f32 v[212:213], v[212:213], v[240:241] op_sel_hi:[1,0]
	v_pk_mul_f32 v[214:215], v[214:215], v[240:241] op_sel_hi:[1,0]
	v_mov_b32_e32 v240, 1.0
	v_mov_b32_e32 v89, 1.0
.Lgdn_nomat_5_1:
	v_mov_b32_e32 v238, v240
	v_mul_f32_e32 v90, v182, v89
	s_nop 1
	v_mfma_f32_16x16x4_f32 v[184:187], v62, v90, v[184:187]
	v_mfma_f32_16x16x4_f32 v[188:191], v63, v90, v[188:191]
	v_mfma_f32_16x16x4_f32 v[192:195], v64, v90, v[192:195]
	v_mfma_f32_16x16x4_f32 v[196:199], v65, v90, v[196:199]
	v_mfma_f32_16x16x4_f32 v[200:203], v66, v90, v[200:203]
	v_mfma_f32_16x16x4_f32 v[204:207], v67, v90, v[204:207]
	v_mfma_f32_16x16x4_f32 v[208:211], v68, v90, v[208:211]
	v_mfma_f32_16x16x4_f32 v[212:215], v69, v90, v[212:215]
	v_cndmask_b32_e32 v183, v82, v83, vcc
	v_cndmask_b32_e64 v183, v183, v84, s[4:5]
	v_cndmask_b32_e64 v183, v183, v85, s[6:7]
	v_mul_f32_e32 v179, v235, v183
	v_fmac_f32_e32 v179, v228, v108
	v_fmac_f32_e32 v179, v229, v109
	v_fmac_f32_e32 v179, v230, v110
	v_fmac_f32_e32 v179, v231, v111
	ds_write_b32 v172, v179 offset:11264
	v_add_u32_e32 v170, 0x1080, v170
	v_add_u32_e32 v237, 0x1080, v237
	v_add_u32_e32 v95, 0x1080, v95
	s_waitcnt lgkmcnt(1)
	v_mfma_f32_16x16x4_f32 v[96:99], v22, v184, 0
	v_mfma_f32_16x16x4_f32 v[100:103], v23, v185, 0
	v_mfma_f32_16x16x4_f32 v[96:99], v24, v186, v[96:99]
	v_mfma_f32_16x16x4_f32 v[100:103], v25, v187, v[100:103]
	v_mul_f32_e32 v129, v132, v70
	v_mul_f32_e32 v130, v133, v71
	v_mul_f32_e32 v131, v134, v72
	v_mul_f32_e32 v153, v135, v73
	v_mfma_f32_16x16x4_f32 v[96:99], v26, v188, v[96:99]
	v_mfma_f32_16x16x4_f32 v[100:103], v27, v189, v[100:103]
	v_mfma_f32_16x16x4_f32 v[96:99], v28, v190, v[96:99]
	v_mfma_f32_16x16x4_f32 v[100:103], v29, v191, v[100:103]
	v_mul_f32_e64 v114, -v132, v136
	v_mul_f32_e64 v115, -v133, v137
	v_mul_f32_e64 v116, -v134, v138
	v_mul_f32_e64 v117, -v135, v139
	v_mfma_f32_16x16x4_f32 v[96:99], v30, v192, v[96:99]
	v_mfma_f32_16x16x4_f32 v[100:103], v31, v193, v[100:103]
	v_mfma_f32_16x16x4_f32 v[96:99], v32, v194, v[96:99]
	v_mfma_f32_16x16x4_f32 v[100:103], v33, v195, v[100:103]
	v_mul_f32_e32 v240, v238, v139
	v_rcp_f32_e32 v89, v240
	v_readfirstlane_b32 s0, v240
	ds_read_b32 v86, v87 offset:768
	v_mfma_f32_16x16x4_f32 v[96:99], v34, v196, v[96:99]
	v_mfma_f32_16x16x4_f32 v[100:103], v35, v197, v[100:103]
	v_mfma_f32_16x16x4_f32 v[96:99], v36, v198, v[96:99]
	v_mfma_f32_16x16x4_f32 v[100:103], v37, v199, v[100:103]
	ds_read2_b32 v[62:63], v237 offset0:0 offset1:16
	ds_read2_b32 v[64:65], v237 offset0:32 offset1:48
	ds_read2_b32 v[66:67], v237 offset0:64 offset1:80
	ds_read2_b32 v[68:69], v237 offset0:96 offset1:112
	v_mfma_f32_16x16x4_f32 v[96:99], v38, v200, v[96:99]
	v_mfma_f32_16x16x4_f32 v[100:103], v39, v201, v[100:103]
	v_mfma_f32_16x16x4_f32 v[96:99], v40, v202, v[96:99]
	v_mfma_f32_16x16x4_f32 v[100:103], v41, v203, v[100:103]
	ds_read2st64_b32 v[74:75], v171 offset0:52 offset1:53
	ds_read2st64_b32 v[76:77], v171 offset0:54 offset1:55
	ds_read_b128 v[216:219], v175 offset:208
	ds_read_b128 v[220:223], v175 offset:464
	v_mfma_f32_16x16x4_f32 v[96:99], v42, v204, v[96:99]
	v_mfma_f32_16x16x4_f32 v[100:103], v43, v205, v[100:103]
	v_mfma_f32_16x16x4_f32 v[96:99], v44, v206, v[96:99]
	v_mfma_f32_16x16x4_f32 v[100:103], v45, v207, v[100:103]
	ds_read_b32 v235, v176 offset:464
	ds_read_b32 v236, v176 offset:720
	ds_read_b32 v234, v173 offset:3248
	ds_read_b64 v[232:233], v173 offset:3280
	v_mfma_f32_16x16x4_f32 v[96:99], v46, v208, v[96:99]
	v_mfma_f32_16x16x4_f32 v[100:103], v47, v209, v[100:103]
	v_mfma_f32_16x16x4_f32 v[96:99], v48, v210, v[96:99]
	v_mfma_f32_16x16x4_f32 v[100:103], v49, v211, v[100:103]
	ds_read_b128 v[224:227], v173 offset:3312
	ds_read_b128 v[228:231], v174 offset:3216
	v_mfma_f32_16x16x4_f32 v[96:99], v50, v212, v[96:99]
	v_mfma_f32_16x16x4_f32 v[100:103], v51, v213, v[100:103]
	v_mfma_f32_16x16x4_f32 v[96:99], v52, v214, v[96:99]
	v_mfma_f32_16x16x4_f32 v[100:103], v53, v215, v[100:103]
	s_nop 7
	s_nop 1
	v_pk_mul_f32 v[100:101], v[100:101], v[238:239] op_sel_hi:[1,0]
	v_pk_mul_f32 v[102:103], v[102:103], v[238:239] op_sel_hi:[1,0]
	v_pk_fma_f32 v[78:79], v[96:97], v[238:239], v[100:101] op_sel_hi:[1,0,1]
	v_pk_fma_f32 v[80:81], v[98:99], v[238:239], v[102:103] op_sel_hi:[1,0,1]
	v_pk_fma_f32 v[96:97], v[96:97], v[238:239], v[100:101] op_sel_hi:[1,0,1]
	v_pk_fma_f32 v[98:99], v[98:99], v[238:239], v[102:103] op_sel_hi:[1,0,1]
	s_nop 0
	v_permlane32_swap_b32_e32 v96, v78
	v_permlane32_swap_b32_e32 v97, v79
	v_permlane32_swap_b32_e32 v98, v80
	v_permlane32_swap_b32_e32 v99, v81
	v_mov_b32_e32 v82, v96
	v_mov_b32_e32 v83, v97
	v_mov_b32_e32 v84, v98
	v_mov_b32_e32 v85, v99
	s_nop 0
	v_permlane16_swap_b32_e32 v96, v82
	v_permlane16_swap_b32_e32 v97, v83
	v_permlane16_swap_b32_e32 v98, v84
	v_permlane16_swap_b32_e32 v99, v85
	v_fma_f32 v108, v114, v96, v129
	v_fma_f32 v109, v115, v97, v130
	v_fma_f32 v110, v116, v98, v131
	v_fma_f32 v111, v117, v99, v153
	v_fma_f32 v109, -v150, v108, v109
	v_fma_f32 v110, -v148, v108, v110
	v_fma_f32 v111, -v140, v108, v111
	v_fma_f32 v110, -v149, v109, v110
	v_fma_f32 v111, -v141, v109, v111
	v_fma_f32 v111, -v142, v110, v111
	v_cndmask_b32_e32 v182, v108, v109, vcc
	v_cndmask_b32_e64 v182, v182, v110, s[4:5]
	v_cndmask_b32_e64 v182, v182, v111, s[6:7]
	v_mul_f32_e32 v182, v152, v182
	s_cmp_lt_u32 s0, 0x2b800000
	s_cbranch_scc0 .Lgdn_nomat_6_0
	v_pk_mul_f32 v[184:185], v[184:185], v[240:241] op_sel_hi:[1,0]
	v_pk_mul_f32 v[186:187], v[186:187], v[240:241] op_sel_hi:[1,0]
	v_pk_mul_f32 v[188:189], v[188:189], v[240:241] op_sel_hi:[1,0]
	v_pk_mul_f32 v[190:191], v[190:191], v[240:241] op_sel_hi:[1,0]
	v_pk_mul_f32 v[192:193], v[192:193], v[240:241] op_sel_hi:[1,0]
	v_pk_mul_f32 v[194:195], v[194:195], v[240:241] op_sel_hi:[1,0]
	v_pk_mul_f32 v[196:197], v[196:197], v[240:241] op_sel_hi:[1,0]
	v_pk_mul_f32 v[198:199], v[198:199], v[240:241] op_sel_hi:[1,0]
	v_pk_mul_f32 v[200:201], v[200:201], v[240:241] op_sel_hi:[1,0]
	v_pk_mul_f32 v[202:203], v[202:203], v[240:241] op_sel_hi:[1,0]
	v_pk_mul_f32 v[204:205], v[204:205], v[240:241] op_sel_hi:[1,0]
	v_pk_mul_f32 v[206:207], v[206:207], v[240:241] op_sel_hi:[1,0]
	v_pk_mul_f32 v[208:209], v[208:209], v[240:241] op_sel_hi:[1,0]
	v_pk_mul_f32 v[210:211], v[210:211], v[240:241] op_sel_hi:[1,0]
	v_pk_mul_f32 v[212:213], v[212:213], v[240:241] op_sel_hi:[1,0]
	v_pk_mul_f32 v[214:215], v[214:215], v[240:241] op_sel_hi:[1,0]
	v_mov_b32_e32 v240, 1.0
	v_mov_b32_e32 v89, 1.0
.Lgdn_nomat_6_0:
	v_mov_b32_e32 v238, v240
	v_mul_f32_e32 v90, v182, v89
	s_nop 1
	v_mfma_f32_16x16x4_f32 v[184:187], v54, v90, v[184:187]
	v_mfma_f32_16x16x4_f32 v[188:191], v55, v90, v[188:191]
	v_mfma_f32_16x16x4_f32 v[192:195], v56, v90, v[192:195]
	v_mfma_f32_16x16x4_f32 v[196:199], v57, v90, v[196:199]
	v_mfma_f32_16x16x4_f32 v[200:203], v58, v90, v[200:203]
	v_mfma_f32_16x16x4_f32 v[204:207], v59, v90, v[204:207]
	v_mfma_f32_16x16x4_f32 v[208:211], v60, v90, v[208:211]
	v_mfma_f32_16x16x4_f32 v[212:215], v61, v90, v[212:215]
	v_pk_mul_f32 v[78:79], v[78:79], v[138:139] op_sel:[0,1] op_sel_hi:[1,1]
	v_pk_mul_f32 v[80:81], v[80:81], v[138:139] op_sel:[0,1] op_sel_hi:[1,1]
	v_cndmask_b32_e32 v183, v82, v83, vcc
	v_cndmask_b32_e64 v183, v183, v84, s[4:5]
	v_cndmask_b32_e64 v183, v183, v85, s[6:7]
	v_mul_f32_e32 v179, v151, v183
	v_fmac_f32_e32 v179, v144, v108
	v_fmac_f32_e32 v179, v145, v109
	v_fmac_f32_e32 v179, v146, v110
	v_fmac_f32_e32 v179, v147, v111
	ds_write_b32 v172, v179 offset:12288
	s_waitcnt lgkmcnt(1)
	v_mfma_f32_16x16x4_f32 v[96:99], v86, v182, v[78:81]
	s_nop 7
	v_mul_f32_e32 v129, v216, v74
	v_mul_f32_e32 v130, v217, v75
	v_mul_f32_e32 v131, v218, v76
	v_mul_f32_e32 v153, v219, v77
	v_mul_f32_e64 v114, -v216, v220
	v_mul_f32_e64 v115, -v217, v221
	v_mul_f32_e64 v116, -v218, v222
	v_mul_f32_e64 v117, -v219, v223
	v_mul_f32_e32 v240, v238, v223
	v_rcp_f32_e32 v89, v240
	v_readfirstlane_b32 s0, v240
	ds_read_b128 v[22:25], v169 offset:29568
	ds_read_b128 v[26:29], v169 offset:29632
	ds_read_b128 v[30:33], v169 offset:29696
	ds_read_b128 v[34:37], v169 offset:29760
	ds_read_b128 v[38:41], v169 offset:29824
	ds_read_b128 v[42:45], v169 offset:29888
	ds_read_b128 v[46:49], v169 offset:29952
	ds_read_b128 v[50:53], v169 offset:30016
	ds_read2_b32 v[54:55], v95 offset0:0 offset1:16
	ds_read2_b32 v[56:57], v95 offset0:32 offset1:48
	ds_read2_b32 v[58:59], v95 offset0:64 offset1:80
	ds_read2_b32 v[60:61], v95 offset0:96 offset1:112
	ds_read2st64_b32 v[70:71], v171 offset0:56 offset1:57
	ds_read2st64_b32 v[72:73], v171 offset0:58 offset1:59
	ds_read_b128 v[132:135], v175 offset:224
	ds_read_b128 v[136:139], v175 offset:480
	ds_read_b32 v151, v176 offset:480
	ds_read_b32 v152, v176 offset:736
	ds_read_b32 v150, v173 offset:3616
	ds_read_b64 v[148:149], v173 offset:3648
	ds_read_b128 v[140:143], v173 offset:3680
	ds_read_b128 v[144:147], v174 offset:3584
	v_mov_b32_e32 v82, v96
	v_mov_b32_e32 v83, v97
	v_mov_b32_e32 v84, v98
	v_mov_b32_e32 v85, v99
	s_nop 0
	v_permlane16_swap_b32_e32 v96, v82
	v_permlane16_swap_b32_e32 v97, v83
	v_permlane16_swap_b32_e32 v98, v84
	v_permlane16_swap_b32_e32 v99, v85
	v_fma_f32 v108, v114, v96, v129
	v_fma_f32 v109, v115, v97, v130
	v_fma_f32 v110, v116, v98, v131
	v_fma_f32 v111, v117, v99, v153
	v_fma_f32 v109, -v234, v108, v109
	v_fma_f32 v110, -v232, v108, v110
	v_fma_f32 v111, -v224, v108, v111
	v_fma_f32 v110, -v233, v109, v110
	v_fma_f32 v111, -v225, v109, v111
	v_fma_f32 v111, -v226, v110, v111
	v_cndmask_b32_e32 v182, v108, v109, vcc
	v_cndmask_b32_e64 v182, v182, v110, s[4:5]
	v_cndmask_b32_e64 v182, v182, v111, s[6:7]
	v_mul_f32_e32 v182, v236, v182
	s_cmp_lt_u32 s0, 0x2b800000
	s_cbranch_scc0 .Lgdn_nomat_6_1
	v_pk_mul_f32 v[184:185], v[184:185], v[240:241] op_sel_hi:[1,0]
	v_pk_mul_f32 v[186:187], v[186:187], v[240:241] op_sel_hi:[1,0]
	v_pk_mul_f32 v[188:189], v[188:189], v[240:241] op_sel_hi:[1,0]
	v_pk_mul_f32 v[190:191], v[190:191], v[240:241] op_sel_hi:[1,0]
	v_pk_mul_f32 v[192:193], v[192:193], v[240:241] op_sel_hi:[1,0]
	v_pk_mul_f32 v[194:195], v[194:195], v[240:241] op_sel_hi:[1,0]
	v_pk_mul_f32 v[196:197], v[196:197], v[240:241] op_sel_hi:[1,0]
	v_pk_mul_f32 v[198:199], v[198:199], v[240:241] op_sel_hi:[1,0]
	v_pk_mul_f32 v[200:201], v[200:201], v[240:241] op_sel_hi:[1,0]
	v_pk_mul_f32 v[202:203], v[202:203], v[240:241] op_sel_hi:[1,0]
	v_pk_mul_f32 v[204:205], v[204:205], v[240:241] op_sel_hi:[1,0]
	v_pk_mul_f32 v[206:207], v[206:207], v[240:241] op_sel_hi:[1,0]
	v_pk_mul_f32 v[208:209], v[208:209], v[240:241] op_sel_hi:[1,0]
	v_pk_mul_f32 v[210:211], v[210:211], v[240:241] op_sel_hi:[1,0]
	v_pk_mul_f32 v[212:213], v[212:213], v[240:241] op_sel_hi:[1,0]
	v_pk_mul_f32 v[214:215], v[214:215], v[240:241] op_sel_hi:[1,0]
	v_mov_b32_e32 v240, 1.0
	v_mov_b32_e32 v89, 1.0
.Lgdn_nomat_6_1:
	v_mov_b32_e32 v238, v240
	v_mul_f32_e32 v90, v182, v89
	s_nop 1
	v_mfma_f32_16x16x4_f32 v[184:187], v62, v90, v[184:187]
	v_mfma_f32_16x16x4_f32 v[188:191], v63, v90, v[188:191]
	v_mfma_f32_16x16x4_f32 v[192:195], v64, v90, v[192:195]
	v_mfma_f32_16x16x4_f32 v[196:199], v65, v90, v[196:199]
	v_mfma_f32_16x16x4_f32 v[200:203], v66, v90, v[200:203]
	v_mfma_f32_16x16x4_f32 v[204:207], v67, v90, v[204:207]
	v_mfma_f32_16x16x4_f32 v[208:211], v68, v90, v[208:211]
	v_mfma_f32_16x16x4_f32 v[212:215], v69, v90, v[212:215]
	v_cndmask_b32_e32 v183, v82, v83, vcc
	v_cndmask_b32_e64 v183, v183, v84, s[4:5]
	v_cndmask_b32_e64 v183, v183, v85, s[6:7]
	v_mul_f32_e32 v179, v235, v183
	v_fmac_f32_e32 v179, v228, v108
	v_fmac_f32_e32 v179, v229, v109
	v_fmac_f32_e32 v179, v230, v110
	v_fmac_f32_e32 v179, v231, v111
	ds_write_b32 v172, v179 offset:13312
	v_add_u32_e32 v170, 0x1080, v170
	v_add_u32_e32 v237, 0x1080, v237
	v_add_u32_e32 v95, 0x1080, v95
	s_waitcnt lgkmcnt(1)
	v_mfma_f32_16x16x4_f32 v[96:99], v22, v184, 0
	v_mfma_f32_16x16x4_f32 v[100:103], v23, v185, 0
	v_mfma_f32_16x16x4_f32 v[96:99], v24, v186, v[96:99]
	v_mfma_f32_16x16x4_f32 v[100:103], v25, v187, v[100:103]
	v_mul_f32_e32 v129, v132, v70
	v_mul_f32_e32 v130, v133, v71
	v_mul_f32_e32 v131, v134, v72
	v_mul_f32_e32 v153, v135, v73
	v_mfma_f32_16x16x4_f32 v[96:99], v26, v188, v[96:99]
	v_mfma_f32_16x16x4_f32 v[100:103], v27, v189, v[100:103]
	v_mfma_f32_16x16x4_f32 v[96:99], v28, v190, v[96:99]
	v_mfma_f32_16x16x4_f32 v[100:103], v29, v191, v[100:103]
	v_mul_f32_e64 v114, -v132, v136
	v_mul_f32_e64 v115, -v133, v137
	v_mul_f32_e64 v116, -v134, v138
	v_mul_f32_e64 v117, -v135, v139
	v_mfma_f32_16x16x4_f32 v[96:99], v30, v192, v[96:99]
	v_mfma_f32_16x16x4_f32 v[100:103], v31, v193, v[100:103]
	v_mfma_f32_16x16x4_f32 v[96:99], v32, v194, v[96:99]
	v_mfma_f32_16x16x4_f32 v[100:103], v33, v195, v[100:103]
	v_mul_f32_e32 v240, v238, v139
	v_rcp_f32_e32 v89, v240
	v_readfirstlane_b32 s0, v240
	ds_read_b32 v86, v87 offset:896
	v_mfma_f32_16x16x4_f32 v[96:99], v34, v196, v[96:99]
	v_mfma_f32_16x16x4_f32 v[100:103], v35, v197, v[100:103]
	v_mfma_f32_16x16x4_f32 v[96:99], v36, v198, v[96:99]
	v_mfma_f32_16x16x4_f32 v[100:103], v37, v199, v[100:103]
	ds_read2_b32 v[62:63], v237 offset0:0 offset1:16
	ds_read2_b32 v[64:65], v237 offset0:32 offset1:48
	ds_read2_b32 v[66:67], v237 offset0:64 offset1:80
	ds_read2_b32 v[68:69], v237 offset0:96 offset1:112
	v_mfma_f32_16x16x4_f32 v[96:99], v38, v200, v[96:99]
	v_mfma_f32_16x16x4_f32 v[100:103], v39, v201, v[100:103]
	v_mfma_f32_16x16x4_f32 v[96:99], v40, v202, v[96:99]
	v_mfma_f32_16x16x4_f32 v[100:103], v41, v203, v[100:103]
	ds_read2st64_b32 v[74:75], v171 offset0:60 offset1:61
	ds_read2st64_b32 v[76:77], v171 offset0:62 offset1:63
	ds_read_b128 v[216:219], v175 offset:240
	ds_read_b128 v[220:223], v175 offset:496
	v_mfma_f32_16x16x4_f32 v[96:99], v42, v204, v[96:99]
	v_mfma_f32_16x16x4_f32 v[100:103], v43, v205, v[100:103]
	v_mfma_f32_16x16x4_f32 v[96:99], v44, v206, v[96:99]
	v_mfma_f32_16x16x4_f32 v[100:103], v45, v207, v[100:103]
	ds_read_b32 v235, v176 offset:496
	ds_read_b32 v236, v176 offset:752
	ds_read_b32 v234, v173 offset:3760
	ds_read_b64 v[232:233], v173 offset:3792
	v_mfma_f32_16x16x4_f32 v[96:99], v46, v208, v[96:99]
	v_mfma_f32_16x16x4_f32 v[100:103], v47, v209, v[100:103]
	v_mfma_f32_16x16x4_f32 v[96:99], v48, v210, v[96:99]
	v_mfma_f32_16x16x4_f32 v[100:103], v49, v211, v[100:103]
	ds_read_b128 v[224:227], v173 offset:3824
	ds_read_b128 v[228:231], v174 offset:3728
	v_mfma_f32_16x16x4_f32 v[96:99], v50, v212, v[96:99]
	v_mfma_f32_16x16x4_f32 v[100:103], v51, v213, v[100:103]
	v_mfma_f32_16x16x4_f32 v[96:99], v52, v214, v[96:99]
	v_mfma_f32_16x16x4_f32 v[100:103], v53, v215, v[100:103]
	s_nop 7
	s_nop 1
	v_pk_mul_f32 v[100:101], v[100:101], v[238:239] op_sel_hi:[1,0]
	v_pk_mul_f32 v[102:103], v[102:103], v[238:239] op_sel_hi:[1,0]
	v_pk_fma_f32 v[78:79], v[96:97], v[238:239], v[100:101] op_sel_hi:[1,0,1]
	v_pk_fma_f32 v[80:81], v[98:99], v[238:239], v[102:103] op_sel_hi:[1,0,1]
	v_pk_fma_f32 v[96:97], v[96:97], v[238:239], v[100:101] op_sel_hi:[1,0,1]
	v_pk_fma_f32 v[98:99], v[98:99], v[238:239], v[102:103] op_sel_hi:[1,0,1]
	s_nop 0
	v_permlane32_swap_b32_e32 v96, v78
	v_permlane32_swap_b32_e32 v97, v79
	v_permlane32_swap_b32_e32 v98, v80
	v_permlane32_swap_b32_e32 v99, v81
	v_mov_b32_e32 v82, v96
	v_mov_b32_e32 v83, v97
	v_mov_b32_e32 v84, v98
	v_mov_b32_e32 v85, v99
	s_nop 0
	v_permlane16_swap_b32_e32 v96, v82
	v_permlane16_swap_b32_e32 v97, v83
	v_permlane16_swap_b32_e32 v98, v84
	v_permlane16_swap_b32_e32 v99, v85
	v_fma_f32 v108, v114, v96, v129
	v_fma_f32 v109, v115, v97, v130
	v_fma_f32 v110, v116, v98, v131
	v_fma_f32 v111, v117, v99, v153
	v_fma_f32 v109, -v150, v108, v109
	v_fma_f32 v110, -v148, v108, v110
	v_fma_f32 v111, -v140, v108, v111
	v_fma_f32 v110, -v149, v109, v110
	v_fma_f32 v111, -v141, v109, v111
	v_fma_f32 v111, -v142, v110, v111
	v_cndmask_b32_e32 v182, v108, v109, vcc
	v_cndmask_b32_e64 v182, v182, v110, s[4:5]
	v_cndmask_b32_e64 v182, v182, v111, s[6:7]
	v_mul_f32_e32 v182, v152, v182
	s_cmp_lt_u32 s0, 0x2b800000
	s_cbranch_scc0 .Lgdn_nomat_7_0
	v_pk_mul_f32 v[184:185], v[184:185], v[240:241] op_sel_hi:[1,0]
	v_pk_mul_f32 v[186:187], v[186:187], v[240:241] op_sel_hi:[1,0]
	v_pk_mul_f32 v[188:189], v[188:189], v[240:241] op_sel_hi:[1,0]
	v_pk_mul_f32 v[190:191], v[190:191], v[240:241] op_sel_hi:[1,0]
	v_pk_mul_f32 v[192:193], v[192:193], v[240:241] op_sel_hi:[1,0]
	v_pk_mul_f32 v[194:195], v[194:195], v[240:241] op_sel_hi:[1,0]
	v_pk_mul_f32 v[196:197], v[196:197], v[240:241] op_sel_hi:[1,0]
	v_pk_mul_f32 v[198:199], v[198:199], v[240:241] op_sel_hi:[1,0]
	v_pk_mul_f32 v[200:201], v[200:201], v[240:241] op_sel_hi:[1,0]
	v_pk_mul_f32 v[202:203], v[202:203], v[240:241] op_sel_hi:[1,0]
	v_pk_mul_f32 v[204:205], v[204:205], v[240:241] op_sel_hi:[1,0]
	v_pk_mul_f32 v[206:207], v[206:207], v[240:241] op_sel_hi:[1,0]
	v_pk_mul_f32 v[208:209], v[208:209], v[240:241] op_sel_hi:[1,0]
	v_pk_mul_f32 v[210:211], v[210:211], v[240:241] op_sel_hi:[1,0]
	v_pk_mul_f32 v[212:213], v[212:213], v[240:241] op_sel_hi:[1,0]
	v_pk_mul_f32 v[214:215], v[214:215], v[240:241] op_sel_hi:[1,0]
	v_mov_b32_e32 v240, 1.0
	v_mov_b32_e32 v89, 1.0
.Lgdn_nomat_7_0:
	v_mov_b32_e32 v238, v240
	v_mul_f32_e32 v90, v182, v89
	s_nop 1
	v_mfma_f32_16x16x4_f32 v[184:187], v54, v90, v[184:187]
	v_mfma_f32_16x16x4_f32 v[188:191], v55, v90, v[188:191]
	v_mfma_f32_16x16x4_f32 v[192:195], v56, v90, v[192:195]
	v_mfma_f32_16x16x4_f32 v[196:199], v57, v90, v[196:199]
	v_mfma_f32_16x16x4_f32 v[200:203], v58, v90, v[200:203]
	v_mfma_f32_16x16x4_f32 v[204:207], v59, v90, v[204:207]
	v_mfma_f32_16x16x4_f32 v[208:211], v60, v90, v[208:211]
	v_mfma_f32_16x16x4_f32 v[212:215], v61, v90, v[212:215]
	v_pk_mul_f32 v[78:79], v[78:79], v[138:139] op_sel:[0,1] op_sel_hi:[1,1]
	v_pk_mul_f32 v[80:81], v[80:81], v[138:139] op_sel:[0,1] op_sel_hi:[1,1]
	v_cndmask_b32_e32 v183, v82, v83, vcc
	v_cndmask_b32_e64 v183, v183, v84, s[4:5]
	v_cndmask_b32_e64 v183, v183, v85, s[6:7]
	v_mul_f32_e32 v179, v151, v183
	v_fmac_f32_e32 v179, v144, v108
	v_fmac_f32_e32 v179, v145, v109
	v_fmac_f32_e32 v179, v146, v110
	v_fmac_f32_e32 v179, v147, v111
	ds_write_b32 v172, v179 offset:14336
	s_waitcnt lgkmcnt(1)
	v_mfma_f32_16x16x4_f32 v[96:99], v86, v182, v[78:81]
	s_nop 7
	v_mul_f32_e32 v129, v216, v74
	v_mul_f32_e32 v130, v217, v75
	v_mul_f32_e32 v131, v218, v76
	v_mul_f32_e32 v153, v219, v77
	v_mul_f32_e64 v114, -v216, v220
	v_mul_f32_e64 v115, -v217, v221
	v_mul_f32_e64 v116, -v218, v222
	v_mul_f32_e64 v117, -v219, v223
	v_mul_f32_e32 v240, v238, v223
	v_rcp_f32_e32 v89, v240
	v_readfirstlane_b32 s0, v240
	ds_read_b128 v[22:25], v169 offset:33792
	ds_read_b128 v[26:29], v169 offset:33856
	ds_read_b128 v[30:33], v169 offset:33920
	ds_read_b128 v[34:37], v169 offset:33984
	ds_read_b128 v[38:41], v169 offset:34048
	ds_read_b128 v[42:45], v169 offset:34112
	ds_read_b128 v[46:49], v169 offset:34176
	ds_read_b128 v[50:53], v169 offset:34240
	ds_read2_b32 v[54:55], v95 offset0:0 offset1:16
	ds_read2_b32 v[56:57], v95 offset0:32 offset1:48
	ds_read2_b32 v[58:59], v95 offset0:64 offset1:80
	ds_read2_b32 v[60:61], v95 offset0:96 offset1:112
	ds_read2st64_b32 v[70:71], v171 offset0:64 offset1:65
	ds_read2st64_b32 v[72:73], v171 offset0:66 offset1:67
	ds_read_b128 v[132:135], v175 offset:256
	ds_read_b128 v[136:139], v175 offset:512
	ds_read_b32 v151, v176 offset:512
	ds_read_b32 v152, v176 offset:768
	ds_read_b32 v150, v173 offset:4128
	ds_read_b64 v[148:149], v173 offset:4160
	ds_read_b128 v[140:143], v173 offset:4192
	ds_read_b128 v[144:147], v174 offset:4096
	v_mov_b32_e32 v82, v96
	v_mov_b32_e32 v83, v97
	v_mov_b32_e32 v84, v98
	v_mov_b32_e32 v85, v99
	s_nop 0
	v_permlane16_swap_b32_e32 v96, v82
	v_permlane16_swap_b32_e32 v97, v83
	v_permlane16_swap_b32_e32 v98, v84
	v_permlane16_swap_b32_e32 v99, v85
	v_fma_f32 v108, v114, v96, v129
	v_fma_f32 v109, v115, v97, v130
	v_fma_f32 v110, v116, v98, v131
	v_fma_f32 v111, v117, v99, v153
	v_fma_f32 v109, -v234, v108, v109
	v_fma_f32 v110, -v232, v108, v110
	v_fma_f32 v111, -v224, v108, v111
	v_fma_f32 v110, -v233, v109, v110
	v_fma_f32 v111, -v225, v109, v111
	v_fma_f32 v111, -v226, v110, v111
	v_cndmask_b32_e32 v182, v108, v109, vcc
	v_cndmask_b32_e64 v182, v182, v110, s[4:5]
	v_cndmask_b32_e64 v182, v182, v111, s[6:7]
	v_mul_f32_e32 v182, v236, v182
	s_cmp_lt_u32 s0, 0x2b800000
	s_cbranch_scc0 .Lgdn_nomat_7_1
	v_pk_mul_f32 v[184:185], v[184:185], v[240:241] op_sel_hi:[1,0]
	v_pk_mul_f32 v[186:187], v[186:187], v[240:241] op_sel_hi:[1,0]
	v_pk_mul_f32 v[188:189], v[188:189], v[240:241] op_sel_hi:[1,0]
	v_pk_mul_f32 v[190:191], v[190:191], v[240:241] op_sel_hi:[1,0]
	v_pk_mul_f32 v[192:193], v[192:193], v[240:241] op_sel_hi:[1,0]
	v_pk_mul_f32 v[194:195], v[194:195], v[240:241] op_sel_hi:[1,0]
	v_pk_mul_f32 v[196:197], v[196:197], v[240:241] op_sel_hi:[1,0]
	v_pk_mul_f32 v[198:199], v[198:199], v[240:241] op_sel_hi:[1,0]
	v_pk_mul_f32 v[200:201], v[200:201], v[240:241] op_sel_hi:[1,0]
	v_pk_mul_f32 v[202:203], v[202:203], v[240:241] op_sel_hi:[1,0]
	v_pk_mul_f32 v[204:205], v[204:205], v[240:241] op_sel_hi:[1,0]
	v_pk_mul_f32 v[206:207], v[206:207], v[240:241] op_sel_hi:[1,0]
	v_pk_mul_f32 v[208:209], v[208:209], v[240:241] op_sel_hi:[1,0]
	v_pk_mul_f32 v[210:211], v[210:211], v[240:241] op_sel_hi:[1,0]
	v_pk_mul_f32 v[212:213], v[212:213], v[240:241] op_sel_hi:[1,0]
	v_pk_mul_f32 v[214:215], v[214:215], v[240:241] op_sel_hi:[1,0]
	v_mov_b32_e32 v240, 1.0
	v_mov_b32_e32 v89, 1.0
.Lgdn_nomat_7_1:
	v_mov_b32_e32 v238, v240
	v_mul_f32_e32 v90, v182, v89
	s_nop 1
	v_mfma_f32_16x16x4_f32 v[184:187], v62, v90, v[184:187]
	v_mfma_f32_16x16x4_f32 v[188:191], v63, v90, v[188:191]
	v_mfma_f32_16x16x4_f32 v[192:195], v64, v90, v[192:195]
	v_mfma_f32_16x16x4_f32 v[196:199], v65, v90, v[196:199]
	v_mfma_f32_16x16x4_f32 v[200:203], v66, v90, v[200:203]
	v_mfma_f32_16x16x4_f32 v[204:207], v67, v90, v[204:207]
	v_mfma_f32_16x16x4_f32 v[208:211], v68, v90, v[208:211]
	v_mfma_f32_16x16x4_f32 v[212:215], v69, v90, v[212:215]
	v_cndmask_b32_e32 v183, v82, v83, vcc
	v_cndmask_b32_e64 v183, v183, v84, s[4:5]
	v_cndmask_b32_e64 v183, v183, v85, s[6:7]
	v_mul_f32_e32 v179, v235, v183
	v_fmac_f32_e32 v179, v228, v108
	v_fmac_f32_e32 v179, v229, v109
	v_fmac_f32_e32 v179, v230, v110
	v_fmac_f32_e32 v179, v231, v111
	ds_write_b32 v172, v179 offset:15360

.LBB0_581:
	ds_read_b128 v[14:17], v30
	ds_read_b128 v[10:13], v30 offset:16
	ds_read_b128 v[6:9], v30 offset:32
	ds_read_b128 v[2:5], v30 offset:48
	ds_read_b128 v[80:83], v31
	ds_read_b128 v[84:87], v31 offset:16
	ds_read_b128 v[88:91], v31 offset:32
	ds_read_b128 v[96:99], v31 offset:48
	ds_read_b128 v[100:103], v31 offset:17408
	ds_read_b128 v[124:127], v31 offset:17424
	ds_read_b128 v[22:25], v31 offset:17440
	ds_read_b128 v[18:21], v31 offset:17456
	s_waitcnt lgkmcnt(7)
	v_mov_b32_e32 v92, v80
	s_waitcnt lgkmcnt(3)
	v_mov_b32_e32 v93, v100
	v_mov_b32_e32 v100, v81
	v_pk_fma_f32 v[32:33], v[14:15], v[92:93], v[32:33] op_sel_hi:[0,1,1]
	v_mov_b32_e32 v80, v82
	v_mov_b32_e32 v81, v102
	v_pk_fma_f32 v[14:15], v[14:15], v[100:101], v[32:33] op_sel:[1,0,0]
	v_mov_b32_e32 v82, v17
	v_mov_b32_e32 v102, v83
	v_pk_fma_f32 v[14:15], v[16:17], v[80:81], v[14:15] op_sel_hi:[0,1,1]
	v_mov_b32_e32 v104, v84
	s_waitcnt lgkmcnt(2)
	v_mov_b32_e32 v105, v124
	v_pk_fma_f32 v[14:15], v[82:83], v[102:103], v[14:15] op_sel_hi:[0,1,1]
	v_mov_b32_e32 v124, v85
	v_pk_fma_f32 v[14:15], v[10:11], v[104:105], v[14:15] op_sel_hi:[0,1,1]
	v_mov_b32_e32 v84, v86
	v_mov_b32_e32 v85, v126
	v_pk_fma_f32 v[10:11], v[10:11], v[124:125], v[14:15] op_sel:[1,0,0]
	v_mov_b32_e32 v86, v13
	v_mov_b32_e32 v126, v87
	v_pk_fma_f32 v[10:11], v[12:13], v[84:85], v[10:11] op_sel_hi:[0,1,1]
	v_mov_b32_e32 v116, v88
	s_waitcnt lgkmcnt(1)
	v_mov_b32_e32 v117, v22
	v_pk_fma_f32 v[10:11], v[86:87], v[126:127], v[10:11] op_sel_hi:[0,1,1]
	v_mov_b32_e32 v22, v89
	v_pk_fma_f32 v[10:11], v[6:7], v[116:117], v[10:11] op_sel_hi:[0,1,1]
	v_mov_b32_e32 v88, v90
	v_mov_b32_e32 v89, v24
	v_pk_fma_f32 v[6:7], v[6:7], v[22:23], v[10:11] op_sel:[1,0,0]
	v_mov_b32_e32 v90, v9
	v_mov_b32_e32 v24, v91
	v_pk_fma_f32 v[6:7], v[8:9], v[88:89], v[6:7] op_sel_hi:[0,1,1]
	v_mov_b32_e32 v128, v96
	s_waitcnt lgkmcnt(0)
	v_mov_b32_e32 v129, v18
	v_pk_fma_f32 v[6:7], v[90:91], v[24:25], v[6:7] op_sel_hi:[0,1,1]
	v_mov_b32_e32 v18, v97
	v_pk_fma_f32 v[6:7], v[2:3], v[128:129], v[6:7] op_sel_hi:[0,1,1]
	v_mov_b32_e32 v96, v98
	v_mov_b32_e32 v97, v20
	v_pk_fma_f32 v[2:3], v[2:3], v[18:19], v[6:7] op_sel:[1,0,0]
	s_add_i32 s0, s0, 16
	v_mov_b32_e32 v98, v5
	v_mov_b32_e32 v20, v99
	v_pk_fma_f32 v[2:3], v[4:5], v[96:97], v[2:3] op_sel_hi:[0,1,1]
	v_add_u32_e32 v31, 64, v31
	v_add_u32_e32 v30, 64, v30
	s_cmp_gt_u32 s0, 47
	v_pk_fma_f32 v[32:33], v[98:99], v[20:21], v[2:3] op_sel_hi:[0,1,1]
	s_cbranch_scc0 .LBB0_581
	v_lshlrev_b32_e32 v2, 2, v78
	v_cndmask_b32_e64 v3, 0, 2, vcc
	v_or_b32_e32 v3, v3, v2
	v_lshl_add_u32 v3, v3, 8, s90
	v_lshlrev_b32_e32 v4, 5, v27
	v_lshlrev_b32_e32 v5, 2, v79
	v_add3_u32 v3, v3, v4, v5
	ds_write_b32 v3, v32
	v_cndmask_b32_e64 v3, 1, 3, vcc
	v_or_b32_e32 v2, v3, v2
	s_lshl_b32 s17, s40, 6
	v_lshl_add_u32 v2, v2, 8, s90
	v_add3_u32 v2, v2, v4, v5
	s_cmp_lg_u32 s40, 31
	ds_write_b32 v2, v33
	s_waitcnt lgkmcnt(0)
	s_barrier
	s_cbranch_scc0 .LBB0_586
	s_add_i32 s3, s17, 64
	s_add_u32 s0, s80, s3
	s_addc_u32 s1, s81, 0
	v_ashrrev_i32_e32 v27, 31, v26
	v_lshl_add_u64 v[4:5], s[0:1], 0, v[26:27]
	v_mad_u64_u32 v[2:3], s[0:1], v4, s83, 0
	v_mad_i32_i24 v3, v5, s83, v3
	v_add_u32_e32 v1, s3, v26
	v_mov_b32_e32 v95, v94
	v_lshl_add_u64 v[2:3], s[46:47], 0, v[2:3]
	v_cmp_lt_i32_e32 vcc, 0, v1
	v_mov_b32_e32 v106, 0
	v_lshl_add_u64 v[2:3], v[28:29], 1, v[2:3]
	v_mov_b64_e32 v[34:35], v[94:95]
	s_and_saveexec_b64 s[0:1], vcc
	s_cbranch_execz .LBB0_585
	global_load_ushort v52, v[2:3], off offset:-3072
	global_load_ushort v53, v[2:3], off offset:-2048
	global_load_ushort v54, v[2:3], off offset:-1024

.LBB0_586:
.Lrw_entry:
	v_readfirstlane_b32 s0, v180
	s_nop 1
	s_cmpk_ge_u32 s0, 0x100
	s_cbranch_scc1 .Lrw_done
	v_and_b32_e32 v222, 15, v180
	v_bfe_u32 v223, v180, 4, 2
	v_lshrrev_b32_e32 v240, 6, v180
	v_and_b32_e32 v176, 7, v222
	v_mul_u32_u24_e32 v176, 0x110, v176
	v_and_b32_e32 v177, 8, v222
	v_mul_u32_u24_e32 v177, 0x880, v177
	v_lshl_add_u32 v168, v223, 4, v176
	v_add_u32_e32 v168, v168, v177
	v_lshlrev_b32_e32 v178, 6, v240
	v_lshl_add_u32 v178, v222, 2, v178
	v_lshl_add_u32 v169, v223, 8, v178
	v_add_u32_e32 v169, s41, v169
	v_lshl_add_u32 v175, v223, 10, v178
	v_add_u32_e32 v175, 0x1f000, v175
	v_mov_b32_e32 v170, 0x15800
	v_lshlrev_b32_e32 v176, 5, v222
	v_lshl_add_u32 v176, v223, 2, v176
	v_and_b32_e32 v177, 8, v222
	v_lshl_add_u32 v172, v177, 5, v176
	v_add_u32_e32 v171, 0x15900, v172
	v_add_u32_e32 v172, 0x15800, v172
	v_mul_u32_u24_e32 v176, 0x110, v223
	v_lshl_add_u32 v173, v222, 2, v176
	v_add_u32_e32 v173, 0x8800, v173
	v_add_u32_e32 v2, 0x440, v173
	v_add_u32_e32 v3, 0x4400, v173
	v_add_u32_e32 v5, 0x4840, v173
	v_lshlrev_b32_e32 v174, 4, v223
	v_add_u32_e32 v174, 0x11000, v174
	v_cmp_eq_u32_e32 vcc, 1, v223
	v_cmp_eq_u32_e64 s[4:5], 2, v223
	v_cmp_eq_u32_e64 s[6:7], 3, v223
	s_mov_b32 s8, 0
	s_mov_b32 s9, -1
	v_mov_b32_e32 v198, 1.0
	v_mov_b32_e32 v199, 1.0
	v_mov_b32_e32 v200, 1.0
	v_mov_b32_e32 v201, 1.0
	v_mov_b32_e32 v202, 1.0
	v_mov_b32_e32 v203, 1.0
	v_mov_b32_e32 v204, 1.0
	v_mov_b32_e32 v205, 1.0
	v_mov_b32_e32 v206, 1.0
	v_mov_b32_e32 v207, 1.0
	v_mov_b32_e32 v208, 1.0
	v_mov_b32_e32 v209, 1.0
	v_mov_b32_e32 v210, 1.0
	v_mov_b32_e32 v211, 1.0
	v_mov_b32_e32 v212, 1.0
	v_mov_b32_e32 v213, 1.0
	ds_read_b128 v[44:47], v168 offset:0
	ds_read_b128 v[48:51], v168 offset:64
	ds_read_b128 v[68:71], v168 offset:128
	ds_read_b128 v[96:99], v168 offset:192
	ds_read_b32 v216, v171 offset:0
	ds_read_b32 v217, v171 offset:16
	ds_read_b32 v214, v169 offset:0
	ds_read_b32 v215, v169 offset:1024
	ds_read_b128 v[124:127], v170 offset:32
	ds_read_b128 v[128:131], v170 offset:64
	ds_read_b128 v[132:135], v170 offset:96
	ds_read_b128 v[136:139], v170 offset:128
	ds_read_b128 v[144:147], v170 offset:160
	ds_read_b128 v[148:151], v170 offset:176
	ds_read_b128 v[152:155], v170 offset:192
	ds_read_b128 v[156:159], v170 offset:208
	ds_read_b128 v[160:163], v170 offset:224
	ds_read_b128 v[164:167], v170 offset:240
	ds_read_b32 v218, v172 offset:0
	ds_read_b32 v219, v172 offset:16
	ds_read2_b32 v[182:183], v173 offset0:0 offset1:16
	ds_read2_b32 v[184:185], v173 offset0:32 offset1:48
	ds_read2_b32 v[186:187], v2 offset0:0 offset1:16
	ds_read2_b32 v[188:189], v2 offset0:32 offset1:48
	ds_read2_b32 v[190:191], v3 offset0:0 offset1:16
	ds_read2_b32 v[192:193], v3 offset0:32 offset1:48
	ds_read2_b32 v[194:195], v5 offset0:0 offset1:16
	ds_read2_b32 v[196:197], v5 offset0:32 offset1:48
	s_mov_b32 s1, 0
	s_waitcnt lgkmcnt(0)
	s_waitcnt lgkmcnt(4)
	v_pk_mul_f32 v[224:225], v[224:225], v[198:199]
	v_pk_mul_f32 v[226:227], v[226:227], v[200:201]
	v_pk_mul_f32 v[228:229], v[228:229], v[202:203]
	v_pk_mul_f32 v[230:231], v[230:231], v[204:205]
	v_mfma_f32_16x16x4_f32 v[36:39], v44, v224, 0
	v_mfma_f32_16x16x4_f32 v[40:43], v45, v225, 0
	v_mfma_f32_16x16x4_f32 v[36:39], v46, v226, v[36:39]
	v_mfma_f32_16x16x4_f32 v[40:43], v47, v227, v[40:43]
	v_pk_mul_f32 v[232:233], v[232:233], v[206:207]
	v_pk_mul_f32 v[234:235], v[234:235], v[208:209]
	v_mfma_f32_16x16x4_f32 v[36:39], v48, v228, v[36:39]
	v_mfma_f32_16x16x4_f32 v[40:43], v49, v229, v[40:43]
	v_mfma_f32_16x16x4_f32 v[36:39], v50, v230, v[36:39]
	v_mfma_f32_16x16x4_f32 v[40:43], v51, v231, v[40:43]
	v_pk_mul_f32 v[236:237], v[236:237], v[210:211]
	v_pk_mul_f32 v[238:239], v[238:239], v[212:213]
	v_mfma_f32_16x16x4_f32 v[36:39], v68, v232, v[36:39]
	v_mfma_f32_16x16x4_f32 v[40:43], v69, v233, v[40:43]
	v_mfma_f32_16x16x4_f32 v[36:39], v70, v234, v[36:39]
	v_mfma_f32_16x16x4_f32 v[40:43], v71, v235, v[40:43]
	v_mfma_f32_16x16x4_f32 v[36:39], v96, v236, v[36:39]
	v_mfma_f32_16x16x4_f32 v[40:43], v97, v237, v[40:43]
	v_mfma_f32_16x16x4_f32 v[36:39], v98, v238, v[36:39]
	v_mfma_f32_16x16x4_f32 v[40:43], v99, v239, v[40:43]
	v_mfma_f32_16x16x4_f32 v[36:39], v216, v214, v[36:39]
	v_mfma_f32_16x16x4_f32 v[40:43], v217, v215, v[40:43]
	ds_read_b128 v[44:47], v168 offset:2176
	ds_read_b128 v[48:51], v168 offset:2240
	ds_read_b128 v[68:71], v168 offset:2304
	ds_read_b128 v[96:99], v168 offset:2368
	ds_read_b32 v216, v171 offset:1024
	ds_read_b32 v217, v171 offset:1040
	ds_read_b128 v[198:201], v174 offset:0
	ds_read_b128 v[202:205], v174 offset:64
	ds_read_b128 v[206:209], v174 offset:128
	ds_read_b128 v[210:213], v174 offset:192
	v_mfma_f32_16x16x4_f32 v[224:227], v190, v214, v[224:227]
	v_mfma_f32_16x16x4_f32 v[224:227], v194, v215, v[224:227]
	v_mfma_f32_16x16x4_f32 v[228:231], v191, v214, v[228:231]
	v_mfma_f32_16x16x4_f32 v[228:231], v195, v215, v[228:231]
	v_mfma_f32_16x16x4_f32 v[232:235], v192, v214, v[232:235]
	v_mfma_f32_16x16x4_f32 v[232:235], v196, v215, v[232:235]
	v_mfma_f32_16x16x4_f32 v[236:239], v193, v214, v[236:239]
	v_mfma_f32_16x16x4_f32 v[236:239], v197, v215, v[236:239]
	ds_read_b32 v214, v169 offset:2048
	ds_read_b32 v215, v169 offset:3072
	v_pk_add_f32 v[80:81], v[36:37], v[40:41]
	v_pk_add_f32 v[82:83], v[38:39], v[42:43]
	v_pk_add_f32 v[84:85], v[36:37], v[40:41]
	v_pk_add_f32 v[86:87], v[38:39], v[42:43]
	v_pk_add_f32 v[36:37], v[36:37], v[40:41]
	v_pk_add_f32 v[38:39], v[38:39], v[42:43]
	v_permlane32_swap_b32_e32 v80, v84
	v_permlane32_swap_b32_e32 v81, v85
	v_permlane32_swap_b32_e32 v82, v86
	v_permlane32_swap_b32_e32 v83, v87
	v_mov_b32_e32 v88, v80
	v_mov_b32_e32 v89, v81
	v_mov_b32_e32 v90, v82
	v_mov_b32_e32 v91, v83
	s_nop 0
	v_permlane16_swap_b32_e32 v80, v88
	v_permlane16_swap_b32_e32 v81, v89
	v_permlane16_swap_b32_e32 v82, v90
	v_permlane16_swap_b32_e32 v83, v91
	v_fmac_f32_e32 v81, v124, v80
	v_fmac_f32_e32 v82, v128, v80
	v_fmac_f32_e32 v83, v132, v80
	v_fmac_f32_e32 v88, v136, v80
	v_fmac_f32_e32 v89, v144, v80
	v_fmac_f32_e32 v90, v152, v80
	v_fmac_f32_e32 v91, v160, v80
	v_fmac_f32_e32 v82, v129, v81
	v_fmac_f32_e32 v83, v133, v81
	v_fmac_f32_e32 v88, v137, v81
	v_fmac_f32_e32 v89, v145, v81
	v_fmac_f32_e32 v90, v153, v81
	v_fmac_f32_e32 v91, v161, v81
	v_fmac_f32_e32 v83, v134, v82
	v_fmac_f32_e32 v88, v138, v82
	v_fmac_f32_e32 v89, v146, v82
	v_fmac_f32_e32 v90, v154, v82
	v_fmac_f32_e32 v91, v162, v82
	v_fmac_f32_e32 v88, v139, v83
	v_fmac_f32_e32 v89, v147, v83
	v_fmac_f32_e32 v90, v155, v83
	v_fmac_f32_e32 v91, v163, v83
	v_fmac_f32_e32 v89, v148, v88
	v_fmac_f32_e32 v90, v156, v88
	v_fmac_f32_e32 v91, v164, v88
	v_fmac_f32_e32 v90, v157, v89
	v_fmac_f32_e32 v91, v165, v89
	v_fmac_f32_e32 v91, v166, v90
	ds_read_b128 v[124:127], v170 offset:1056
	ds_read_b128 v[128:131], v170 offset:1088
	ds_read_b128 v[132:135], v170 offset:1120
	ds_read_b128 v[136:139], v170 offset:1152
	ds_read_b128 v[144:147], v170 offset:1184
	ds_read_b128 v[148:151], v170 offset:1200
	ds_read_b128 v[152:155], v170 offset:1216
	ds_read_b128 v[156:159], v170 offset:1232
	ds_read_b128 v[160:163], v170 offset:1248
	ds_read_b128 v[164:167], v170 offset:1264
	v_cndmask_b32_e32 v220, v80, v81, vcc
	v_cndmask_b32_e64 v220, v220, v82, s[4:5]
	v_cndmask_b32_e64 v220, v220, v83, s[6:7]
	v_cndmask_b32_e32 v221, v88, v89, vcc
	v_cndmask_b32_e64 v221, v221, v90, s[4:5]
	v_cndmask_b32_e64 v221, v221, v91, s[6:7]
	s_nop 1
	v_mfma_f32_16x16x4_f32 v[84:87], v218, v220, v[36:39]
	v_mfma_f32_16x16x4_f32 v[84:87], v219, v221, v[84:87]
	ds_read_b32 v218, v172 offset:1024
	ds_read_b32 v219, v172 offset:1040
	v_mfma_f32_16x16x4_f32 v[224:227], v182, v220, v[224:227]
	v_mfma_f32_16x16x4_f32 v[224:227], v186, v221, v[224:227]
	v_mfma_f32_16x16x4_f32 v[228:231], v183, v220, v[228:231]
	v_mfma_f32_16x16x4_f32 v[228:231], v187, v221, v[228:231]
	v_mfma_f32_16x16x4_f32 v[232:235], v184, v220, v[232:235]
	v_mfma_f32_16x16x4_f32 v[232:235], v188, v221, v[232:235]
	v_mfma_f32_16x16x4_f32 v[236:239], v185, v220, v[236:239]
	v_mfma_f32_16x16x4_f32 v[236:239], v189, v221, v[236:239]
	v_add_u32_e32 v173, 0x880, v173
	v_add_u32_e32 v2, 0x880, v2
	v_add_u32_e32 v3, 0x880, v3
	v_add_u32_e32 v5, 0x880, v5
	ds_read2_b32 v[182:183], v173 offset0:0 offset1:16
	ds_read2_b32 v[184:185], v173 offset0:32 offset1:48
	ds_read2_b32 v[186:187], v2 offset0:0 offset1:16
	ds_read2_b32 v[188:189], v2 offset0:32 offset1:48
	ds_read2_b32 v[190:191], v3 offset0:0 offset1:16
	ds_read2_b32 v[192:193], v3 offset0:32 offset1:48
	ds_read2_b32 v[194:195], v5 offset0:0 offset1:16
	ds_read2_b32 v[196:197], v5 offset0:32 offset1:48
	s_mov_b64 exec, s[8:9]
	ds_write_b32 v175, v84 offset:0
	ds_write_b32 v175, v85 offset:256
	ds_write_b32 v175, v86 offset:512
	ds_write_b32 v175, v87 offset:768
	s_mov_b64 exec, -1
	s_waitcnt lgkmcnt(4)
	v_pk_mul_f32 v[224:225], v[224:225], v[198:199]
	v_pk_mul_f32 v[226:227], v[226:227], v[200:201]
	v_pk_mul_f32 v[228:229], v[228:229], v[202:203]
	v_pk_mul_f32 v[230:231], v[230:231], v[204:205]
	v_mfma_f32_16x16x4_f32 v[36:39], v44, v224, 0
	v_mfma_f32_16x16x4_f32 v[40:43], v45, v225, 0
	v_mfma_f32_16x16x4_f32 v[36:39], v46, v226, v[36:39]
	v_mfma_f32_16x16x4_f32 v[40:43], v47, v227, v[40:43]
	v_pk_mul_f32 v[232:233], v[232:233], v[206:207]
	v_pk_mul_f32 v[234:235], v[234:235], v[208:209]
	v_mfma_f32_16x16x4_f32 v[36:39], v48, v228, v[36:39]
	v_mfma_f32_16x16x4_f32 v[40:43], v49, v229, v[40:43]
	v_mfma_f32_16x16x4_f32 v[36:39], v50, v230, v[36:39]
	v_mfma_f32_16x16x4_f32 v[40:43], v51, v231, v[40:43]
	v_pk_mul_f32 v[236:237], v[236:237], v[210:211]
	v_pk_mul_f32 v[238:239], v[238:239], v[212:213]
	v_mfma_f32_16x16x4_f32 v[36:39], v68, v232, v[36:39]
	v_mfma_f32_16x16x4_f32 v[40:43], v69, v233, v[40:43]
	v_mfma_f32_16x16x4_f32 v[36:39], v70, v234, v[36:39]
	v_mfma_f32_16x16x4_f32 v[40:43], v71, v235, v[40:43]
	v_mfma_f32_16x16x4_f32 v[36:39], v96, v236, v[36:39]
	v_mfma_f32_16x16x4_f32 v[40:43], v97, v237, v[40:43]
	v_mfma_f32_16x16x4_f32 v[36:39], v98, v238, v[36:39]
	v_mfma_f32_16x16x4_f32 v[40:43], v99, v239, v[40:43]
	v_mfma_f32_16x16x4_f32 v[36:39], v216, v214, v[36:39]
	v_mfma_f32_16x16x4_f32 v[40:43], v217, v215, v[40:43]
	ds_read_b128 v[44:47], v168 offset:4352
	ds_read_b128 v[48:51], v168 offset:4416
	ds_read_b128 v[68:71], v168 offset:4480
	ds_read_b128 v[96:99], v168 offset:4544
	ds_read_b32 v216, v171 offset:2048
	ds_read_b32 v217, v171 offset:2064
	ds_read_b128 v[198:201], v174 offset:256
	ds_read_b128 v[202:205], v174 offset:320
	ds_read_b128 v[206:209], v174 offset:384
	ds_read_b128 v[210:213], v174 offset:448
	v_mfma_f32_16x16x4_f32 v[224:227], v190, v214, v[224:227]
	v_mfma_f32_16x16x4_f32 v[224:227], v194, v215, v[224:227]
	v_mfma_f32_16x16x4_f32 v[228:231], v191, v214, v[228:231]
	v_mfma_f32_16x16x4_f32 v[228:231], v195, v215, v[228:231]
	v_mfma_f32_16x16x4_f32 v[232:235], v192, v214, v[232:235]
	v_mfma_f32_16x16x4_f32 v[232:235], v196, v215, v[232:235]
	v_mfma_f32_16x16x4_f32 v[236:239], v193, v214, v[236:239]
	v_mfma_f32_16x16x4_f32 v[236:239], v197, v215, v[236:239]
	ds_read_b32 v214, v169 offset:4096
	ds_read_b32 v215, v169 offset:5120
	v_pk_add_f32 v[80:81], v[36:37], v[40:41]
	v_pk_add_f32 v[82:83], v[38:39], v[42:43]
	v_pk_add_f32 v[84:85], v[36:37], v[40:41]
	v_pk_add_f32 v[86:87], v[38:39], v[42:43]
	v_pk_add_f32 v[36:37], v[36:37], v[40:41]
	v_pk_add_f32 v[38:39], v[38:39], v[42:43]
	v_permlane32_swap_b32_e32 v80, v84
	v_permlane32_swap_b32_e32 v81, v85
	v_permlane32_swap_b32_e32 v82, v86
	v_permlane32_swap_b32_e32 v83, v87
	v_mov_b32_e32 v88, v80
	v_mov_b32_e32 v89, v81
	v_mov_b32_e32 v90, v82
	v_mov_b32_e32 v91, v83
	s_nop 0
	v_permlane16_swap_b32_e32 v80, v88
	v_permlane16_swap_b32_e32 v81, v89
	v_permlane16_swap_b32_e32 v82, v90
	v_permlane16_swap_b32_e32 v83, v91
	v_fmac_f32_e32 v81, v124, v80
	v_fmac_f32_e32 v82, v128, v80
	v_fmac_f32_e32 v83, v132, v80
	v_fmac_f32_e32 v88, v136, v80
	v_fmac_f32_e32 v89, v144, v80
	v_fmac_f32_e32 v90, v152, v80
	v_fmac_f32_e32 v91, v160, v80
	v_fmac_f32_e32 v82, v129, v81
	v_fmac_f32_e32 v83, v133, v81
	v_fmac_f32_e32 v88, v137, v81
	v_fmac_f32_e32 v89, v145, v81
	v_fmac_f32_e32 v90, v153, v81
	v_fmac_f32_e32 v91, v161, v81
	v_fmac_f32_e32 v83, v134, v82
	v_fmac_f32_e32 v88, v138, v82
	v_fmac_f32_e32 v89, v146, v82
	v_fmac_f32_e32 v90, v154, v82
	v_fmac_f32_e32 v91, v162, v82
	v_fmac_f32_e32 v88, v139, v83
	v_fmac_f32_e32 v89, v147, v83
	v_fmac_f32_e32 v90, v155, v83
	v_fmac_f32_e32 v91, v163, v83
	v_fmac_f32_e32 v89, v148, v88
	v_fmac_f32_e32 v90, v156, v88
	v_fmac_f32_e32 v91, v164, v88
	v_fmac_f32_e32 v90, v157, v89
	v_fmac_f32_e32 v91, v165, v89
	v_fmac_f32_e32 v91, v166, v90
	ds_read_b128 v[124:127], v170 offset:2080
	ds_read_b128 v[128:131], v170 offset:2112
	ds_read_b128 v[132:135], v170 offset:2144
	ds_read_b128 v[136:139], v170 offset:2176
	ds_read_b128 v[144:147], v170 offset:2208
	ds_read_b128 v[148:151], v170 offset:2224
	ds_read_b128 v[152:155], v170 offset:2240
	ds_read_b128 v[156:159], v170 offset:2256
	ds_read_b128 v[160:163], v170 offset:2272
	ds_read_b128 v[164:167], v170 offset:2288
	v_cndmask_b32_e32 v220, v80, v81, vcc
	v_cndmask_b32_e64 v220, v220, v82, s[4:5]
	v_cndmask_b32_e64 v220, v220, v83, s[6:7]
	v_cndmask_b32_e32 v221, v88, v89, vcc
	v_cndmask_b32_e64 v221, v221, v90, s[4:5]
	v_cndmask_b32_e64 v221, v221, v91, s[6:7]
	s_nop 1
	v_mfma_f32_16x16x4_f32 v[84:87], v218, v220, v[36:39]
	v_mfma_f32_16x16x4_f32 v[84:87], v219, v221, v[84:87]
	ds_read_b32 v218, v172 offset:2048
	ds_read_b32 v219, v172 offset:2064
	v_mfma_f32_16x16x4_f32 v[224:227], v182, v220, v[224:227]
	v_mfma_f32_16x16x4_f32 v[224:227], v186, v221, v[224:227]
	v_mfma_f32_16x16x4_f32 v[228:231], v183, v220, v[228:231]
	v_mfma_f32_16x16x4_f32 v[228:231], v187, v221, v[228:231]
	v_mfma_f32_16x16x4_f32 v[232:235], v184, v220, v[232:235]
	v_mfma_f32_16x16x4_f32 v[232:235], v188, v221, v[232:235]
	v_mfma_f32_16x16x4_f32 v[236:239], v185, v220, v[236:239]
	v_mfma_f32_16x16x4_f32 v[236:239], v189, v221, v[236:239]
	v_add_u32_e32 v173, 0x880, v173
	v_add_u32_e32 v2, 0x880, v2
	v_add_u32_e32 v3, 0x880, v3
	v_add_u32_e32 v5, 0x880, v5
	ds_read2_b32 v[182:183], v173 offset0:0 offset1:16
	ds_read2_b32 v[184:185], v173 offset0:32 offset1:48
	ds_read2_b32 v[186:187], v2 offset0:0 offset1:16
	ds_read2_b32 v[188:189], v2 offset0:32 offset1:48
	ds_read2_b32 v[190:191], v3 offset0:0 offset1:16
	ds_read2_b32 v[192:193], v3 offset0:32 offset1:48
	ds_read2_b32 v[194:195], v5 offset0:0 offset1:16
	ds_read2_b32 v[196:197], v5 offset0:32 offset1:48
	s_mov_b64 exec, s[8:9]
	ds_write_b32 v175, v84 offset:2048
	ds_write_b32 v175, v85 offset:2304
	ds_write_b32 v175, v86 offset:2560
	ds_write_b32 v175, v87 offset:2816
	s_mov_b64 exec, -1
	s_waitcnt lgkmcnt(4)
	v_pk_mul_f32 v[224:225], v[224:225], v[198:199]
	v_pk_mul_f32 v[226:227], v[226:227], v[200:201]
	v_pk_mul_f32 v[228:229], v[228:229], v[202:203]
	v_pk_mul_f32 v[230:231], v[230:231], v[204:205]
	v_mfma_f32_16x16x4_f32 v[36:39], v44, v224, 0
	v_mfma_f32_16x16x4_f32 v[40:43], v45, v225, 0
	v_mfma_f32_16x16x4_f32 v[36:39], v46, v226, v[36:39]
	v_mfma_f32_16x16x4_f32 v[40:43], v47, v227, v[40:43]
	v_pk_mul_f32 v[232:233], v[232:233], v[206:207]
	v_pk_mul_f32 v[234:235], v[234:235], v[208:209]
	v_mfma_f32_16x16x4_f32 v[36:39], v48, v228, v[36:39]
	v_mfma_f32_16x16x4_f32 v[40:43], v49, v229, v[40:43]
	v_mfma_f32_16x16x4_f32 v[36:39], v50, v230, v[36:39]
	v_mfma_f32_16x16x4_f32 v[40:43], v51, v231, v[40:43]
	v_pk_mul_f32 v[236:237], v[236:237], v[210:211]
	v_pk_mul_f32 v[238:239], v[238:239], v[212:213]
	v_mfma_f32_16x16x4_f32 v[36:39], v68, v232, v[36:39]
	v_mfma_f32_16x16x4_f32 v[40:43], v69, v233, v[40:43]
	v_mfma_f32_16x16x4_f32 v[36:39], v70, v234, v[36:39]
	v_mfma_f32_16x16x4_f32 v[40:43], v71, v235, v[40:43]
	v_mfma_f32_16x16x4_f32 v[36:39], v96, v236, v[36:39]
	v_mfma_f32_16x16x4_f32 v[40:43], v97, v237, v[40:43]
	v_mfma_f32_16x16x4_f32 v[36:39], v98, v238, v[36:39]
	v_mfma_f32_16x16x4_f32 v[40:43], v99, v239, v[40:43]
	v_mfma_f32_16x16x4_f32 v[36:39], v216, v214, v[36:39]
	v_mfma_f32_16x16x4_f32 v[40:43], v217, v215, v[40:43]
	ds_read_b128 v[44:47], v168 offset:6528
	ds_read_b128 v[48:51], v168 offset:6592
	ds_read_b128 v[68:71], v168 offset:6656
	ds_read_b128 v[96:99], v168 offset:6720
	ds_read_b32 v216, v171 offset:3072
	ds_read_b32 v217, v171 offset:3088
	ds_read_b128 v[198:201], v174 offset:512
	ds_read_b128 v[202:205], v174 offset:576
	ds_read_b128 v[206:209], v174 offset:640
	ds_read_b128 v[210:213], v174 offset:704
	v_mfma_f32_16x16x4_f32 v[224:227], v190, v214, v[224:227]
	v_mfma_f32_16x16x4_f32 v[224:227], v194, v215, v[224:227]
	v_mfma_f32_16x16x4_f32 v[228:231], v191, v214, v[228:231]
	v_mfma_f32_16x16x4_f32 v[228:231], v195, v215, v[228:231]
	v_mfma_f32_16x16x4_f32 v[232:235], v192, v214, v[232:235]
	v_mfma_f32_16x16x4_f32 v[232:235], v196, v215, v[232:235]
	v_mfma_f32_16x16x4_f32 v[236:239], v193, v214, v[236:239]
	v_mfma_f32_16x16x4_f32 v[236:239], v197, v215, v[236:239]
	ds_read_b32 v214, v169 offset:6144
	ds_read_b32 v215, v169 offset:7168
	v_pk_add_f32 v[80:81], v[36:37], v[40:41]
	v_pk_add_f32 v[82:83], v[38:39], v[42:43]
	v_pk_add_f32 v[84:85], v[36:37], v[40:41]
	v_pk_add_f32 v[86:87], v[38:39], v[42:43]
	v_pk_add_f32 v[36:37], v[36:37], v[40:41]
	v_pk_add_f32 v[38:39], v[38:39], v[42:43]
	v_permlane32_swap_b32_e32 v80, v84
	v_permlane32_swap_b32_e32 v81, v85
	v_permlane32_swap_b32_e32 v82, v86
	v_permlane32_swap_b32_e32 v83, v87
	v_mov_b32_e32 v88, v80
	v_mov_b32_e32 v89, v81
	v_mov_b32_e32 v90, v82
	v_mov_b32_e32 v91, v83
	s_nop 0
	v_permlane16_swap_b32_e32 v80, v88
	v_permlane16_swap_b32_e32 v81, v89
	v_permlane16_swap_b32_e32 v82, v90
	v_permlane16_swap_b32_e32 v83, v91
	v_fmac_f32_e32 v81, v124, v80
	v_fmac_f32_e32 v82, v128, v80
	v_fmac_f32_e32 v83, v132, v80
	v_fmac_f32_e32 v88, v136, v80
	v_fmac_f32_e32 v89, v144, v80
	v_fmac_f32_e32 v90, v152, v80
	v_fmac_f32_e32 v91, v160, v80
	v_fmac_f32_e32 v82, v129, v81
	v_fmac_f32_e32 v83, v133, v81
	v_fmac_f32_e32 v88, v137, v81
	v_fmac_f32_e32 v89, v145, v81
	v_fmac_f32_e32 v90, v153, v81
	v_fmac_f32_e32 v91, v161, v81
	v_fmac_f32_e32 v83, v134, v82
	v_fmac_f32_e32 v88, v138, v82
	v_fmac_f32_e32 v89, v146, v82
	v_fmac_f32_e32 v90, v154, v82
	v_fmac_f32_e32 v91, v162, v82
	v_fmac_f32_e32 v88, v139, v83
	v_fmac_f32_e32 v89, v147, v83
	v_fmac_f32_e32 v90, v155, v83
	v_fmac_f32_e32 v91, v163, v83
	v_fmac_f32_e32 v89, v148, v88
	v_fmac_f32_e32 v90, v156, v88
	v_fmac_f32_e32 v91, v164, v88
	v_fmac_f32_e32 v90, v157, v89
	v_fmac_f32_e32 v91, v165, v89
	v_fmac_f32_e32 v91, v166, v90
	ds_read_b128 v[124:127], v170 offset:3104
	ds_read_b128 v[128:131], v170 offset:3136
	ds_read_b128 v[132:135], v170 offset:3168
	ds_read_b128 v[136:139], v170 offset:3200
	ds_read_b128 v[144:147], v170 offset:3232
	ds_read_b128 v[148:151], v170 offset:3248
	ds_read_b128 v[152:155], v170 offset:3264
	ds_read_b128 v[156:159], v170 offset:3280
	ds_read_b128 v[160:163], v170 offset:3296
	ds_read_b128 v[164:167], v170 offset:3312
	v_cndmask_b32_e32 v220, v80, v81, vcc
	v_cndmask_b32_e64 v220, v220, v82, s[4:5]
	v_cndmask_b32_e64 v220, v220, v83, s[6:7]
	v_cndmask_b32_e32 v221, v88, v89, vcc
	v_cndmask_b32_e64 v221, v221, v90, s[4:5]
	v_cndmask_b32_e64 v221, v221, v91, s[6:7]
	s_nop 1
	v_mfma_f32_16x16x4_f32 v[84:87], v218, v220, v[36:39]
	v_mfma_f32_16x16x4_f32 v[84:87], v219, v221, v[84:87]
	ds_read_b32 v218, v172 offset:3072
	ds_read_b32 v219, v172 offset:3088
	v_mfma_f32_16x16x4_f32 v[224:227], v182, v220, v[224:227]
	v_mfma_f32_16x16x4_f32 v[224:227], v186, v221, v[224:227]
	v_mfma_f32_16x16x4_f32 v[228:231], v183, v220, v[228:231]
	v_mfma_f32_16x16x4_f32 v[228:231], v187, v221, v[228:231]
	v_mfma_f32_16x16x4_f32 v[232:235], v184, v220, v[232:235]
	v_mfma_f32_16x16x4_f32 v[232:235], v188, v221, v[232:235]
	v_mfma_f32_16x16x4_f32 v[236:239], v185, v220, v[236:239]
	v_mfma_f32_16x16x4_f32 v[236:239], v189, v221, v[236:239]
	v_add_u32_e32 v173, 0x880, v173
	v_add_u32_e32 v2, 0x880, v2
	v_add_u32_e32 v3, 0x880, v3
	v_add_u32_e32 v5, 0x880, v5
	ds_read2_b32 v[182:183], v173 offset0:0 offset1:16
	ds_read2_b32 v[184:185], v173 offset0:32 offset1:48
	ds_read2_b32 v[186:187], v2 offset0:0 offset1:16
	ds_read2_b32 v[188:189], v2 offset0:32 offset1:48
	ds_read2_b32 v[190:191], v3 offset0:0 offset1:16
	ds_read2_b32 v[192:193], v3 offset0:32 offset1:48
	ds_read2_b32 v[194:195], v5 offset0:0 offset1:16
	ds_read2_b32 v[196:197], v5 offset0:32 offset1:48
	s_mov_b64 exec, s[8:9]
	ds_write_b32 v175, v84 offset:4096
	ds_write_b32 v175, v85 offset:4352
	ds_write_b32 v175, v86 offset:4608
	ds_write_b32 v175, v87 offset:4864
	s_mov_b64 exec, -1
	s_waitcnt lgkmcnt(4)
	v_pk_mul_f32 v[224:225], v[224:225], v[198:199]
	v_pk_mul_f32 v[226:227], v[226:227], v[200:201]
	v_pk_mul_f32 v[228:229], v[228:229], v[202:203]
	v_pk_mul_f32 v[230:231], v[230:231], v[204:205]
	v_mfma_f32_16x16x4_f32 v[36:39], v44, v224, 0
	v_mfma_f32_16x16x4_f32 v[40:43], v45, v225, 0
	v_mfma_f32_16x16x4_f32 v[36:39], v46, v226, v[36:39]
	v_mfma_f32_16x16x4_f32 v[40:43], v47, v227, v[40:43]
	v_pk_mul_f32 v[232:233], v[232:233], v[206:207]
	v_pk_mul_f32 v[234:235], v[234:235], v[208:209]
	v_mfma_f32_16x16x4_f32 v[36:39], v48, v228, v[36:39]
	v_mfma_f32_16x16x4_f32 v[40:43], v49, v229, v[40:43]
	v_mfma_f32_16x16x4_f32 v[36:39], v50, v230, v[36:39]
	v_mfma_f32_16x16x4_f32 v[40:43], v51, v231, v[40:43]
	v_pk_mul_f32 v[236:237], v[236:237], v[210:211]
	v_pk_mul_f32 v[238:239], v[238:239], v[212:213]
	v_mfma_f32_16x16x4_f32 v[36:39], v68, v232, v[36:39]
	v_mfma_f32_16x16x4_f32 v[40:43], v69, v233, v[40:43]
	v_mfma_f32_16x16x4_f32 v[36:39], v70, v234, v[36:39]
	v_mfma_f32_16x16x4_f32 v[40:43], v71, v235, v[40:43]
	v_mfma_f32_16x16x4_f32 v[36:39], v96, v236, v[36:39]
	v_mfma_f32_16x16x4_f32 v[40:43], v97, v237, v[40:43]
	v_mfma_f32_16x16x4_f32 v[36:39], v98, v238, v[36:39]
	v_mfma_f32_16x16x4_f32 v[40:43], v99, v239, v[40:43]
	v_mfma_f32_16x16x4_f32 v[36:39], v216, v214, v[36:39]
	v_mfma_f32_16x16x4_f32 v[40:43], v217, v215, v[40:43]
	ds_read_b128 v[44:47], v168 offset:8704
	ds_read_b128 v[48:51], v168 offset:8768
	ds_read_b128 v[68:71], v168 offset:8832
	ds_read_b128 v[96:99], v168 offset:8896
	ds_read_b32 v216, v171 offset:4096
	ds_read_b32 v217, v171 offset:4112
	ds_read_b128 v[198:201], v174 offset:768
	ds_read_b128 v[202:205], v174 offset:832
	ds_read_b128 v[206:209], v174 offset:896
	ds_read_b128 v[210:213], v174 offset:960
	v_mfma_f32_16x16x4_f32 v[224:227], v190, v214, v[224:227]
	v_mfma_f32_16x16x4_f32 v[224:227], v194, v215, v[224:227]
	v_mfma_f32_16x16x4_f32 v[228:231], v191, v214, v[228:231]
	v_mfma_f32_16x16x4_f32 v[228:231], v195, v215, v[228:231]
	v_mfma_f32_16x16x4_f32 v[232:235], v192, v214, v[232:235]
	v_mfma_f32_16x16x4_f32 v[232:235], v196, v215, v[232:235]
	v_mfma_f32_16x16x4_f32 v[236:239], v193, v214, v[236:239]
	v_mfma_f32_16x16x4_f32 v[236:239], v197, v215, v[236:239]
	ds_read_b32 v214, v169 offset:8192
	ds_read_b32 v215, v169 offset:9216
	v_pk_add_f32 v[80:81], v[36:37], v[40:41]
	v_pk_add_f32 v[82:83], v[38:39], v[42:43]
	v_pk_add_f32 v[84:85], v[36:37], v[40:41]
	v_pk_add_f32 v[86:87], v[38:39], v[42:43]
	v_pk_add_f32 v[36:37], v[36:37], v[40:41]
	v_pk_add_f32 v[38:39], v[38:39], v[42:43]
	v_permlane32_swap_b32_e32 v80, v84
	v_permlane32_swap_b32_e32 v81, v85
	v_permlane32_swap_b32_e32 v82, v86
	v_permlane32_swap_b32_e32 v83, v87
	v_mov_b32_e32 v88, v80
	v_mov_b32_e32 v89, v81
	v_mov_b32_e32 v90, v82
	v_mov_b32_e32 v91, v83
	s_nop 0
	v_permlane16_swap_b32_e32 v80, v88
	v_permlane16_swap_b32_e32 v81, v89
	v_permlane16_swap_b32_e32 v82, v90
	v_permlane16_swap_b32_e32 v83, v91
	v_fmac_f32_e32 v81, v124, v80
	v_fmac_f32_e32 v82, v128, v80
	v_fmac_f32_e32 v83, v132, v80
	v_fmac_f32_e32 v88, v136, v80
	v_fmac_f32_e32 v89, v144, v80
	v_fmac_f32_e32 v90, v152, v80
	v_fmac_f32_e32 v91, v160, v80
	v_fmac_f32_e32 v82, v129, v81
	v_fmac_f32_e32 v83, v133, v81
	v_fmac_f32_e32 v88, v137, v81
	v_fmac_f32_e32 v89, v145, v81
	v_fmac_f32_e32 v90, v153, v81
	v_fmac_f32_e32 v91, v161, v81
	v_fmac_f32_e32 v83, v134, v82
	v_fmac_f32_e32 v88, v138, v82
	v_fmac_f32_e32 v89, v146, v82
	v_fmac_f32_e32 v90, v154, v82
	v_fmac_f32_e32 v91, v162, v82
	v_fmac_f32_e32 v88, v139, v83
	v_fmac_f32_e32 v89, v147, v83
	v_fmac_f32_e32 v90, v155, v83
	v_fmac_f32_e32 v91, v163, v83
	v_fmac_f32_e32 v89, v148, v88
	v_fmac_f32_e32 v90, v156, v88
	v_fmac_f32_e32 v91, v164, v88
	v_fmac_f32_e32 v90, v157, v89
	v_fmac_f32_e32 v91, v165, v89
	v_fmac_f32_e32 v91, v166, v90
	ds_read_b128 v[124:127], v170 offset:4128
	ds_read_b128 v[128:131], v170 offset:4160
	ds_read_b128 v[132:135], v170 offset:4192
	ds_read_b128 v[136:139], v170 offset:4224
	ds_read_b128 v[144:147], v170 offset:4256
	ds_read_b128 v[148:151], v170 offset:4272
	ds_read_b128 v[152:155], v170 offset:4288
	ds_read_b128 v[156:159], v170 offset:4304
	ds_read_b128 v[160:163], v170 offset:4320
	ds_read_b128 v[164:167], v170 offset:4336
	v_cndmask_b32_e32 v220, v80, v81, vcc
	v_cndmask_b32_e64 v220, v220, v82, s[4:5]
	v_cndmask_b32_e64 v220, v220, v83, s[6:7]
	v_cndmask_b32_e32 v221, v88, v89, vcc
	v_cndmask_b32_e64 v221, v221, v90, s[4:5]
	v_cndmask_b32_e64 v221, v221, v91, s[6:7]
	s_nop 1
	v_mfma_f32_16x16x4_f32 v[84:87], v218, v220, v[36:39]
	v_mfma_f32_16x16x4_f32 v[84:87], v219, v221, v[84:87]
	ds_read_b32 v218, v172 offset:4096
	ds_read_b32 v219, v172 offset:4112
	v_mfma_f32_16x16x4_f32 v[224:227], v182, v220, v[224:227]
	v_mfma_f32_16x16x4_f32 v[224:227], v186, v221, v[224:227]
	v_mfma_f32_16x16x4_f32 v[228:231], v183, v220, v[228:231]
	v_mfma_f32_16x16x4_f32 v[228:231], v187, v221, v[228:231]
	v_mfma_f32_16x16x4_f32 v[232:235], v184, v220, v[232:235]
	v_mfma_f32_16x16x4_f32 v[232:235], v188, v221, v[232:235]
	v_mfma_f32_16x16x4_f32 v[236:239], v185, v220, v[236:239]
	v_mfma_f32_16x16x4_f32 v[236:239], v189, v221, v[236:239]
	v_add_u32_e32 v173, 0x880, v173
	v_add_u32_e32 v2, 0x880, v2
	v_add_u32_e32 v3, 0x880, v3
	v_add_u32_e32 v5, 0x880, v5
	ds_read2_b32 v[182:183], v173 offset0:0 offset1:16
	ds_read2_b32 v[184:185], v173 offset0:32 offset1:48
	ds_read2_b32 v[186:187], v2 offset0:0 offset1:16
	ds_read2_b32 v[188:189], v2 offset0:32 offset1:48
	ds_read2_b32 v[190:191], v3 offset0:0 offset1:16
	ds_read2_b32 v[192:193], v3 offset0:32 offset1:48
	ds_read2_b32 v[194:195], v5 offset0:0 offset1:16
	ds_read2_b32 v[196:197], v5 offset0:32 offset1:48
	s_mov_b64 exec, s[8:9]
	ds_write_b32 v175, v84 offset:6144
	ds_write_b32 v175, v85 offset:6400
	ds_write_b32 v175, v86 offset:6656
	ds_write_b32 v175, v87 offset:6912
	s_mov_b64 exec, -1
	s_waitcnt lgkmcnt(4)
	v_pk_mul_f32 v[224:225], v[224:225], v[198:199]
	v_pk_mul_f32 v[226:227], v[226:227], v[200:201]
	v_pk_mul_f32 v[228:229], v[228:229], v[202:203]
	v_pk_mul_f32 v[230:231], v[230:231], v[204:205]
	v_mfma_f32_16x16x4_f32 v[36:39], v44, v224, 0
	v_mfma_f32_16x16x4_f32 v[40:43], v45, v225, 0
	v_mfma_f32_16x16x4_f32 v[36:39], v46, v226, v[36:39]
	v_mfma_f32_16x16x4_f32 v[40:43], v47, v227, v[40:43]
	v_pk_mul_f32 v[232:233], v[232:233], v[206:207]
	v_pk_mul_f32 v[234:235], v[234:235], v[208:209]
	v_mfma_f32_16x16x4_f32 v[36:39], v48, v228, v[36:39]
	v_mfma_f32_16x16x4_f32 v[40:43], v49, v229, v[40:43]
	v_mfma_f32_16x16x4_f32 v[36:39], v50, v230, v[36:39]
	v_mfma_f32_16x16x4_f32 v[40:43], v51, v231, v[40:43]
	v_pk_mul_f32 v[236:237], v[236:237], v[210:211]
	v_pk_mul_f32 v[238:239], v[238:239], v[212:213]
	v_mfma_f32_16x16x4_f32 v[36:39], v68, v232, v[36:39]
	v_mfma_f32_16x16x4_f32 v[40:43], v69, v233, v[40:43]
	v_mfma_f32_16x16x4_f32 v[36:39], v70, v234, v[36:39]
	v_mfma_f32_16x16x4_f32 v[40:43], v71, v235, v[40:43]
	v_mfma_f32_16x16x4_f32 v[36:39], v96, v236, v[36:39]
	v_mfma_f32_16x16x4_f32 v[40:43], v97, v237, v[40:43]
	v_mfma_f32_16x16x4_f32 v[36:39], v98, v238, v[36:39]
	v_mfma_f32_16x16x4_f32 v[40:43], v99, v239, v[40:43]
	v_mfma_f32_16x16x4_f32 v[36:39], v216, v214, v[36:39]
	v_mfma_f32_16x16x4_f32 v[40:43], v217, v215, v[40:43]
	ds_read_b128 v[44:47], v168 offset:10880
	ds_read_b128 v[48:51], v168 offset:10944
	ds_read_b128 v[68:71], v168 offset:11008
	ds_read_b128 v[96:99], v168 offset:11072
	ds_read_b32 v216, v171 offset:5120
	ds_read_b32 v217, v171 offset:5136
	ds_read_b128 v[198:201], v174 offset:1024
	ds_read_b128 v[202:205], v174 offset:1088
	ds_read_b128 v[206:209], v174 offset:1152
	ds_read_b128 v[210:213], v174 offset:1216
	v_mfma_f32_16x16x4_f32 v[224:227], v190, v214, v[224:227]
	v_mfma_f32_16x16x4_f32 v[224:227], v194, v215, v[224:227]
	v_mfma_f32_16x16x4_f32 v[228:231], v191, v214, v[228:231]
	v_mfma_f32_16x16x4_f32 v[228:231], v195, v215, v[228:231]
	v_mfma_f32_16x16x4_f32 v[232:235], v192, v214, v[232:235]
	v_mfma_f32_16x16x4_f32 v[232:235], v196, v215, v[232:235]
	v_mfma_f32_16x16x4_f32 v[236:239], v193, v214, v[236:239]
	v_mfma_f32_16x16x4_f32 v[236:239], v197, v215, v[236:239]
	ds_read_b32 v214, v169 offset:10240
	ds_read_b32 v215, v169 offset:11264
	v_pk_add_f32 v[80:81], v[36:37], v[40:41]
	v_pk_add_f32 v[82:83], v[38:39], v[42:43]
	v_pk_add_f32 v[84:85], v[36:37], v[40:41]
	v_pk_add_f32 v[86:87], v[38:39], v[42:43]
	v_pk_add_f32 v[36:37], v[36:37], v[40:41]
	v_pk_add_f32 v[38:39], v[38:39], v[42:43]
	v_permlane32_swap_b32_e32 v80, v84
	v_permlane32_swap_b32_e32 v81, v85
	v_permlane32_swap_b32_e32 v82, v86
	v_permlane32_swap_b32_e32 v83, v87
	v_mov_b32_e32 v88, v80
	v_mov_b32_e32 v89, v81
	v_mov_b32_e32 v90, v82
	v_mov_b32_e32 v91, v83
	s_nop 0
	v_permlane16_swap_b32_e32 v80, v88
	v_permlane16_swap_b32_e32 v81, v89
	v_permlane16_swap_b32_e32 v82, v90
	v_permlane16_swap_b32_e32 v83, v91
	v_fmac_f32_e32 v81, v124, v80
	v_fmac_f32_e32 v82, v128, v80
	v_fmac_f32_e32 v83, v132, v80
	v_fmac_f32_e32 v88, v136, v80
	v_fmac_f32_e32 v89, v144, v80
	v_fmac_f32_e32 v90, v152, v80
	v_fmac_f32_e32 v91, v160, v80
	v_fmac_f32_e32 v82, v129, v81
	v_fmac_f32_e32 v83, v133, v81
	v_fmac_f32_e32 v88, v137, v81
	v_fmac_f32_e32 v89, v145, v81
	v_fmac_f32_e32 v90, v153, v81
	v_fmac_f32_e32 v91, v161, v81
	v_fmac_f32_e32 v83, v134, v82
	v_fmac_f32_e32 v88, v138, v82
	v_fmac_f32_e32 v89, v146, v82
	v_fmac_f32_e32 v90, v154, v82
	v_fmac_f32_e32 v91, v162, v82
	v_fmac_f32_e32 v88, v139, v83
	v_fmac_f32_e32 v89, v147, v83
	v_fmac_f32_e32 v90, v155, v83
	v_fmac_f32_e32 v91, v163, v83
	v_fmac_f32_e32 v89, v148, v88
	v_fmac_f32_e32 v90, v156, v88
	v_fmac_f32_e32 v91, v164, v88
	v_fmac_f32_e32 v90, v157, v89
	v_fmac_f32_e32 v91, v165, v89
	v_fmac_f32_e32 v91, v166, v90
	ds_read_b128 v[124:127], v170 offset:5152
	ds_read_b128 v[128:131], v170 offset:5184
	ds_read_b128 v[132:135], v170 offset:5216
	ds_read_b128 v[136:139], v170 offset:5248
	ds_read_b128 v[144:147], v170 offset:5280
	ds_read_b128 v[148:151], v170 offset:5296
	ds_read_b128 v[152:155], v170 offset:5312
	ds_read_b128 v[156:159], v170 offset:5328
	ds_read_b128 v[160:163], v170 offset:5344
	ds_read_b128 v[164:167], v170 offset:5360
	v_cndmask_b32_e32 v220, v80, v81, vcc
	v_cndmask_b32_e64 v220, v220, v82, s[4:5]
	v_cndmask_b32_e64 v220, v220, v83, s[6:7]
	v_cndmask_b32_e32 v221, v88, v89, vcc
	v_cndmask_b32_e64 v221, v221, v90, s[4:5]
	v_cndmask_b32_e64 v221, v221, v91, s[6:7]
	s_nop 1
	v_mfma_f32_16x16x4_f32 v[84:87], v218, v220, v[36:39]
	v_mfma_f32_16x16x4_f32 v[84:87], v219, v221, v[84:87]
	ds_read_b32 v218, v172 offset:5120
	ds_read_b32 v219, v172 offset:5136
	v_mfma_f32_16x16x4_f32 v[224:227], v182, v220, v[224:227]
	v_mfma_f32_16x16x4_f32 v[224:227], v186, v221, v[224:227]
	v_mfma_f32_16x16x4_f32 v[228:231], v183, v220, v[228:231]
	v_mfma_f32_16x16x4_f32 v[228:231], v187, v221, v[228:231]
	v_mfma_f32_16x16x4_f32 v[232:235], v184, v220, v[232:235]
	v_mfma_f32_16x16x4_f32 v[232:235], v188, v221, v[232:235]
	v_mfma_f32_16x16x4_f32 v[236:239], v185, v220, v[236:239]
	v_mfma_f32_16x16x4_f32 v[236:239], v189, v221, v[236:239]
	v_add_u32_e32 v173, 0x880, v173
	v_add_u32_e32 v2, 0x880, v2
	v_add_u32_e32 v3, 0x880, v3
	v_add_u32_e32 v5, 0x880, v5
	ds_read2_b32 v[182:183], v173 offset0:0 offset1:16
	ds_read2_b32 v[184:185], v173 offset0:32 offset1:48
	ds_read2_b32 v[186:187], v2 offset0:0 offset1:16
	ds_read2_b32 v[188:189], v2 offset0:32 offset1:48
	ds_read2_b32 v[190:191], v3 offset0:0 offset1:16
	ds_read2_b32 v[192:193], v3 offset0:32 offset1:48
	ds_read2_b32 v[194:195], v5 offset0:0 offset1:16
	ds_read2_b32 v[196:197], v5 offset0:32 offset1:48
	s_mov_b64 exec, s[8:9]
	ds_write_b32 v175, v84 offset:8192
	ds_write_b32 v175, v85 offset:8448
	ds_write_b32 v175, v86 offset:8704
	ds_write_b32 v175, v87 offset:8960
	s_mov_b64 exec, -1
	s_waitcnt lgkmcnt(4)
	v_pk_mul_f32 v[224:225], v[224:225], v[198:199]
	v_pk_mul_f32 v[226:227], v[226:227], v[200:201]
	v_pk_mul_f32 v[228:229], v[228:229], v[202:203]
	v_pk_mul_f32 v[230:231], v[230:231], v[204:205]
	v_mfma_f32_16x16x4_f32 v[36:39], v44, v224, 0
	v_mfma_f32_16x16x4_f32 v[40:43], v45, v225, 0
	v_mfma_f32_16x16x4_f32 v[36:39], v46, v226, v[36:39]
	v_mfma_f32_16x16x4_f32 v[40:43], v47, v227, v[40:43]
	v_pk_mul_f32 v[232:233], v[232:233], v[206:207]
	v_pk_mul_f32 v[234:235], v[234:235], v[208:209]
	v_mfma_f32_16x16x4_f32 v[36:39], v48, v228, v[36:39]
	v_mfma_f32_16x16x4_f32 v[40:43], v49, v229, v[40:43]
	v_mfma_f32_16x16x4_f32 v[36:39], v50, v230, v[36:39]
	v_mfma_f32_16x16x4_f32 v[40:43], v51, v231, v[40:43]
	v_pk_mul_f32 v[236:237], v[236:237], v[210:211]
	v_pk_mul_f32 v[238:239], v[238:239], v[212:213]
	v_mfma_f32_16x16x4_f32 v[36:39], v68, v232, v[36:39]
	v_mfma_f32_16x16x4_f32 v[40:43], v69, v233, v[40:43]
	v_mfma_f32_16x16x4_f32 v[36:39], v70, v234, v[36:39]
	v_mfma_f32_16x16x4_f32 v[40:43], v71, v235, v[40:43]
	v_mfma_f32_16x16x4_f32 v[36:39], v96, v236, v[36:39]
	v_mfma_f32_16x16x4_f32 v[40:43], v97, v237, v[40:43]
	v_mfma_f32_16x16x4_f32 v[36:39], v98, v238, v[36:39]
	v_mfma_f32_16x16x4_f32 v[40:43], v99, v239, v[40:43]
	v_mfma_f32_16x16x4_f32 v[36:39], v216, v214, v[36:39]
	v_mfma_f32_16x16x4_f32 v[40:43], v217, v215, v[40:43]
	ds_read_b128 v[44:47], v168 offset:13056
	ds_read_b128 v[48:51], v168 offset:13120
	ds_read_b128 v[68:71], v168 offset:13184
	ds_read_b128 v[96:99], v168 offset:13248
	ds_read_b32 v216, v171 offset:6144
	ds_read_b32 v217, v171 offset:6160
	ds_read_b128 v[198:201], v174 offset:1280
	ds_read_b128 v[202:205], v174 offset:1344
	ds_read_b128 v[206:209], v174 offset:1408
	ds_read_b128 v[210:213], v174 offset:1472
	v_mfma_f32_16x16x4_f32 v[224:227], v190, v214, v[224:227]
	v_mfma_f32_16x16x4_f32 v[224:227], v194, v215, v[224:227]
	v_mfma_f32_16x16x4_f32 v[228:231], v191, v214, v[228:231]
	v_mfma_f32_16x16x4_f32 v[228:231], v195, v215, v[228:231]
	v_mfma_f32_16x16x4_f32 v[232:235], v192, v214, v[232:235]
	v_mfma_f32_16x16x4_f32 v[232:235], v196, v215, v[232:235]
	v_mfma_f32_16x16x4_f32 v[236:239], v193, v214, v[236:239]
	v_mfma_f32_16x16x4_f32 v[236:239], v197, v215, v[236:239]
	ds_read_b32 v214, v169 offset:12288
	ds_read_b32 v215, v169 offset:13312
	v_pk_add_f32 v[80:81], v[36:37], v[40:41]
	v_pk_add_f32 v[82:83], v[38:39], v[42:43]
	v_pk_add_f32 v[84:85], v[36:37], v[40:41]
	v_pk_add_f32 v[86:87], v[38:39], v[42:43]
	v_pk_add_f32 v[36:37], v[36:37], v[40:41]
	v_pk_add_f32 v[38:39], v[38:39], v[42:43]
	v_permlane32_swap_b32_e32 v80, v84
	v_permlane32_swap_b32_e32 v81, v85
	v_permlane32_swap_b32_e32 v82, v86
	v_permlane32_swap_b32_e32 v83, v87
	v_mov_b32_e32 v88, v80
	v_mov_b32_e32 v89, v81
	v_mov_b32_e32 v90, v82
	v_mov_b32_e32 v91, v83
	s_nop 0
	v_permlane16_swap_b32_e32 v80, v88
	v_permlane16_swap_b32_e32 v81, v89
	v_permlane16_swap_b32_e32 v82, v90
	v_permlane16_swap_b32_e32 v83, v91
	v_fmac_f32_e32 v81, v124, v80
	v_fmac_f32_e32 v82, v128, v80
	v_fmac_f32_e32 v83, v132, v80
	v_fmac_f32_e32 v88, v136, v80
	v_fmac_f32_e32 v89, v144, v80
	v_fmac_f32_e32 v90, v152, v80
	v_fmac_f32_e32 v91, v160, v80
	v_fmac_f32_e32 v82, v129, v81
	v_fmac_f32_e32 v83, v133, v81
	v_fmac_f32_e32 v88, v137, v81
	v_fmac_f32_e32 v89, v145, v81
	v_fmac_f32_e32 v90, v153, v81
	v_fmac_f32_e32 v91, v161, v81
	v_fmac_f32_e32 v83, v134, v82
	v_fmac_f32_e32 v88, v138, v82
	v_fmac_f32_e32 v89, v146, v82
	v_fmac_f32_e32 v90, v154, v82
	v_fmac_f32_e32 v91, v162, v82
	v_fmac_f32_e32 v88, v139, v83
	v_fmac_f32_e32 v89, v147, v83
	v_fmac_f32_e32 v90, v155, v83
	v_fmac_f32_e32 v91, v163, v83
	v_fmac_f32_e32 v89, v148, v88
	v_fmac_f32_e32 v90, v156, v88
	v_fmac_f32_e32 v91, v164, v88
	v_fmac_f32_e32 v90, v157, v89
	v_fmac_f32_e32 v91, v165, v89
	v_fmac_f32_e32 v91, v166, v90
	ds_read_b128 v[124:127], v170 offset:6176
	ds_read_b128 v[128:131], v170 offset:6208
	ds_read_b128 v[132:135], v170 offset:6240
	ds_read_b128 v[136:139], v170 offset:6272
	ds_read_b128 v[144:147], v170 offset:6304
	ds_read_b128 v[148:151], v170 offset:6320
	ds_read_b128 v[152:155], v170 offset:6336
	ds_read_b128 v[156:159], v170 offset:6352
	ds_read_b128 v[160:163], v170 offset:6368
	ds_read_b128 v[164:167], v170 offset:6384
	v_cndmask_b32_e32 v220, v80, v81, vcc
	v_cndmask_b32_e64 v220, v220, v82, s[4:5]
	v_cndmask_b32_e64 v220, v220, v83, s[6:7]
	v_cndmask_b32_e32 v221, v88, v89, vcc
	v_cndmask_b32_e64 v221, v221, v90, s[4:5]
	v_cndmask_b32_e64 v221, v221, v91, s[6:7]
	s_nop 1
	v_mfma_f32_16x16x4_f32 v[84:87], v218, v220, v[36:39]
	v_mfma_f32_16x16x4_f32 v[84:87], v219, v221, v[84:87]
	ds_read_b32 v218, v172 offset:6144
	ds_read_b32 v219, v172 offset:6160
	v_mfma_f32_16x16x4_f32 v[224:227], v182, v220, v[224:227]
	v_mfma_f32_16x16x4_f32 v[224:227], v186, v221, v[224:227]
	v_mfma_f32_16x16x4_f32 v[228:231], v183, v220, v[228:231]
	v_mfma_f32_16x16x4_f32 v[228:231], v187, v221, v[228:231]
	v_mfma_f32_16x16x4_f32 v[232:235], v184, v220, v[232:235]
	v_mfma_f32_16x16x4_f32 v[232:235], v188, v221, v[232:235]
	v_mfma_f32_16x16x4_f32 v[236:239], v185, v220, v[236:239]
	v_mfma_f32_16x16x4_f32 v[236:239], v189, v221, v[236:239]
	v_add_u32_e32 v173, 0x880, v173
	v_add_u32_e32 v2, 0x880, v2
	v_add_u32_e32 v3, 0x880, v3
	v_add_u32_e32 v5, 0x880, v5
	ds_read2_b32 v[182:183], v173 offset0:0 offset1:16
	ds_read2_b32 v[184:185], v173 offset0:32 offset1:48
	ds_read2_b32 v[186:187], v2 offset0:0 offset1:16
	ds_read2_b32 v[188:189], v2 offset0:32 offset1:48
	ds_read2_b32 v[190:191], v3 offset0:0 offset1:16
	ds_read2_b32 v[192:193], v3 offset0:32 offset1:48
	ds_read2_b32 v[194:195], v5 offset0:0 offset1:16
	ds_read2_b32 v[196:197], v5 offset0:32 offset1:48
	s_mov_b64 exec, s[8:9]
	ds_write_b32 v175, v84 offset:10240
	ds_write_b32 v175, v85 offset:10496
	ds_write_b32 v175, v86 offset:10752
	ds_write_b32 v175, v87 offset:11008
	s_mov_b64 exec, -1
	s_waitcnt lgkmcnt(4)
	v_pk_mul_f32 v[224:225], v[224:225], v[198:199]
	v_pk_mul_f32 v[226:227], v[226:227], v[200:201]
	v_pk_mul_f32 v[228:229], v[228:229], v[202:203]
	v_pk_mul_f32 v[230:231], v[230:231], v[204:205]
	v_mfma_f32_16x16x4_f32 v[36:39], v44, v224, 0
	v_mfma_f32_16x16x4_f32 v[40:43], v45, v225, 0
	v_mfma_f32_16x16x4_f32 v[36:39], v46, v226, v[36:39]
	v_mfma_f32_16x16x4_f32 v[40:43], v47, v227, v[40:43]
	v_pk_mul_f32 v[232:233], v[232:233], v[206:207]
	v_pk_mul_f32 v[234:235], v[234:235], v[208:209]
	v_mfma_f32_16x16x4_f32 v[36:39], v48, v228, v[36:39]
	v_mfma_f32_16x16x4_f32 v[40:43], v49, v229, v[40:43]
	v_mfma_f32_16x16x4_f32 v[36:39], v50, v230, v[36:39]
	v_mfma_f32_16x16x4_f32 v[40:43], v51, v231, v[40:43]
	v_pk_mul_f32 v[236:237], v[236:237], v[210:211]
	v_pk_mul_f32 v[238:239], v[238:239], v[212:213]
	v_mfma_f32_16x16x4_f32 v[36:39], v68, v232, v[36:39]
	v_mfma_f32_16x16x4_f32 v[40:43], v69, v233, v[40:43]
	v_mfma_f32_16x16x4_f32 v[36:39], v70, v234, v[36:39]
	v_mfma_f32_16x16x4_f32 v[40:43], v71, v235, v[40:43]
	v_mfma_f32_16x16x4_f32 v[36:39], v96, v236, v[36:39]
	v_mfma_f32_16x16x4_f32 v[40:43], v97, v237, v[40:43]
	v_mfma_f32_16x16x4_f32 v[36:39], v98, v238, v[36:39]
	v_mfma_f32_16x16x4_f32 v[40:43], v99, v239, v[40:43]
	v_mfma_f32_16x16x4_f32 v[36:39], v216, v214, v[36:39]
	v_mfma_f32_16x16x4_f32 v[40:43], v217, v215, v[40:43]
	ds_read_b128 v[44:47], v168 offset:15232
	ds_read_b128 v[48:51], v168 offset:15296
	ds_read_b128 v[68:71], v168 offset:15360
	ds_read_b128 v[96:99], v168 offset:15424
	ds_read_b32 v216, v171 offset:7168
	ds_read_b32 v217, v171 offset:7184
	ds_read_b128 v[198:201], v174 offset:1536
	ds_read_b128 v[202:205], v174 offset:1600
	ds_read_b128 v[206:209], v174 offset:1664
	ds_read_b128 v[210:213], v174 offset:1728
	v_mfma_f32_16x16x4_f32 v[224:227], v190, v214, v[224:227]
	v_mfma_f32_16x16x4_f32 v[224:227], v194, v215, v[224:227]
	v_mfma_f32_16x16x4_f32 v[228:231], v191, v214, v[228:231]
	v_mfma_f32_16x16x4_f32 v[228:231], v195, v215, v[228:231]
	v_mfma_f32_16x16x4_f32 v[232:235], v192, v214, v[232:235]
	v_mfma_f32_16x16x4_f32 v[232:235], v196, v215, v[232:235]
	v_mfma_f32_16x16x4_f32 v[236:239], v193, v214, v[236:239]
	v_mfma_f32_16x16x4_f32 v[236:239], v197, v215, v[236:239]
	ds_read_b32 v214, v169 offset:14336
	ds_read_b32 v215, v169 offset:15360
	v_pk_add_f32 v[80:81], v[36:37], v[40:41]
	v_pk_add_f32 v[82:83], v[38:39], v[42:43]
	v_pk_add_f32 v[84:85], v[36:37], v[40:41]
	v_pk_add_f32 v[86:87], v[38:39], v[42:43]
	v_pk_add_f32 v[36:37], v[36:37], v[40:41]
	v_pk_add_f32 v[38:39], v[38:39], v[42:43]
	v_permlane32_swap_b32_e32 v80, v84
	v_permlane32_swap_b32_e32 v81, v85
	v_permlane32_swap_b32_e32 v82, v86
	v_permlane32_swap_b32_e32 v83, v87
	v_mov_b32_e32 v88, v80
	v_mov_b32_e32 v89, v81
	v_mov_b32_e32 v90, v82
	v_mov_b32_e32 v91, v83
	s_nop 0
	v_permlane16_swap_b32_e32 v80, v88
	v_permlane16_swap_b32_e32 v81, v89
	v_permlane16_swap_b32_e32 v82, v90
	v_permlane16_swap_b32_e32 v83, v91
	v_fmac_f32_e32 v81, v124, v80
	v_fmac_f32_e32 v82, v128, v80
	v_fmac_f32_e32 v83, v132, v80
	v_fmac_f32_e32 v88, v136, v80
	v_fmac_f32_e32 v89, v144, v80
	v_fmac_f32_e32 v90, v152, v80
	v_fmac_f32_e32 v91, v160, v80
	v_fmac_f32_e32 v82, v129, v81
	v_fmac_f32_e32 v83, v133, v81
	v_fmac_f32_e32 v88, v137, v81
	v_fmac_f32_e32 v89, v145, v81
	v_fmac_f32_e32 v90, v153, v81
	v_fmac_f32_e32 v91, v161, v81
	v_fmac_f32_e32 v83, v134, v82
	v_fmac_f32_e32 v88, v138, v82
	v_fmac_f32_e32 v89, v146, v82
	v_fmac_f32_e32 v90, v154, v82
	v_fmac_f32_e32 v91, v162, v82
	v_fmac_f32_e32 v88, v139, v83
	v_fmac_f32_e32 v89, v147, v83
	v_fmac_f32_e32 v90, v155, v83
	v_fmac_f32_e32 v91, v163, v83
	v_fmac_f32_e32 v89, v148, v88
	v_fmac_f32_e32 v90, v156, v88
	v_fmac_f32_e32 v91, v164, v88
	v_fmac_f32_e32 v90, v157, v89
	v_fmac_f32_e32 v91, v165, v89
	v_fmac_f32_e32 v91, v166, v90
	ds_read_b128 v[124:127], v170 offset:7200
	ds_read_b128 v[128:131], v170 offset:7232
	ds_read_b128 v[132:135], v170 offset:7264
	ds_read_b128 v[136:139], v170 offset:7296
	ds_read_b128 v[144:147], v170 offset:7328
	ds_read_b128 v[148:151], v170 offset:7344
	ds_read_b128 v[152:155], v170 offset:7360
	ds_read_b128 v[156:159], v170 offset:7376
	ds_read_b128 v[160:163], v170 offset:7392
	ds_read_b128 v[164:167], v170 offset:7408
	v_cndmask_b32_e32 v220, v80, v81, vcc
	v_cndmask_b32_e64 v220, v220, v82, s[4:5]
	v_cndmask_b32_e64 v220, v220, v83, s[6:7]
	v_cndmask_b32_e32 v221, v88, v89, vcc
	v_cndmask_b32_e64 v221, v221, v90, s[4:5]
	v_cndmask_b32_e64 v221, v221, v91, s[6:7]
	s_nop 1
	v_mfma_f32_16x16x4_f32 v[84:87], v218, v220, v[36:39]
	v_mfma_f32_16x16x4_f32 v[84:87], v219, v221, v[84:87]
	ds_read_b32 v218, v172 offset:7168
	ds_read_b32 v219, v172 offset:7184
	v_mfma_f32_16x16x4_f32 v[224:227], v182, v220, v[224:227]
	v_mfma_f32_16x16x4_f32 v[224:227], v186, v221, v[224:227]
	v_mfma_f32_16x16x4_f32 v[228:231], v183, v220, v[228:231]
	v_mfma_f32_16x16x4_f32 v[228:231], v187, v221, v[228:231]
	v_mfma_f32_16x16x4_f32 v[232:235], v184, v220, v[232:235]
	v_mfma_f32_16x16x4_f32 v[232:235], v188, v221, v[232:235]
	v_mfma_f32_16x16x4_f32 v[236:239], v185, v220, v[236:239]
	v_mfma_f32_16x16x4_f32 v[236:239], v189, v221, v[236:239]
	v_add_u32_e32 v173, 0x880, v173
	v_add_u32_e32 v2, 0x880, v2
	v_add_u32_e32 v3, 0x880, v3
	v_add_u32_e32 v5, 0x880, v5
	ds_read2_b32 v[182:183], v173 offset0:0 offset1:16
	ds_read2_b32 v[184:185], v173 offset0:32 offset1:48
	ds_read2_b32 v[186:187], v2 offset0:0 offset1:16
	ds_read2_b32 v[188:189], v2 offset0:32 offset1:48
	ds_read2_b32 v[190:191], v3 offset0:0 offset1:16
	ds_read2_b32 v[192:193], v3 offset0:32 offset1:48
	ds_read2_b32 v[194:195], v5 offset0:0 offset1:16
	ds_read2_b32 v[196:197], v5 offset0:32 offset1:48
	s_mov_b64 exec, s[8:9]
	ds_write_b32 v175, v84 offset:12288
	ds_write_b32 v175, v85 offset:12544
	ds_write_b32 v175, v86 offset:12800
	ds_write_b32 v175, v87 offset:13056
	s_mov_b64 exec, -1
	s_waitcnt lgkmcnt(4)
	v_pk_mul_f32 v[224:225], v[224:225], v[198:199]
	v_pk_mul_f32 v[226:227], v[226:227], v[200:201]
	v_pk_mul_f32 v[228:229], v[228:229], v[202:203]
	v_pk_mul_f32 v[230:231], v[230:231], v[204:205]
	v_mfma_f32_16x16x4_f32 v[36:39], v44, v224, 0
	v_mfma_f32_16x16x4_f32 v[40:43], v45, v225, 0
	v_mfma_f32_16x16x4_f32 v[36:39], v46, v226, v[36:39]
	v_mfma_f32_16x16x4_f32 v[40:43], v47, v227, v[40:43]
	v_pk_mul_f32 v[232:233], v[232:233], v[206:207]
	v_pk_mul_f32 v[234:235], v[234:235], v[208:209]
	v_mfma_f32_16x16x4_f32 v[36:39], v48, v228, v[36:39]
	v_mfma_f32_16x16x4_f32 v[40:43], v49, v229, v[40:43]
	v_mfma_f32_16x16x4_f32 v[36:39], v50, v230, v[36:39]
	v_mfma_f32_16x16x4_f32 v[40:43], v51, v231, v[40:43]
	v_pk_mul_f32 v[236:237], v[236:237], v[210:211]
	v_pk_mul_f32 v[238:239], v[238:239], v[212:213]
	v_mfma_f32_16x16x4_f32 v[36:39], v68, v232, v[36:39]
	v_mfma_f32_16x16x4_f32 v[40:43], v69, v233, v[40:43]
	v_mfma_f32_16x16x4_f32 v[36:39], v70, v234, v[36:39]
	v_mfma_f32_16x16x4_f32 v[40:43], v71, v235, v[40:43]
	v_mfma_f32_16x16x4_f32 v[36:39], v96, v236, v[36:39]
	v_mfma_f32_16x16x4_f32 v[40:43], v97, v237, v[40:43]
	v_mfma_f32_16x16x4_f32 v[36:39], v98, v238, v[36:39]
	v_mfma_f32_16x16x4_f32 v[40:43], v99, v239, v[40:43]
	v_mfma_f32_16x16x4_f32 v[36:39], v216, v214, v[36:39]
	v_mfma_f32_16x16x4_f32 v[40:43], v217, v215, v[40:43]
	ds_read_b128 v[44:47], v168 offset:17408
	ds_read_b128 v[48:51], v168 offset:17472
	ds_read_b128 v[68:71], v168 offset:17536
	ds_read_b128 v[96:99], v168 offset:17600
	ds_read_b32 v216, v171 offset:8192
	ds_read_b32 v217, v171 offset:8208
	ds_read_b128 v[198:201], v174 offset:1792
	ds_read_b128 v[202:205], v174 offset:1856
	ds_read_b128 v[206:209], v174 offset:1920
	ds_read_b128 v[210:213], v174 offset:1984
	v_mfma_f32_16x16x4_f32 v[224:227], v190, v214, v[224:227]
	v_mfma_f32_16x16x4_f32 v[224:227], v194, v215, v[224:227]
	v_mfma_f32_16x16x4_f32 v[228:231], v191, v214, v[228:231]
	v_mfma_f32_16x16x4_f32 v[228:231], v195, v215, v[228:231]
	v_mfma_f32_16x16x4_f32 v[232:235], v192, v214, v[232:235]
	v_mfma_f32_16x16x4_f32 v[232:235], v196, v215, v[232:235]
	v_mfma_f32_16x16x4_f32 v[236:239], v193, v214, v[236:239]
	v_mfma_f32_16x16x4_f32 v[236:239], v197, v215, v[236:239]
	ds_read_b32 v214, v169 offset:16384
	ds_read_b32 v215, v169 offset:17408
	v_pk_add_f32 v[80:81], v[36:37], v[40:41]
	v_pk_add_f32 v[82:83], v[38:39], v[42:43]
	v_pk_add_f32 v[84:85], v[36:37], v[40:41]
	v_pk_add_f32 v[86:87], v[38:39], v[42:43]
	v_pk_add_f32 v[36:37], v[36:37], v[40:41]
	v_pk_add_f32 v[38:39], v[38:39], v[42:43]
	v_permlane32_swap_b32_e32 v80, v84
	v_permlane32_swap_b32_e32 v81, v85
	v_permlane32_swap_b32_e32 v82, v86
	v_permlane32_swap_b32_e32 v83, v87
	v_mov_b32_e32 v88, v80
	v_mov_b32_e32 v89, v81
	v_mov_b32_e32 v90, v82
	v_mov_b32_e32 v91, v83
	s_nop 0
	v_permlane16_swap_b32_e32 v80, v88
	v_permlane16_swap_b32_e32 v81, v89
	v_permlane16_swap_b32_e32 v82, v90
	v_permlane16_swap_b32_e32 v83, v91
	v_fmac_f32_e32 v81, v124, v80
	v_fmac_f32_e32 v82, v128, v80
	v_fmac_f32_e32 v83, v132, v80
	v_fmac_f32_e32 v88, v136, v80
	v_fmac_f32_e32 v89, v144, v80
	v_fmac_f32_e32 v90, v152, v80
	v_fmac_f32_e32 v91, v160, v80
	v_fmac_f32_e32 v82, v129, v81
	v_fmac_f32_e32 v83, v133, v81
	v_fmac_f32_e32 v88, v137, v81
	v_fmac_f32_e32 v89, v145, v81
	v_fmac_f32_e32 v90, v153, v81
	v_fmac_f32_e32 v91, v161, v81
	v_fmac_f32_e32 v83, v134, v82
	v_fmac_f32_e32 v88, v138, v82
	v_fmac_f32_e32 v89, v146, v82
	v_fmac_f32_e32 v90, v154, v82
	v_fmac_f32_e32 v91, v162, v82
	v_fmac_f32_e32 v88, v139, v83
	v_fmac_f32_e32 v89, v147, v83
	v_fmac_f32_e32 v90, v155, v83
	v_fmac_f32_e32 v91, v163, v83
	v_fmac_f32_e32 v89, v148, v88
	v_fmac_f32_e32 v90, v156, v88
	v_fmac_f32_e32 v91, v164, v88
	v_fmac_f32_e32 v90, v157, v89
	v_fmac_f32_e32 v91, v165, v89
	v_fmac_f32_e32 v91, v166, v90
	ds_read_b128 v[124:127], v170 offset:8224
	ds_read_b128 v[128:131], v170 offset:8256
	ds_read_b128 v[132:135], v170 offset:8288
	ds_read_b128 v[136:139], v170 offset:8320
	ds_read_b128 v[144:147], v170 offset:8352
	ds_read_b128 v[148:151], v170 offset:8368
	ds_read_b128 v[152:155], v170 offset:8384
	ds_read_b128 v[156:159], v170 offset:8400
	ds_read_b128 v[160:163], v170 offset:8416
	ds_read_b128 v[164:167], v170 offset:8432
	v_cndmask_b32_e32 v220, v80, v81, vcc
	v_cndmask_b32_e64 v220, v220, v82, s[4:5]
	v_cndmask_b32_e64 v220, v220, v83, s[6:7]
	v_cndmask_b32_e32 v221, v88, v89, vcc
	v_cndmask_b32_e64 v221, v221, v90, s[4:5]
	v_cndmask_b32_e64 v221, v221, v91, s[6:7]
	s_nop 1
	v_mfma_f32_16x16x4_f32 v[84:87], v218, v220, v[36:39]
	v_mfma_f32_16x16x4_f32 v[84:87], v219, v221, v[84:87]
	ds_read_b32 v218, v172 offset:8192
	ds_read_b32 v219, v172 offset:8208
	v_mfma_f32_16x16x4_f32 v[224:227], v182, v220, v[224:227]
	v_mfma_f32_16x16x4_f32 v[224:227], v186, v221, v[224:227]
	v_mfma_f32_16x16x4_f32 v[228:231], v183, v220, v[228:231]
	v_mfma_f32_16x16x4_f32 v[228:231], v187, v221, v[228:231]
	v_mfma_f32_16x16x4_f32 v[232:235], v184, v220, v[232:235]
	v_mfma_f32_16x16x4_f32 v[232:235], v188, v221, v[232:235]
	v_mfma_f32_16x16x4_f32 v[236:239], v185, v220, v[236:239]
	v_mfma_f32_16x16x4_f32 v[236:239], v189, v221, v[236:239]
	v_add_u32_e32 v173, 0x880, v173
	v_add_u32_e32 v2, 0x880, v2
	v_add_u32_e32 v3, 0x880, v3
	v_add_u32_e32 v5, 0x880, v5
	ds_read2_b32 v[182:183], v173 offset0:0 offset1:16
	ds_read2_b32 v[184:185], v173 offset0:32 offset1:48
	ds_read2_b32 v[186:187], v2 offset0:0 offset1:16
	ds_read2_b32 v[188:189], v2 offset0:32 offset1:48
	ds_read2_b32 v[190:191], v3 offset0:0 offset1:16
	ds_read2_b32 v[192:193], v3 offset0:32 offset1:48
	ds_read2_b32 v[194:195], v5 offset0:0 offset1:16
	ds_read2_b32 v[196:197], v5 offset0:32 offset1:48
	s_mov_b64 exec, s[8:9]
	ds_write_b32 v175, v84 offset:14336
	ds_write_b32 v175, v85 offset:14592
	ds_write_b32 v175, v86 offset:14848
	ds_write_b32 v175, v87 offset:15104
	s_mov_b64 exec, -1
	s_waitcnt lgkmcnt(0)
	s_nop 7
	v_pk_mul_f32 v[224:225], v[224:225], v[198:199]
	v_pk_mul_f32 v[226:227], v[226:227], v[200:201]
	v_pk_mul_f32 v[228:229], v[228:229], v[202:203]
	v_pk_mul_f32 v[230:231], v[230:231], v[204:205]
	v_pk_mul_f32 v[232:233], v[232:233], v[206:207]
	v_pk_mul_f32 v[234:235], v[234:235], v[208:209]
	v_pk_mul_f32 v[236:237], v[236:237], v[210:211]
	v_pk_mul_f32 v[238:239], v[238:239], v[212:213]
.Lrw_done:
	s_cmp_lg_u32 s40, 31
	s_cbranch_scc0 .Lrw_noladder
	s_waitcnt vmcnt(39)
	v_lshlrev_b32_e32 v106, 16, v52
	v_lshlrev_b32_e32 v35, 16, v53
	v_lshlrev_b32_e32 v34, 16, v54
	v_lshlrev_b32_e32 v44, 16, v18
	s_waitcnt vmcnt(38)
	v_lshlrev_b32_e32 v1, 16, v1
	s_waitcnt vmcnt(37)
	v_lshlrev_b32_e32 v46, 16, v19
	s_waitcnt vmcnt(36)
	v_lshlrev_b32_e32 v48, 16, v20
	s_waitcnt vmcnt(34)
	v_lshlrev_b32_e32 v45, 16, v21
	s_waitcnt vmcnt(33)
	v_lshlrev_b32_e32 v47, 16, v22
	s_waitcnt vmcnt(32)
	v_lshlrev_b32_e32 v51, 16, v23
	s_waitcnt vmcnt(30)
	v_lshlrev_b32_e32 v54, 16, v24
	s_waitcnt vmcnt(29)
	v_lshlrev_b32_e32 v52, 16, v25
	s_waitcnt vmcnt(28)
	v_lshlrev_b32_e32 v50, 16, v27
	s_waitcnt vmcnt(26)
	v_lshlrev_b32_e32 v49, 16, v28
	s_waitcnt vmcnt(25)
	v_lshlrev_b32_e32 v53, 16, v29
	s_waitcnt vmcnt(23)
	v_lshlrev_b32_e32 v57, 16, v31
	s_waitcnt vmcnt(22)
	v_lshlrev_b32_e32 v60, 16, v32
	s_waitcnt vmcnt(21)
	v_lshlrev_b32_e32 v58, 16, v33
	s_waitcnt vmcnt(20)
	v_lshlrev_b32_e32 v56, 16, v55
	v_lshlrev_b32_e32 v55, 16, v30
	s_waitcnt vmcnt(17)
	v_lshlrev_b32_e32 v59, 16, v59
	s_waitcnt vmcnt(16)
	v_lshlrev_b32_e32 v61, 16, v61
	s_waitcnt vmcnt(15)
	v_lshlrev_b32_e32 v62, 16, v62
	s_waitcnt vmcnt(14)
	v_lshlrev_b32_e32 v63, 16, v63
	s_waitcnt vmcnt(13)
	v_lshlrev_b32_e32 v66, 16, v66
	s_waitcnt vmcnt(12)
	v_lshlrev_b32_e32 v64, 16, v64
	s_waitcnt vmcnt(11)
	v_lshlrev_b32_e32 v65, 16, v6
	s_waitcnt vmcnt(9)
	v_lshlrev_b32_e32 v67, 16, v7
	s_waitcnt vmcnt(8)
	v_lshlrev_b32_e32 v70, 16, v12
	s_waitcnt vmcnt(7)
	v_lshlrev_b32_e32 v72, 16, v13
	s_waitcnt vmcnt(6)
	v_lshlrev_b32_e32 v68, 16, v16
	s_waitcnt vmcnt(5)
	v_lshlrev_b32_e32 v69, 16, v17
	s_waitcnt vmcnt(4)
	v_lshlrev_b32_e32 v71, 16, v8
	s_waitcnt vmcnt(2)
	v_lshlrev_b32_e32 v74, 16, v9
	s_waitcnt vmcnt(1)
	v_lshlrev_b32_e32 v73, 16, v4
